# SGU group loop: all eight u/g_c epilogue loads issued together at the epilogue start
# speedup vs baseline: 1.0106x; 1.0106x over previous
; __device__ __forceinline__ unsigned pk2(float lo, float hi) { f32x2 v = {lo, hi}; bf16x2_t b = __builtin_convertvector(v, bf16x2_t); return __builtin_bit_cast(unsigned, b); }
; #define MFMA32(a, b, c) __builtin_amdgcn_mfma_f32_32x32x16_bf16((a), (b), (c), 0, 0, 0)
; __device__ __forceinline__ void unpack8(const u32x4 w, float* v) { v[0] = bflo(w.x); v[1] = bfhi(w.x); v[2] = bflo(w.y); v[3] = bfhi(w.y); v[4] = bflo(w.z); v[5] = bfhi(w.z); v[6] = bflo(w.w); v[7] = bfhi(w.w); }
; template <int tbA, int tbB> ...
;     for (int gi = 0; gi < 4; ++gi) {
;         const int g = gh * 4 + gi;
;         const int ch = g * 128 + cb * 32 + r;
;         const float gg = lng[ch], bb = lnb[ch];
;         const bf16_t* ap = VCT + (size_t)ch * PT + tok0 + 8 * hh;
;         const bf16_t* wp = Wbf + (size_t)g * 16384 + 8 * hh;
;         constexpr int NSB = (tbB + 1) * 2, NSA = (tbA + 1) * 2;
;         int so = 0; asm volatile("" : "+v"(so));
;         u32x4 raw[NSB]; bf16x8 wB[NSB], wA[NSA];
; #pragma unroll
;         for (int k = 0; k < NSB; ++k) { raw[k] = *(const u32x4*)(ap + 16 * k); wB[k] = *(const bf16x8*)(wp + (size_t)(tbB * 32 + r) * 128 + 16 * k); }
; #pragma unroll
;         for (int k = 0; k < NSA; ++k) wA[k] = *(const bf16x8*)(wp + (size_t)(tbA * 32 + r) * 128 + 16 * k);
;         f32x16 accA, accB;
; #pragma unroll
;         for (int i = 0; i < 16; ++i) { accA[i] = 0.f; accB[i] = 0.f; }
; #pragma unroll
;         for (int k = 0; k < NSB; ++k) {
;             float v[8]; unpack8(raw[k], v);
; #pragma unroll
;             for (int jj = 0; jj < 8; ++jj) { const float mean = stat[(16 * k + 8 * hh + jj) * 2 + so], rstd = stat[(16 * k + 8 * hh + jj) * 2 + 1 + so]; v[jj] = (v[jj] - mean) * rstd * gg + bb; }
;             u32x4 af; af.x = pk2(v[0], v[1]); af.y = pk2(v[2], v[3]); af.z = pk2(v[4], v[5]); af.w = pk2(v[6], v[7]);
;             accB = MFMA32(__builtin_bit_cast(bf16x8, af), wB[k], accB);
;             if (k < NSA) accA = MFMA32(__builtin_bit_cast(bf16x8, af), wA[k < NSA ? k : 0], accA);
.LBB0_229:
	v_lshl_add_u64 v[8:9], v[52:53], 0, v[148:149]
	v_mov_b32_e32 v14, v133
	global_load_dword v60, v[56:57], off
	global_load_dword v62, v[54:55], off
	global_load_dwordx4 v[0:3], v[8:9], off offset:-96
	v_lshl_add_u64 v[10:11], v[58:59], 0, v[148:149]
	v_add_co_u32_e32 v12, vcc, s95, v10
	v_lshl_add_u32 v74, v14, 2, v158
	s_nop 0
	v_addc_co_u32_e32 v13, vcc, 0, v11, vcc
	v_add_co_u32_e32 v20, vcc, s96, v10
	global_load_dwordx4 v[4:7], v[12:13], off
	global_load_dwordx4 v[68:71], v[8:9], off offset:-64
	global_load_dwordx4 v[76:79], v[12:13], off offset:32
	global_load_dwordx4 v[80:83], v[8:9], off offset:-32
	global_load_dwordx4 v[84:87], v[12:13], off offset:64
	global_load_dwordx4 v[88:91], v[8:9], off
	global_load_dwordx4 v[92:95], v[12:13], off offset:96
	global_load_dwordx4 v[44:47], v[8:9], off offset:32
	global_load_dwordx4 v[40:43], v[12:13], off offset:128
	global_load_dwordx4 v[36:39], v[8:9], off offset:64
	global_load_dwordx4 v[32:35], v[12:13], off offset:160
	v_addc_co_u32_e32 v21, vcc, 0, v11, vcc
	v_add_u32_e32 v12, 0x2000, v74
	global_load_dwordx4 v[96:99], v[20:21], off offset:32
	global_load_dwordx4 v[100:103], v[20:21], off offset:64
	global_load_dwordx4 v[104:107], v[20:21], off offset:96
	v_add_u32_e32 v110, 0x2080, v74
	v_lshl_add_u64 v[58:59], v[58:59], 0, s[58:59]
	v_lshl_add_u64 v[52:53], v[52:53], 0, s[60:61]
	v_lshl_add_u64 v[54:55], v[54:55], 0, s[62:63]
	v_lshl_add_u64 v[56:57], v[56:57], 0, s[62:63]
	s_waitcnt vmcnt(12)
	v_lshlrev_b32_e32 v72, 16, v68
	v_lshlrev_b32_e32 v8, 16, v0
	v_and_b32_e32 v9, 0xffff0000, v0
	v_add_u32_e32 v0, 0x2008, v74
	ds_read2_b32 v[10:11], v0 offset1:1
	ds_read2_b32 v[12:13], v12 offset1:1
	v_lshlrev_b32_e32 v0, 16, v1
	v_and_b32_e32 v1, 0xffff0000, v1
	v_and_b32_e32 v73, 0xffff0000, v68
	s_waitcnt lgkmcnt(1)
	v_mov_b32_e32 v15, v10
	s_waitcnt lgkmcnt(0)
	v_mov_b32_e32 v14, v12
	v_pk_add_f32 v[8:9], v[8:9], v[14:15] neg_lo:[0,1] neg_hi:[0,1]
	v_mov_b32_e32 v10, v13
	v_pk_mul_f32 v[8:9], v[8:9], v[10:11]
	v_add_u32_e32 v12, 0x2010, v74
	v_add_u32_e32 v10, 0x2018, v74
	ds_read2_b32 v[10:11], v10 offset1:1
	ds_read2_b32 v[12:13], v12 offset1:1
	v_add_u32_e32 v68, 0x2088, v74
	v_pk_fma_f32 v[8:9], v[60:61], v[8:9], v[62:63] op_sel_hi:[0,1,0]
	s_waitcnt lgkmcnt(1)
	v_mov_b32_e32 v15, v10
	s_waitcnt lgkmcnt(0)
	v_mov_b32_e32 v14, v12
	v_pk_add_f32 v[0:1], v[0:1], v[14:15] neg_lo:[0,1] neg_hi:[0,1]
	v_mov_b32_e32 v10, v13
	v_pk_mul_f32 v[0:1], v[0:1], v[10:11]
	v_add_u32_e32 v14, 0x2020, v74
	v_lshlrev_b32_e32 v10, 16, v2
	v_and_b32_e32 v11, 0xffff0000, v2
	v_add_u32_e32 v2, 0x2028, v74
	ds_read2_b32 v[12:13], v2 offset1:1
	ds_read2_b32 v[14:15], v14 offset1:1
	v_lshlrev_b32_e32 v2, 16, v3
	v_and_b32_e32 v3, 0xffff0000, v3
	v_pk_fma_f32 v[0:1], v[60:61], v[0:1], v[62:63] op_sel_hi:[0,1,0]
	s_waitcnt lgkmcnt(1)
	v_mov_b32_e32 v17, v12
	s_waitcnt lgkmcnt(0)
	v_mov_b32_e32 v16, v14
	v_pk_add_f32 v[10:11], v[10:11], v[16:17] neg_lo:[0,1] neg_hi:[0,1]
	v_mov_b32_e32 v12, v15
	v_pk_mul_f32 v[10:11], v[10:11], v[12:13]
	v_add_u32_e32 v14, 0x2030, v74
	v_add_u32_e32 v12, 0x2038, v74
	ds_read2_b32 v[12:13], v12 offset1:1
	ds_read2_b32 v[14:15], v14 offset1:1
	global_load_dwordx4 v[20:23], v[20:21], off
	ds_read2_b32 v[108:109], v68 offset1:1
	ds_read2_b32 v[110:111], v110 offset1:1
	v_lshlrev_b32_e32 v68, 16, v69
	v_and_b32_e32 v69, 0xffff0000, v69
	s_waitcnt lgkmcnt(2)
	v_mov_b32_e32 v16, v14
	s_waitcnt lgkmcnt(1)
	v_mov_b32_e32 v113, v108
	s_waitcnt lgkmcnt(0)
	v_mov_b32_e32 v112, v110
	v_pk_add_f32 v[72:73], v[72:73], v[112:113] neg_lo:[0,1] neg_hi:[0,1]
	v_mov_b32_e32 v108, v111
	v_pk_mul_f32 v[72:73], v[72:73], v[108:109]
	v_add_u32_e32 v110, 0x2090, v74
	v_add_u32_e32 v108, 0x2098, v74
	ds_read2_b32 v[108:109], v108 offset1:1
	ds_read2_b32 v[110:111], v110 offset1:1
	v_mov_b32_e32 v17, v12
	v_pk_add_f32 v[2:3], v[2:3], v[16:17] neg_lo:[0,1] neg_hi:[0,1]
	v_mov_b32_e32 v12, v15
	s_waitcnt lgkmcnt(1)
	v_mov_b32_e32 v113, v108
	s_waitcnt lgkmcnt(0)
	v_mov_b32_e32 v112, v110
	v_pk_add_f32 v[68:69], v[68:69], v[112:113] neg_lo:[0,1] neg_hi:[0,1]
	v_mov_b32_e32 v108, v111
	v_pk_mul_f32 v[68:69], v[68:69], v[108:109]
	v_add_u32_e32 v112, 0x20a0, v74
	v_pk_fma_f32 v[108:109], v[60:61], v[68:69], v[62:63] op_sel_hi:[0,1,0]
	v_lshlrev_b32_e32 v68, 16, v70
	v_and_b32_e32 v69, 0xffff0000, v70
	v_add_u32_e32 v70, 0x20a8, v74
	ds_read2_b32 v[110:111], v70 offset1:1
	ds_read2_b32 v[112:113], v112 offset1:1
	v_pk_mul_f32 v[2:3], v[2:3], v[12:13]
	v_add_u32_e32 v70, 0x20b8, v74
	v_pk_fma_f32 v[10:11], v[60:61], v[10:11], v[62:63] op_sel_hi:[0,1,0]
	s_waitcnt lgkmcnt(1)
	v_mov_b32_e32 v115, v110
	s_waitcnt lgkmcnt(0)
	v_mov_b32_e32 v114, v112
	v_pk_add_f32 v[68:69], v[68:69], v[114:115] neg_lo:[0,1] neg_hi:[0,1]
	v_mov_b32_e32 v110, v113
	v_pk_mul_f32 v[68:69], v[68:69], v[110:111]
	v_add_u32_e32 v112, 0x20b0, v74
	v_pk_fma_f32 v[2:3], v[60:61], v[2:3], v[62:63] op_sel_hi:[0,1,0]
	v_pk_fma_f32 v[110:111], v[60:61], v[68:69], v[62:63] op_sel_hi:[0,1,0]
	v_lshlrev_b32_e32 v68, 16, v71
	v_and_b32_e32 v69, 0xffff0000, v71
	ds_read2_b32 v[70:71], v70 offset1:1
	ds_read2_b32 v[112:113], v112 offset1:1
	v_cvt_pk_bf16_f32 v16, v8, v9
	v_cvt_pk_bf16_f32 v17, v0, v1
	v_cvt_pk_bf16_f32 v18, v10, v11
	v_cvt_pk_bf16_f32 v19, v2, v3
	s_waitcnt lgkmcnt(0)
	v_mov_b32_e32 v114, v112
	v_mov_b32_e32 v115, v70
	v_mfma_f32_32x32x16_bf16 v[0:15], v[16:19], v[4:7], 0
	v_add_f32_e64 v68, v68, -v114
	v_add_f32_e64 v69, v69, -v115
	v_mov_b32_e32 v70, v113
	v_mul_f32_e64 v68, v68, v70
	v_mul_f32_e64 v69, v69, v71
	v_pk_fma_f32 v[72:73], v[60:61], v[72:73], v[62:63] op_sel_hi:[0,1,0]
	v_pk_fma_f32 v[112:113], v[60:61], v[68:69], v[62:63] op_sel_hi:[0,1,0]
	v_cvt_pk_bf16_f32 v68, v72, v73
	v_cvt_pk_bf16_f32 v69, v108, v109
	v_cvt_pk_bf16_f32 v70, v110, v111
	v_cvt_pk_bf16_f32 v71, v112, v113
	v_add_u32_e32 v72, 0x2100, v74
	s_waitcnt vmcnt(0)
; __device__ __forceinline__ unsigned pk2(float lo, float hi) { f32x2 v = {lo, hi}; bf16x2_t b = __builtin_convertvector(v, bf16x2_t); return __builtin_bit_cast(unsigned, b); }
; #define MFMA32(a, b, c) __builtin_amdgcn_mfma_f32_32x32x16_bf16((a), (b), (c), 0, 0, 0)
; __device__ __forceinline__ void unpack8(const u32x4 w, float* v) { v[0] = bflo(w.x); v[1] = bfhi(w.x); v[2] = bflo(w.y); v[3] = bfhi(w.y); v[4] = bflo(w.z); v[5] = bfhi(w.z); v[6] = bflo(w.w); v[7] = bfhi(w.w); }
; template <int tbA, int tbB> ...
;     ...
; #pragma unroll
;         for (int k = 0; k < NSB; ++k) {
;             float v[8]; unpack8(raw[k], v);
; #pragma unroll
;             for (int jj = 0; jj < 8; ++jj) { const float mean = stat[(16 * k + 8 * hh + jj) * 2 + so], rstd = stat[(16 * k + 8 * hh + jj) * 2 + 1 + so]; v[jj] = (v[jj] - mean) * rstd * gg + bb; }
;             u32x4 af; af.x = pk2(v[0], v[1]); af.y = pk2(v[2], v[3]); af.z = pk2(v[4], v[5]); af.w = pk2(v[6], v[7]);
;             accB = MFMA32(__builtin_bit_cast(bf16x8, af), wB[k], accB);
;             if (k < NSA) accA = MFMA32(__builtin_bit_cast(bf16x8, af), wA[k < NSA ? k : 0], accA);
;         }
	v_mfma_f32_32x32x16_bf16 v[16:31], v[16:19], v[20:23], 0
	v_mfma_f32_32x32x16_bf16 v[0:15], v[68:71], v[76:79], v[0:15]
	v_mfma_f32_32x32x16_bf16 v[16:31], v[68:71], v[96:99], v[16:31]
	v_add_u32_e32 v70, 0x2108, v74
	ds_read2_b32 v[70:71], v70 offset1:1
	ds_read2_b32 v[72:73], v72 offset1:1
	v_lshlrev_b32_e32 v68, 16, v80
	v_and_b32_e32 v69, 0xffff0000, v80
	s_waitcnt lgkmcnt(1)
	v_mov_b32_e32 v77, v70
	s_waitcnt lgkmcnt(0)
	v_mov_b32_e32 v76, v72
	v_pk_add_f32 v[68:69], v[68:69], v[76:77] neg_lo:[0,1] neg_hi:[0,1]
	v_add_u32_e32 v76, 0x2110, v74
	v_add_u32_e32 v72, 0x2118, v74
	v_mov_b32_e32 v70, v73
	ds_read2_b32 v[72:73], v72 offset1:1
	ds_read2_b32 v[76:77], v76 offset1:1
	v_pk_mul_f32 v[68:69], v[68:69], v[70:71]
	v_lshlrev_b32_e32 v70, 16, v81
	v_and_b32_e32 v71, 0xffff0000, v81
	s_waitcnt lgkmcnt(1)
	v_mov_b32_e32 v79, v72
	s_waitcnt lgkmcnt(0)
	v_mov_b32_e32 v78, v76
	v_pk_add_f32 v[70:71], v[70:71], v[78:79] neg_lo:[0,1] neg_hi:[0,1]
	v_add_u32_e32 v78, 0x2120, v74
	v_add_u32_e32 v76, 0x2128, v74
	v_mov_b32_e32 v72, v77
	ds_read2_b32 v[76:77], v76 offset1:1
	ds_read2_b32 v[78:79], v78 offset1:1
	v_pk_mul_f32 v[70:71], v[70:71], v[72:73]
	v_lshlrev_b32_e32 v72, 16, v82
	v_and_b32_e32 v73, 0xffff0000, v82
	s_waitcnt lgkmcnt(1)
	v_mov_b32_e32 v81, v76
	s_waitcnt lgkmcnt(0)
	v_mov_b32_e32 v80, v78
	v_pk_add_f32 v[72:73], v[72:73], v[80:81] neg_lo:[0,1] neg_hi:[0,1]
	v_add_u32_e32 v80, 0x2130, v74
	v_add_u32_e32 v78, 0x2138, v74
	v_mov_b32_e32 v76, v79
	ds_read2_b32 v[78:79], v78 offset1:1
	ds_read2_b32 v[80:81], v80 offset1:1
	v_pk_mul_f32 v[72:73], v[72:73], v[76:77]
	v_lshlrev_b32_e32 v76, 16, v83
	v_and_b32_e32 v77, 0xffff0000, v83
	s_waitcnt lgkmcnt(1)
	v_mov_b32_e32 v83, v78
	s_waitcnt lgkmcnt(0)
	v_mov_b32_e32 v82, v80
	v_pk_add_f32 v[76:77], v[76:77], v[82:83] neg_lo:[0,1] neg_hi:[0,1]
	v_mov_b32_e32 v78, v81
	v_pk_mul_f32 v[76:77], v[76:77], v[78:79]
	v_pk_fma_f32 v[68:69], v[60:61], v[68:69], v[62:63] op_sel_hi:[0,1,0]
	v_pk_fma_f32 v[70:71], v[60:61], v[70:71], v[62:63] op_sel_hi:[0,1,0]
	v_pk_fma_f32 v[72:73], v[60:61], v[72:73], v[62:63] op_sel_hi:[0,1,0]
	v_pk_fma_f32 v[76:77], v[60:61], v[76:77], v[62:63] op_sel_hi:[0,1,0]
	v_cvt_pk_bf16_f32 v68, v68, v69
	v_cvt_pk_bf16_f32 v69, v70, v71
	v_cvt_pk_bf16_f32 v70, v72, v73
	v_cvt_pk_bf16_f32 v71, v76, v77
	v_add_u32_e32 v72, 0x2180, v74
	s_nop 0
	v_mfma_f32_32x32x16_bf16 v[0:15], v[68:71], v[84:87], v[0:15]
	v_mfma_f32_32x32x16_bf16 v[16:31], v[68:71], v[100:103], v[16:31]
	v_add_u32_e32 v70, 0x2188, v74
	ds_read2_b32 v[70:71], v70 offset1:1
	ds_read2_b32 v[72:73], v72 offset1:1
	v_lshlrev_b32_e32 v68, 16, v88
	v_and_b32_e32 v69, 0xffff0000, v88
	s_waitcnt lgkmcnt(1)
	v_mov_b32_e32 v77, v70
	s_waitcnt lgkmcnt(0)
	v_mov_b32_e32 v76, v72
	v_pk_add_f32 v[68:69], v[68:69], v[76:77] neg_lo:[0,1] neg_hi:[0,1]
	v_add_u32_e32 v76, 0x2190, v74
	v_add_u32_e32 v72, 0x2198, v74
	v_mov_b32_e32 v70, v73
	ds_read2_b32 v[72:73], v72 offset1:1
	ds_read2_b32 v[76:77], v76 offset1:1
	v_pk_mul_f32 v[68:69], v[68:69], v[70:71]
	v_lshlrev_b32_e32 v70, 16, v89
	v_and_b32_e32 v71, 0xffff0000, v89
	s_waitcnt lgkmcnt(1)
	v_mov_b32_e32 v79, v72
	s_waitcnt lgkmcnt(0)
	v_mov_b32_e32 v78, v76
	v_pk_add_f32 v[70:71], v[70:71], v[78:79] neg_lo:[0,1] neg_hi:[0,1]
	v_add_u32_e32 v78, 0x21a0, v74
	v_add_u32_e32 v76, 0x21a8, v74
	v_mov_b32_e32 v72, v77
	ds_read2_b32 v[76:77], v76 offset1:1
	ds_read2_b32 v[78:79], v78 offset1:1
	v_pk_mul_f32 v[70:71], v[70:71], v[72:73]
	v_lshlrev_b32_e32 v72, 16, v90
	v_and_b32_e32 v73, 0xffff0000, v90
	s_waitcnt lgkmcnt(1)
	v_mov_b32_e32 v81, v76
	s_waitcnt lgkmcnt(0)
	v_mov_b32_e32 v80, v78
	v_pk_add_f32 v[72:73], v[72:73], v[80:81] neg_lo:[0,1] neg_hi:[0,1]
	v_add_u32_e32 v80, 0x21b0, v74
	v_add_u32_e32 v78, 0x21b8, v74
	v_mov_b32_e32 v76, v79
	ds_read2_b32 v[78:79], v78 offset1:1
	ds_read2_b32 v[80:81], v80 offset1:1
	v_pk_mul_f32 v[72:73], v[72:73], v[76:77]
	v_lshlrev_b32_e32 v76, 16, v91
	v_and_b32_e32 v77, 0xffff0000, v91
	s_waitcnt lgkmcnt(1)
	v_mov_b32_e32 v83, v78
	s_waitcnt lgkmcnt(0)
	v_mov_b32_e32 v82, v80
	v_pk_add_f32 v[76:77], v[76:77], v[82:83] neg_lo:[0,1] neg_hi:[0,1]
	v_mov_b32_e32 v78, v81
	v_pk_mul_f32 v[76:77], v[76:77], v[78:79]
	v_pk_fma_f32 v[68:69], v[60:61], v[68:69], v[62:63] op_sel_hi:[0,1,0]
	v_pk_fma_f32 v[70:71], v[60:61], v[70:71], v[62:63] op_sel_hi:[0,1,0]
	v_pk_fma_f32 v[72:73], v[60:61], v[72:73], v[62:63] op_sel_hi:[0,1,0]
	v_pk_fma_f32 v[76:77], v[60:61], v[76:77], v[62:63] op_sel_hi:[0,1,0]
	v_cvt_pk_bf16_f32 v68, v68, v69
	v_cvt_pk_bf16_f32 v69, v70, v71
	v_cvt_pk_bf16_f32 v70, v72, v73
	v_cvt_pk_bf16_f32 v71, v76, v77
	v_add_u32_e32 v72, 0x2200, v74
	s_nop 0
	v_mfma_f32_32x32x16_bf16 v[0:15], v[68:71], v[92:95], v[0:15]
	v_mfma_f32_32x32x16_bf16 v[16:31], v[68:71], v[104:107], v[16:31]
	v_lshlrev_b32_e32 v68, 16, v44
	v_and_b32_e32 v69, 0xffff0000, v44
	v_add_u32_e32 v44, 0x2208, v74
	ds_read2_b32 v[70:71], v44 offset1:1
	ds_read2_b32 v[72:73], v72 offset1:1
	v_lshlrev_b32_e32 v44, 16, v45
	v_and_b32_e32 v45, 0xffff0000, v45
	s_waitcnt lgkmcnt(1)
	v_mov_b32_e32 v77, v70
	s_waitcnt lgkmcnt(0)
	v_mov_b32_e32 v76, v72
	v_pk_add_f32 v[68:69], v[68:69], v[76:77] neg_lo:[0,1] neg_hi:[0,1]
	v_mov_b32_e32 v70, v73
	v_pk_mul_f32 v[68:69], v[68:69], v[70:71]
	v_add_u32_e32 v72, 0x2210, v74
	v_add_u32_e32 v70, 0x2218, v74
	ds_read2_b32 v[70:71], v70 offset1:1
	ds_read2_b32 v[72:73], v72 offset1:1
	v_pk_fma_f32 v[68:69], v[60:61], v[68:69], v[62:63] op_sel_hi:[0,1,0]
	s_waitcnt lgkmcnt(1)
	v_mov_b32_e32 v77, v70
	s_waitcnt lgkmcnt(0)
; #define LAS __attribute__((address_space(3)))
; __device__ __forceinline__ unsigned pk2(float lo, float hi) { f32x2 v = {lo, hi}; bf16x2_t b = __builtin_convertvector(v, bf16x2_t); return __builtin_bit_cast(unsigned, b); }
; #define MFMA32(a, b, c) __builtin_amdgcn_mfma_f32_32x32x16_bf16((a), (b), (c), 0, 0, 0)
; __device__ __forceinline__ void unpack8(const u32x4 w, float* v) { v[0] = bflo(w.x); v[1] = bfhi(w.x); v[2] = bflo(w.y); v[3] = bfhi(w.y); v[4] = bflo(w.z); v[5] = bfhi(w.z); v[6] = bflo(w.w); v[7] = bfhi(w.w); }
; template <int tbA, int tbB> ...
;     ...
; #pragma unroll
;         for (int k = 0; k < NSB; ++k) {
;             float v[8]; unpack8(raw[k], v);
; #pragma unroll
;             for (int jj = 0; jj < 8; ++jj) { const float mean = stat[(16 * k + 8 * hh + jj) * 2 + so], rstd = stat[(16 * k + 8 * hh + jj) * 2 + 1 + so]; v[jj] = (v[jj] - mean) * rstd * gg + bb; }
;             u32x4 af; af.x = pk2(v[0], v[1]); af.y = pk2(v[2], v[3]); af.z = pk2(v[4], v[5]); af.w = pk2(v[6], v[7]);
;             accB = MFMA32(__builtin_bit_cast(bf16x8, af), wB[k], accB);
;             if (k < NSA) accA = MFMA32(__builtin_bit_cast(bf16x8, af), wA[k < NSA ? k : 0], accA);
;         }
; #pragma unroll
;         for (int which = 0; which < 2; ++which) {
;             const int tb = which ? tbB : tbA; const f32x16& acc = which ? accB : accA;
;             const float sbv = spb[g * 128 + tb * 32 + r];
; #pragma unroll
;             for (int q = 0; q < 4; ++q) {
;                 u32x2 w; w.x = pk2(acc[4 * q + 0] + sbv, acc[4 * q + 1] + sbv); w.y = pk2(acc[4 * q + 2] + sbv, acc[4 * q + 3] + sbv);
;                 *(LAS u32x2*)(stg + which * 2560 + r * 80 + (8 * q + 4 * hh) * 2) = w;
;             }
;         }
; #pragma unroll
;         for (int which = 0; which < 2; ++which) {
;             const int tb = which ? tbB : tbA;
; #pragma unroll
;             for (int i = 0; i < 2; ++i) {
;                 const int t = (lane >> 2) + 16 * i, ck = lane & 3;
;                 const size_t a = (size_t)(tok0 + tb * 32 + t) * DH + g * 128 + cb * 32 + ck * 8;
;                 const u32x4 uu = *(const u32x4*)(U + a), gc = *(const u32x4*)(GC + a);
	v_mov_b32_e32 v76, v72
	v_pk_add_f32 v[44:45], v[44:45], v[76:77] neg_lo:[0,1] neg_hi:[0,1]
	v_mov_b32_e32 v70, v73
	v_pk_mul_f32 v[44:45], v[44:45], v[70:71]
	v_add_u32_e32 v76, 0x2220, v74
	v_pk_fma_f32 v[70:71], v[60:61], v[44:45], v[62:63] op_sel_hi:[0,1,0]
	v_lshlrev_b32_e32 v44, 16, v46
	v_and_b32_e32 v45, 0xffff0000, v46
	v_add_u32_e32 v46, 0x2228, v74
	ds_read2_b32 v[72:73], v46 offset1:1
	ds_read2_b32 v[76:77], v76 offset1:1
	v_add_u32_e32 v46, 0x2238, v74
	s_waitcnt lgkmcnt(1)
	v_mov_b32_e32 v79, v72
	s_waitcnt lgkmcnt(0)
	v_mov_b32_e32 v78, v76
	v_pk_add_f32 v[44:45], v[44:45], v[78:79] neg_lo:[0,1] neg_hi:[0,1]
	v_mov_b32_e32 v72, v77
	v_pk_mul_f32 v[44:45], v[44:45], v[72:73]
	v_add_u32_e32 v76, 0x2230, v74
	v_pk_fma_f32 v[72:73], v[60:61], v[44:45], v[62:63] op_sel_hi:[0,1,0]
	v_lshlrev_b32_e32 v44, 16, v47
	v_and_b32_e32 v45, 0xffff0000, v47
	ds_read2_b32 v[46:47], v46 offset1:1
	ds_read2_b32 v[76:77], v76 offset1:1
	s_waitcnt lgkmcnt(1)
	v_mov_b32_e32 v79, v46
	s_waitcnt lgkmcnt(0)
	v_mov_b32_e32 v78, v76
	v_pk_add_f32 v[44:45], v[44:45], v[78:79] neg_lo:[0,1] neg_hi:[0,1]
	v_mov_b32_e32 v46, v77
	v_pk_mul_f32 v[44:45], v[44:45], v[46:47]
	v_cvt_pk_bf16_f32 v46, v72, v73
	v_pk_fma_f32 v[76:77], v[60:61], v[44:45], v[62:63] op_sel_hi:[0,1,0]
	v_cvt_pk_bf16_f32 v44, v68, v69
	v_cvt_pk_bf16_f32 v45, v70, v71
	v_cvt_pk_bf16_f32 v47, v76, v77
	s_nop 1
	v_mfma_f32_32x32x16_bf16 v[0:15], v[44:47], v[40:43], v[0:15]
	v_add_u32_e32 v44, 0x2280, v74
	v_lshlrev_b32_e32 v40, 16, v36
	v_and_b32_e32 v41, 0xffff0000, v36
	v_add_u32_e32 v36, 0x2288, v74
	ds_read2_b32 v[42:43], v36 offset1:1
	ds_read2_b32 v[44:45], v44 offset1:1
	v_lshlrev_b32_e32 v36, 16, v37
	v_and_b32_e32 v37, 0xffff0000, v37
	s_waitcnt lgkmcnt(1)
	v_mov_b32_e32 v47, v42
	s_waitcnt lgkmcnt(0)
	v_mov_b32_e32 v46, v44
	v_pk_add_f32 v[40:41], v[40:41], v[46:47] neg_lo:[0,1] neg_hi:[0,1]
	v_mov_b32_e32 v42, v45
	v_pk_mul_f32 v[40:41], v[40:41], v[42:43]
	v_add_u32_e32 v44, 0x2290, v74
	v_add_u32_e32 v42, 0x2298, v74
	ds_read2_b32 v[42:43], v42 offset1:1
	ds_read2_b32 v[44:45], v44 offset1:1
	v_pk_fma_f32 v[40:41], v[60:61], v[40:41], v[62:63] op_sel_hi:[0,1,0]
	s_waitcnt lgkmcnt(1)
	v_mov_b32_e32 v47, v42
	s_waitcnt lgkmcnt(0)
	v_mov_b32_e32 v46, v44
	v_pk_add_f32 v[36:37], v[36:37], v[46:47] neg_lo:[0,1] neg_hi:[0,1]
	v_mov_b32_e32 v42, v45
	v_pk_mul_f32 v[36:37], v[36:37], v[42:43]
	v_add_u32_e32 v46, 0x22a0, v74
	v_pk_fma_f32 v[42:43], v[60:61], v[36:37], v[62:63] op_sel_hi:[0,1,0]
	v_lshlrev_b32_e32 v36, 16, v38
	v_and_b32_e32 v37, 0xffff0000, v38
	v_add_u32_e32 v38, 0x22a8, v74
	ds_read2_b32 v[44:45], v38 offset1:1
	ds_read2_b32 v[46:47], v46 offset1:1
	v_add_u32_e32 v38, 0x22b8, v74
	s_waitcnt lgkmcnt(1)
	v_mov_b32_e32 v69, v44
	s_waitcnt lgkmcnt(0)
	v_mov_b32_e32 v68, v46
	v_pk_add_f32 v[36:37], v[36:37], v[68:69] neg_lo:[0,1] neg_hi:[0,1]
	v_mov_b32_e32 v44, v47
	v_pk_mul_f32 v[36:37], v[36:37], v[44:45]
	v_add_u32_e32 v46, 0x22b0, v74
	v_pk_fma_f32 v[44:45], v[60:61], v[36:37], v[62:63] op_sel_hi:[0,1,0]
	v_lshlrev_b32_e32 v36, 16, v39
	v_and_b32_e32 v37, 0xffff0000, v39
	ds_read2_b32 v[38:39], v38 offset1:1
	ds_read2_b32 v[46:47], v46 offset1:1
	s_waitcnt lgkmcnt(1)
	v_mov_b32_e32 v69, v38
	s_waitcnt lgkmcnt(0)
	v_mov_b32_e32 v68, v46
	v_pk_add_f32 v[36:37], v[36:37], v[68:69] neg_lo:[0,1] neg_hi:[0,1]
	v_mov_b32_e32 v38, v47
	v_pk_mul_f32 v[36:37], v[36:37], v[38:39]
	v_cvt_pk_bf16_f32 v38, v44, v45
	v_pk_fma_f32 v[46:47], v[60:61], v[36:37], v[62:63] op_sel_hi:[0,1,0]
	v_cvt_pk_bf16_f32 v36, v40, v41
	v_cvt_pk_bf16_f32 v37, v42, v43
	v_cvt_pk_bf16_f32 v39, v46, v47
	s_nop 1
	v_mfma_f32_32x32x16_bf16 v[0:15], v[36:39], v[32:35], v[0:15]
	v_add_u32_e32 v120, s8, v66
	v_add_u32_e32 v122, 0xfa008000, v120
	v_mov_b32_e32 v123, 0
	v_lshlrev_b64 v[122:123], 1, v[122:123]
	v_lshl_add_u64 v[124:125], s[30:31], 0, v[122:123]
	global_load_dwordx4 v[80:83], v[124:125], off
	v_lshl_add_u64 v[124:125], s[34:35], 0, v[122:123]
	global_load_dwordx4 v[84:87], v[124:125], off
	v_add_u32_e32 v122, 0xfa00c000, v120
	v_mov_b32_e32 v123, 0
	v_lshlrev_b64 v[122:123], 1, v[122:123]
	v_lshl_add_u64 v[124:125], s[30:31], 0, v[122:123]
	global_load_dwordx4 v[88:91], v[124:125], off
	v_lshl_add_u64 v[124:125], s[34:35], 0, v[122:123]
	global_load_dwordx4 v[92:95], v[124:125], off
	v_add_u32_e32 v122, 0xfa010000, v120
	v_mov_b32_e32 v123, 0
	v_lshlrev_b64 v[122:123], 1, v[122:123]
	v_lshl_add_u64 v[124:125], s[30:31], 0, v[122:123]
	global_load_dwordx4 v[96:99], v[124:125], off
	v_lshl_add_u64 v[124:125], s[34:35], 0, v[122:123]
	global_load_dwordx4 v[100:103], v[124:125], off
	v_add_u32_e32 v122, 0xfa014000, v120
	v_mov_b32_e32 v123, 0
	v_lshlrev_b64 v[122:123], 1, v[122:123]
	v_lshl_add_u64 v[124:125], s[30:31], 0, v[122:123]
	global_load_dwordx4 v[104:107], v[124:125], off
	v_lshl_add_u64 v[124:125], s[34:35], 0, v[122:123]
	global_load_dwordx4 v[116:119], v[124:125], off
	global_load_dword v32, v[50:51], off
	s_waitcnt vmcnt(0)
	v_add_f32_e64 v16, v16, v32
	v_add_f32_e64 v17, v17, v32
	v_add_f32_e64 v18, v18, v32
	v_add_f32_e64 v19, v19, v32
	v_cvt_pk_bf16_f32 v16, v16, v17
	v_cvt_pk_bf16_f32 v17, v18, v19
	v_pk_add_f32 v[18:19], v[20:21], v[32:33] op_sel_hi:[1,0]
	v_pk_add_f32 v[20:21], v[22:23], v[32:33] op_sel_hi:[1,0]
	v_cvt_pk_bf16_f32 v18, v18, v19
	v_cvt_pk_bf16_f32 v19, v20, v21
	v_add_u32_e32 v22, 0x4000, v67
	ds_write2_b64 v22, v[16:17], v[18:19] offset1:2
	v_pk_add_f32 v[16:17], v[24:25], v[32:33] op_sel_hi:[1,0]
	v_pk_add_f32 v[18:19], v[26:27], v[32:33] op_sel_hi:[1,0]
	v_cvt_pk_bf16_f32 v16, v16, v17
	v_cvt_pk_bf16_f32 v17, v18, v19
	v_pk_add_f32 v[18:19], v[28:29], v[32:33] op_sel_hi:[1,0]
	v_pk_add_f32 v[20:21], v[30:31], v[32:33] op_sel_hi:[1,0]
	v_cvt_pk_bf16_f32 v18, v18, v19
	v_cvt_pk_bf16_f32 v19, v20, v21
	ds_write2_b64 v22, v[16:17], v[18:19] offset0:4 offset1:6
	global_load_dword v16, v[50:51], off offset:128
	v_add_u32_e32 v18, s8, v66
	v_add_u32_e32 v132, 0xfa008000, v18
	s_addk_i32 s8, 0x80
	v_lshl_add_u64 v[50:51], v[50:51], 0, s[62:63]
	s_cmpk_lg_i32 s8, 0x200
	s_waitcnt vmcnt(0)
; #define LAS __attribute__((address_space(3)))
; __device__ __forceinline__ unsigned pk2(float lo, float hi) { f32x2 v = {lo, hi}; bf16x2_t b = __builtin_convertvector(v, bf16x2_t); return __builtin_bit_cast(unsigned, b); }
; __device__ __forceinline__ float bflo(unsigned u) { return __uint_as_float(u << 16); }
; __device__ __forceinline__ float bfhi(unsigned u) { return __uint_as_float(u & 0xffff0000u); }
; template <int tbA, int tbB> ...
;     ...
;         for (int which = 0; which < 2; ++which) {
;             const int tb = which ? tbB : tbA; const f32x16& acc = which ? accB : accA;
;             const float sbv = spb[g * 128 + tb * 32 + r];
; #pragma unroll
;             for (int q = 0; q < 4; ++q) {
;                 u32x2 w; w.x = pk2(acc[4 * q + 0] + sbv, acc[4 * q + 1] + sbv); w.y = pk2(acc[4 * q + 2] + sbv, acc[4 * q + 3] + sbv);
;                 *(LAS u32x2*)(stg + which * 2560 + r * 80 + (8 * q + 4 * hh) * 2) = w;
;             }
;         }
; #pragma unroll
;         for (int which = 0; which < 2; ++which) {
;             const int tb = which ? tbB : tbA;
; #pragma unroll
;             for (int i = 0; i < 2; ++i) {
;                 const int t = (lane >> 2) + 16 * i, ck = lane & 3;
;                 const size_t a = (size_t)(tok0 + tb * 32 + t) * DH + g * 128 + cb * 32 + ck * 8;
;                 const u32x4 uu = *(const u32x4*)(U + a), gc = *(const u32x4*)(GC + a);
;                 const u32x4 mv = *(const LAS u32x4*)(stg + which * 2560 + t * 80 + ck * 16);
;                 u32x4 o; o.x = pk2(bflo(uu.x) * bflo(mv.x) * bflo(gc.x), bfhi(uu.x) * bfhi(mv.x) * bfhi(gc.x)); o.y = pk2(bflo(uu.y) * bflo(mv.y) * bflo(gc.y), bfhi(uu.y) * bfhi(mv.y) * bfhi(gc.y));
;                 o.z = pk2(bflo(uu.z) * bflo(mv.z) * bflo(gc.z), bfhi(uu.z) * bfhi(mv.z) * bfhi(gc.z)); o.w = pk2(bflo(uu.w) * bflo(mv.w) * bflo(gc.w), bfhi(uu.w) * bfhi(mv.w) * bfhi(gc.w));
;                 *(u32x4*)(OC + a) = o;
;             }
	v_pk_add_f32 v[0:1], v[0:1], v[16:17] op_sel_hi:[1,0]
	v_pk_add_f32 v[2:3], v[2:3], v[16:17] op_sel_hi:[1,0]
	v_cvt_pk_bf16_f32 v0, v0, v1
	v_cvt_pk_bf16_f32 v1, v2, v3
	v_pk_add_f32 v[2:3], v[4:5], v[16:17] op_sel_hi:[1,0]
	v_pk_add_f32 v[4:5], v[6:7], v[16:17] op_sel_hi:[1,0]
	v_cvt_pk_bf16_f32 v2, v2, v3
	v_cvt_pk_bf16_f32 v3, v4, v5
	v_add_u32_e32 v6, 0x4800, v67
	ds_write2_b64 v6, v[0:1], v[2:3] offset0:64 offset1:66
	v_pk_add_f32 v[0:1], v[8:9], v[16:17] op_sel_hi:[1,0]
	v_pk_add_f32 v[2:3], v[10:11], v[16:17] op_sel_hi:[1,0]
	v_cvt_pk_bf16_f32 v0, v0, v1
	v_cvt_pk_bf16_f32 v1, v2, v3
	v_pk_add_f32 v[2:3], v[12:13], v[16:17] op_sel_hi:[1,0]
	v_pk_add_f32 v[4:5], v[14:15], v[16:17] op_sel_hi:[1,0]
	v_cvt_pk_bf16_f32 v2, v2, v3
	v_cvt_pk_bf16_f32 v3, v4, v5
	v_lshlrev_b64 v[12:13], 1, v[132:133]
	ds_write2_b64 v6, v[0:1], v[2:3] offset0:68 offset1:70
	v_mov_b32_e32 v0, v80
	v_mov_b32_e32 v1, v81
	v_mov_b32_e32 v2, v82
	v_mov_b32_e32 v3, v83
	v_mov_b32_e32 v4, v84
	v_mov_b32_e32 v5, v85
	v_mov_b32_e32 v6, v86
	v_mov_b32_e32 v7, v87
	ds_read_b128 v[8:11], v75 offset:16384
	v_add_u32_e32 v132, 0xfa00c000, v18
	s_waitcnt lgkmcnt(0)
	v_lshlrev_b32_e32 v16, 16, v8
	v_and_b32_e32 v17, 0xffff0000, v8
	v_lshlrev_b32_e32 v8, 16, v9
	v_and_b32_e32 v9, 0xffff0000, v9
	v_lshlrev_b32_e32 v14, 16, v0
	v_and_b32_e32 v15, 0xffff0000, v0
	v_pk_mul_f32 v[14:15], v[14:15], v[16:17]
	v_lshlrev_b32_e32 v16, 16, v4
	v_and_b32_e32 v17, 0xffff0000, v4
	v_pk_mul_f32 v[14:15], v[14:15], v[16:17]
	v_lshlrev_b32_e32 v4, 16, v5
	v_cvt_pk_bf16_f32 v0, v14, v15
	v_lshlrev_b32_e32 v14, 16, v1
	v_and_b32_e32 v15, 0xffff0000, v1
	v_pk_mul_f32 v[8:9], v[14:15], v[8:9]
	v_and_b32_e32 v5, 0xffff0000, v5
	v_pk_mul_f32 v[4:5], v[8:9], v[4:5]
	v_lshlrev_b32_e32 v8, 16, v10
	v_cvt_pk_bf16_f32 v1, v4, v5
	v_lshlrev_b32_e32 v4, 16, v2
	v_and_b32_e32 v5, 0xffff0000, v2
	v_and_b32_e32 v9, 0xffff0000, v10
	v_pk_mul_f32 v[4:5], v[4:5], v[8:9]
	v_lshlrev_b32_e32 v8, 16, v6
	v_and_b32_e32 v9, 0xffff0000, v6
	v_pk_mul_f32 v[4:5], v[4:5], v[8:9]
	v_lshlrev_b32_e32 v8, 16, v11
	v_cvt_pk_bf16_f32 v2, v4, v5
	v_lshlrev_b32_e32 v4, 16, v3
	v_and_b32_e32 v5, 0xffff0000, v3
	v_and_b32_e32 v9, 0xffff0000, v11
	v_pk_mul_f32 v[4:5], v[4:5], v[8:9]
	v_lshlrev_b32_e32 v6, 16, v7
	v_and_b32_e32 v7, 0xffff0000, v7
	v_pk_mul_f32 v[4:5], v[4:5], v[6:7]
	ds_read_b128 v[8:11], v75 offset:17664
	v_cvt_pk_bf16_f32 v3, v4, v5
	v_lshl_add_u64 v[4:5], s[36:37], 0, v[12:13]
	v_lshlrev_b64 v[12:13], 1, v[132:133]
	global_store_dwordx4 v[4:5], v[0:3], off
	v_mov_b32_e32 v4, v92
	v_mov_b32_e32 v5, v93
	v_mov_b32_e32 v6, v94
	v_mov_b32_e32 v7, v95
	v_mov_b32_e32 v0, v88
	v_mov_b32_e32 v1, v89
	v_mov_b32_e32 v2, v90
	v_mov_b32_e32 v3, v91
	s_waitcnt lgkmcnt(0)
	v_lshlrev_b32_e32 v16, 16, v8
	v_and_b32_e32 v17, 0xffff0000, v8
	v_lshlrev_b32_e32 v8, 16, v9
	v_and_b32_e32 v9, 0xffff0000, v9
	v_add_u32_e32 v132, 0xfa010000, v18
	v_lshlrev_b32_e32 v14, 16, v0
	v_and_b32_e32 v15, 0xffff0000, v0
	v_pk_mul_f32 v[14:15], v[14:15], v[16:17]
	v_lshlrev_b32_e32 v16, 16, v4
	v_and_b32_e32 v17, 0xffff0000, v4
	v_pk_mul_f32 v[14:15], v[14:15], v[16:17]
	v_lshlrev_b32_e32 v4, 16, v5
	v_cvt_pk_bf16_f32 v0, v14, v15
	v_lshlrev_b32_e32 v14, 16, v1
	v_and_b32_e32 v15, 0xffff0000, v1
	v_pk_mul_f32 v[8:9], v[14:15], v[8:9]
	v_and_b32_e32 v5, 0xffff0000, v5
	v_pk_mul_f32 v[4:5], v[8:9], v[4:5]
	v_lshlrev_b32_e32 v8, 16, v10
	v_cvt_pk_bf16_f32 v1, v4, v5
	v_lshlrev_b32_e32 v4, 16, v2
	v_and_b32_e32 v5, 0xffff0000, v2
	v_and_b32_e32 v9, 0xffff0000, v10
	v_pk_mul_f32 v[4:5], v[4:5], v[8:9]
	v_lshlrev_b32_e32 v8, 16, v6
	v_and_b32_e32 v9, 0xffff0000, v6
	v_pk_mul_f32 v[4:5], v[4:5], v[8:9]
	v_lshlrev_b32_e32 v8, 16, v11
	v_cvt_pk_bf16_f32 v2, v4, v5
	v_lshlrev_b32_e32 v4, 16, v3
	v_and_b32_e32 v5, 0xffff0000, v3
	v_and_b32_e32 v9, 0xffff0000, v11
	v_pk_mul_f32 v[4:5], v[4:5], v[8:9]
	v_lshlrev_b32_e32 v6, 16, v7
	v_and_b32_e32 v7, 0xffff0000, v7
	v_pk_mul_f32 v[4:5], v[4:5], v[6:7]
	ds_read_b128 v[8:11], v75 offset:18944
	v_cvt_pk_bf16_f32 v3, v4, v5
	v_lshl_add_u64 v[4:5], s[36:37], 0, v[12:13]
	v_lshlrev_b64 v[12:13], 1, v[132:133]
	global_store_dwordx4 v[4:5], v[0:3], off
	v_mov_b32_e32 v4, v100
	v_mov_b32_e32 v5, v101
	v_mov_b32_e32 v6, v102
	v_mov_b32_e32 v7, v103
	v_mov_b32_e32 v0, v96
	v_mov_b32_e32 v1, v97
	v_mov_b32_e32 v2, v98
	v_mov_b32_e32 v3, v99
	s_waitcnt lgkmcnt(0)
; #define LAS __attribute__((address_space(3)))
; __device__ __forceinline__ unsigned pk2(float lo, float hi) { f32x2 v = {lo, hi}; bf16x2_t b = __builtin_convertvector(v, bf16x2_t); return __builtin_bit_cast(unsigned, b); }
; __device__ __forceinline__ float bflo(unsigned u) { return __uint_as_float(u << 16); }
; __device__ __forceinline__ float bfhi(unsigned u) { return __uint_as_float(u & 0xffff0000u); }
; template <int tbA, int tbB> ...
;     ...
; #pragma unroll
;         for (int which = 0; which < 2; ++which) {
;             const int tb = which ? tbB : tbA;
; #pragma unroll
;             for (int i = 0; i < 2; ++i) {
;                 const int t = (lane >> 2) + 16 * i, ck = lane & 3;
;                 const size_t a = (size_t)(tok0 + tb * 32 + t) * DH + g * 128 + cb * 32 + ck * 8;
;                 const u32x4 uu = *(const u32x4*)(U + a), gc = *(const u32x4*)(GC + a);
;                 const u32x4 mv = *(const LAS u32x4*)(stg + which * 2560 + t * 80 + ck * 16);
;                 u32x4 o; o.x = pk2(bflo(uu.x) * bflo(mv.x) * bflo(gc.x), bfhi(uu.x) * bfhi(mv.x) * bfhi(gc.x)); o.y = pk2(bflo(uu.y) * bflo(mv.y) * bflo(gc.y), bfhi(uu.y) * bfhi(mv.y) * bfhi(gc.y));
;                 o.z = pk2(bflo(uu.z) * bflo(mv.z) * bflo(gc.z), bfhi(uu.z) * bfhi(mv.z) * bfhi(gc.z)); o.w = pk2(bflo(uu.w) * bflo(mv.w) * bflo(gc.w), bfhi(uu.w) * bfhi(mv.w) * bfhi(gc.w));
;                 *(u32x4*)(OC + a) = o;
;             }
	v_lshlrev_b32_e32 v16, 16, v8
	v_and_b32_e32 v17, 0xffff0000, v8
	v_lshlrev_b32_e32 v8, 16, v9
	v_and_b32_e32 v9, 0xffff0000, v9
	v_add_u32_e32 v132, 0xfa014000, v18
	v_lshlrev_b32_e32 v14, 16, v0
	v_and_b32_e32 v15, 0xffff0000, v0
	v_pk_mul_f32 v[14:15], v[14:15], v[16:17]
	v_lshlrev_b32_e32 v16, 16, v4
	v_and_b32_e32 v17, 0xffff0000, v4
	v_pk_mul_f32 v[14:15], v[14:15], v[16:17]
	v_lshlrev_b32_e32 v4, 16, v5
	v_cvt_pk_bf16_f32 v0, v14, v15
	v_lshlrev_b32_e32 v14, 16, v1
	v_and_b32_e32 v15, 0xffff0000, v1
	v_pk_mul_f32 v[8:9], v[14:15], v[8:9]
	v_and_b32_e32 v5, 0xffff0000, v5
	v_pk_mul_f32 v[4:5], v[8:9], v[4:5]
	v_lshlrev_b32_e32 v8, 16, v10
	v_cvt_pk_bf16_f32 v1, v4, v5
	v_lshlrev_b32_e32 v4, 16, v2
	v_and_b32_e32 v5, 0xffff0000, v2
	v_and_b32_e32 v9, 0xffff0000, v10
	v_pk_mul_f32 v[4:5], v[4:5], v[8:9]
	v_lshlrev_b32_e32 v8, 16, v6
	v_and_b32_e32 v9, 0xffff0000, v6
	v_pk_mul_f32 v[4:5], v[4:5], v[8:9]
	v_lshlrev_b32_e32 v8, 16, v11
	v_cvt_pk_bf16_f32 v2, v4, v5
	v_lshlrev_b32_e32 v4, 16, v3
	v_and_b32_e32 v5, 0xffff0000, v3
	v_and_b32_e32 v9, 0xffff0000, v11
	v_pk_mul_f32 v[4:5], v[4:5], v[8:9]
	v_lshlrev_b32_e32 v6, 16, v7
	v_and_b32_e32 v7, 0xffff0000, v7
	v_pk_mul_f32 v[4:5], v[4:5], v[6:7]
	ds_read_b128 v[8:11], v75 offset:20224
	v_cvt_pk_bf16_f32 v3, v4, v5
	v_lshl_add_u64 v[4:5], s[36:37], 0, v[12:13]
	v_lshlrev_b64 v[12:13], 1, v[132:133]
	global_store_dwordx4 v[4:5], v[0:3], off
	v_mov_b32_e32 v4, v116
	v_mov_b32_e32 v5, v117
	v_mov_b32_e32 v6, v118
	v_mov_b32_e32 v7, v119
	v_mov_b32_e32 v0, v104
	v_mov_b32_e32 v1, v105
	v_mov_b32_e32 v2, v106
	v_mov_b32_e32 v3, v107
	s_waitcnt lgkmcnt(0)
	v_lshlrev_b32_e32 v16, 16, v8
	v_and_b32_e32 v17, 0xffff0000, v8
	v_lshlrev_b32_e32 v8, 16, v9
	v_and_b32_e32 v9, 0xffff0000, v9
	v_lshlrev_b32_e32 v14, 16, v0
	v_and_b32_e32 v15, 0xffff0000, v0
	v_pk_mul_f32 v[14:15], v[14:15], v[16:17]
	v_lshlrev_b32_e32 v16, 16, v4
	v_and_b32_e32 v17, 0xffff0000, v4
	v_pk_mul_f32 v[14:15], v[14:15], v[16:17]
	v_lshlrev_b32_e32 v4, 16, v5
	v_cvt_pk_bf16_f32 v0, v14, v15
	v_lshlrev_b32_e32 v14, 16, v1
	v_and_b32_e32 v15, 0xffff0000, v1
	v_pk_mul_f32 v[8:9], v[14:15], v[8:9]
	v_and_b32_e32 v5, 0xffff0000, v5
	v_pk_mul_f32 v[4:5], v[8:9], v[4:5]
	v_lshlrev_b32_e32 v8, 16, v10
	v_cvt_pk_bf16_f32 v1, v4, v5
	v_lshlrev_b32_e32 v4, 16, v2
	v_and_b32_e32 v5, 0xffff0000, v2
	v_and_b32_e32 v9, 0xffff0000, v10
	v_pk_mul_f32 v[4:5], v[4:5], v[8:9]
	v_lshlrev_b32_e32 v8, 16, v6
	v_and_b32_e32 v9, 0xffff0000, v6
	v_pk_mul_f32 v[4:5], v[4:5], v[8:9]
	v_lshlrev_b32_e32 v8, 16, v11
	v_cvt_pk_bf16_f32 v2, v4, v5
	v_lshlrev_b32_e32 v4, 16, v3
	v_and_b32_e32 v5, 0xffff0000, v3
	v_and_b32_e32 v9, 0xffff0000, v11
	v_pk_mul_f32 v[4:5], v[4:5], v[8:9]
	v_lshlrev_b32_e32 v6, 16, v7
	v_and_b32_e32 v7, 0xffff0000, v7
	v_pk_mul_f32 v[4:5], v[4:5], v[6:7]
	s_nop 0
	v_cvt_pk_bf16_f32 v3, v4, v5
	v_lshl_add_u64 v[4:5], s[36:37], 0, v[12:13]
	global_store_dwordx4 v[4:5], v[0:3], off
	s_cbranch_scc1 .LBB0_229
	s_mov_b64 s[8:9], 0

; __device__ __forceinline__ void unpack8(const u32x4 w, float* v) { v[0] = bflo(w.x); v[1] = bfhi(w.x); v[2] = bflo(w.y); v[3] = bfhi(w.y); v[4] = bflo(w.z); v[5] = bfhi(w.z); v[6] = bflo(w.w); v[7] = bfhi(w.w); }
; template <int tbA, int tbB> ...
;     for (int gi = 0; gi < 4; ++gi) {
;         const int g = gh * 4 + gi;
;         const int ch = g * 128 + cb * 32 + r;
;         const float gg = lng[ch], bb = lnb[ch];
;         const bf16_t* ap = VCT + (size_t)ch * PT + tok0 + 8 * hh;
;         const bf16_t* wp = Wbf + (size_t)g * 16384 + 8 * hh;
;         constexpr int NSB = (tbB + 1) * 2, NSA = (tbA + 1) * 2;
;         int so = 0; asm volatile("" : "+v"(so));
;         u32x4 raw[NSB]; bf16x8 wB[NSB], wA[NSA];
; #pragma unroll
;         for (int k = 0; k < NSB; ++k) { raw[k] = *(const u32x4*)(ap + 16 * k); wB[k] = *(const bf16x8*)(wp + (size_t)(tbB * 32 + r) * 128 + 16 * k); }
; #pragma unroll
;         for (int k = 0; k < NSA; ++k) wA[k] = *(const bf16x8*)(wp + (size_t)(tbA * 32 + r) * 128 + 16 * k);
;         f32x16 accA, accB;
; #pragma unroll
;         for (int i = 0; i < 16; ++i) { accA[i] = 0.f; accB[i] = 0.f; }
; #pragma unroll
;         for (int k = 0; k < NSB; ++k) {
;             float v[8]; unpack8(raw[k], v);
; #pragma unroll
;             for (int jj = 0; jj < 8; ++jj) { const float mean = stat[(16 * k + 8 * hh + jj) * 2 + so], rstd = stat[(16 * k + 8 * hh + jj) * 2 + 1 + so]; v[jj] = (v[jj] - mean) * rstd * gg + bb; }
.LBB0_233:
	v_lshl_add_u64 v[8:9], v[68:69], 0, v[148:149]
	v_mov_b32_e32 v14, 0
	global_load_dword v74, v[72:73], off
	global_load_dword v76, v[70:71], off
	global_load_dwordx4 v[0:3], v[8:9], off offset:-128
	v_lshl_add_u64 v[10:11], v[64:65], 0, v[148:149]
	v_add_co_u32_e32 v12, vcc, s97, v10
	v_lshl_add_u32 v79, v14, 2, v158
	s_nop 0
	v_addc_co_u32_e32 v13, vcc, 0, v11, vcc
	v_add_co_u32_e32 v20, vcc, s93, v10
	global_load_dwordx4 v[4:7], v[12:13], off
	global_load_dwordx4 v[80:83], v[8:9], off offset:-96
	global_load_dwordx4 v[84:87], v[12:13], off offset:32
	global_load_dwordx4 v[88:91], v[8:9], off offset:-64
	global_load_dwordx4 v[92:95], v[12:13], off offset:64
	global_load_dwordx4 v[96:99], v[8:9], off offset:-32
	global_load_dwordx4 v[100:103], v[12:13], off offset:96
	global_load_dwordx4 v[60:63], v[8:9], off
	global_load_dwordx4 v[56:59], v[12:13], off offset:128
	global_load_dwordx4 v[52:55], v[8:9], off offset:32
	global_load_dwordx4 v[48:51], v[12:13], off offset:160
	global_load_dwordx4 v[44:47], v[8:9], off offset:64
	global_load_dwordx4 v[40:43], v[12:13], off offset:192
	global_load_dwordx4 v[36:39], v[8:9], off offset:96
	global_load_dwordx4 v[32:35], v[12:13], off offset:224
	v_addc_co_u32_e32 v21, vcc, 0, v11, vcc
	v_add_u32_e32 v12, 0x2000, v79
	global_load_dwordx4 v[104:107], v[20:21], off offset:32
	v_add_u32_e32 v112, 0x2080, v79
	v_lshl_add_u64 v[64:65], v[64:65], 0, s[58:59]
	v_lshl_add_u64 v[68:69], v[68:69], 0, s[60:61]
	v_lshl_add_u64 v[70:71], v[70:71], 0, s[62:63]
	v_lshl_add_u64 v[72:73], v[72:73], 0, s[62:63]
	s_waitcnt vmcnt(14)
	v_lshlrev_b32_e32 v108, 16, v80
	v_and_b32_e32 v109, 0xffff0000, v80
	v_add_u32_e32 v80, 0x2088, v79
	v_lshlrev_b32_e32 v8, 16, v0
	v_and_b32_e32 v9, 0xffff0000, v0
	v_add_u32_e32 v0, 0x2008, v79
	ds_read2_b32 v[10:11], v0 offset1:1
	ds_read2_b32 v[12:13], v12 offset1:1
	v_lshlrev_b32_e32 v0, 16, v1
	v_and_b32_e32 v1, 0xffff0000, v1
	s_waitcnt lgkmcnt(1)
	v_mov_b32_e32 v15, v10
	s_waitcnt lgkmcnt(0)
	v_mov_b32_e32 v14, v12
	v_pk_add_f32 v[8:9], v[8:9], v[14:15] neg_lo:[0,1] neg_hi:[0,1]
	v_mov_b32_e32 v10, v13
	v_pk_mul_f32 v[8:9], v[8:9], v[10:11]
	v_add_u32_e32 v12, 0x2010, v79
	v_add_u32_e32 v10, 0x2018, v79
	ds_read2_b32 v[10:11], v10 offset1:1
	ds_read2_b32 v[12:13], v12 offset1:1
	v_pk_fma_f32 v[8:9], v[74:75], v[8:9], v[76:77] op_sel_hi:[0,1,0]
	s_waitcnt lgkmcnt(1)
	v_mov_b32_e32 v15, v10
	s_waitcnt lgkmcnt(0)
	v_mov_b32_e32 v14, v12
	v_pk_add_f32 v[0:1], v[0:1], v[14:15] neg_lo:[0,1] neg_hi:[0,1]
	v_mov_b32_e32 v10, v13
	v_pk_mul_f32 v[0:1], v[0:1], v[10:11]
	v_add_u32_e32 v14, 0x2020, v79
	v_lshlrev_b32_e32 v10, 16, v2
	v_and_b32_e32 v11, 0xffff0000, v2
	v_add_u32_e32 v2, 0x2028, v79
	ds_read2_b32 v[12:13], v2 offset1:1
	ds_read2_b32 v[14:15], v14 offset1:1
	v_lshlrev_b32_e32 v2, 16, v3
	v_and_b32_e32 v3, 0xffff0000, v3
	v_pk_fma_f32 v[0:1], v[74:75], v[0:1], v[76:77] op_sel_hi:[0,1,0]
	s_waitcnt lgkmcnt(1)
	v_mov_b32_e32 v17, v12
	s_waitcnt lgkmcnt(0)
	v_mov_b32_e32 v16, v14
	v_pk_add_f32 v[10:11], v[10:11], v[16:17] neg_lo:[0,1] neg_hi:[0,1]
	v_mov_b32_e32 v12, v15
	v_pk_mul_f32 v[10:11], v[10:11], v[12:13]
	v_add_u32_e32 v14, 0x2030, v79
	v_add_u32_e32 v12, 0x2038, v79
	ds_read2_b32 v[12:13], v12 offset1:1
	ds_read2_b32 v[14:15], v14 offset1:1
	global_load_dwordx4 v[20:23], v[20:21], off
	ds_read2_b32 v[110:111], v80 offset1:1
	ds_read2_b32 v[112:113], v112 offset1:1
	v_lshlrev_b32_e32 v80, 16, v81
	v_and_b32_e32 v81, 0xffff0000, v81
	s_waitcnt lgkmcnt(2)
	v_mov_b32_e32 v16, v14
	s_waitcnt lgkmcnt(1)
	v_mov_b32_e32 v115, v110
	s_waitcnt lgkmcnt(0)
	v_mov_b32_e32 v114, v112
	v_pk_add_f32 v[108:109], v[108:109], v[114:115] neg_lo:[0,1] neg_hi:[0,1]
	v_mov_b32_e32 v110, v113
	v_pk_mul_f32 v[108:109], v[108:109], v[110:111]
	v_add_u32_e32 v112, 0x2090, v79
	v_add_u32_e32 v110, 0x2098, v79
	ds_read2_b32 v[110:111], v110 offset1:1
	ds_read2_b32 v[112:113], v112 offset1:1
	v_mov_b32_e32 v17, v12
	v_pk_add_f32 v[2:3], v[2:3], v[16:17] neg_lo:[0,1] neg_hi:[0,1]
	v_mov_b32_e32 v12, v15
	s_waitcnt lgkmcnt(1)
	v_mov_b32_e32 v115, v110
	s_waitcnt lgkmcnt(0)
	v_mov_b32_e32 v114, v112
	v_pk_add_f32 v[80:81], v[80:81], v[114:115] neg_lo:[0,1] neg_hi:[0,1]
	v_mov_b32_e32 v110, v113
	v_pk_mul_f32 v[80:81], v[80:81], v[110:111]
	v_add_u32_e32 v114, 0x20a0, v79
	v_pk_fma_f32 v[110:111], v[74:75], v[80:81], v[76:77] op_sel_hi:[0,1,0]
	v_lshlrev_b32_e32 v80, 16, v82
	v_and_b32_e32 v81, 0xffff0000, v82
	v_add_u32_e32 v82, 0x20a8, v79
	ds_read2_b32 v[112:113], v82 offset1:1
	ds_read2_b32 v[114:115], v114 offset1:1
	v_pk_mul_f32 v[2:3], v[2:3], v[12:13]
	v_add_u32_e32 v82, 0x20b8, v79
	v_pk_fma_f32 v[10:11], v[74:75], v[10:11], v[76:77] op_sel_hi:[0,1,0]
	s_waitcnt lgkmcnt(1)
	v_mov_b32_e32 v117, v112
	s_waitcnt lgkmcnt(0)
	v_mov_b32_e32 v116, v114
	v_pk_add_f32 v[80:81], v[80:81], v[116:117] neg_lo:[0,1] neg_hi:[0,1]
	v_mov_b32_e32 v112, v115
	v_pk_mul_f32 v[80:81], v[80:81], v[112:113]
	v_add_u32_e32 v114, 0x20b0, v79
	v_pk_fma_f32 v[2:3], v[74:75], v[2:3], v[76:77] op_sel_hi:[0,1,0]
	v_pk_fma_f32 v[112:113], v[74:75], v[80:81], v[76:77] op_sel_hi:[0,1,0]
	v_lshlrev_b32_e32 v80, 16, v83
	v_and_b32_e32 v81, 0xffff0000, v83
	ds_read2_b32 v[82:83], v82 offset1:1
	ds_read2_b32 v[114:115], v114 offset1:1
	v_cvt_pk_bf16_f32 v16, v8, v9
	v_cvt_pk_bf16_f32 v17, v0, v1
	v_cvt_pk_bf16_f32 v18, v10, v11
	v_cvt_pk_bf16_f32 v19, v2, v3
	s_waitcnt lgkmcnt(0)
; __device__ __forceinline__ unsigned pk2(float lo, float hi) { f32x2 v = {lo, hi}; bf16x2_t b = __builtin_convertvector(v, bf16x2_t); return __builtin_bit_cast(unsigned, b); }
; #define MFMA32(a, b, c) __builtin_amdgcn_mfma_f32_32x32x16_bf16((a), (b), (c), 0, 0, 0)
; __device__ __forceinline__ void unpack8(const u32x4 w, float* v) { v[0] = bflo(w.x); v[1] = bfhi(w.x); v[2] = bflo(w.y); v[3] = bfhi(w.y); v[4] = bflo(w.z); v[5] = bfhi(w.z); v[6] = bflo(w.w); v[7] = bfhi(w.w); }
; template <int tbA, int tbB> ...
;     ...
; #pragma unroll
;         for (int k = 0; k < NSB; ++k) {
;             float v[8]; unpack8(raw[k], v);
; #pragma unroll
;             for (int jj = 0; jj < 8; ++jj) { const float mean = stat[(16 * k + 8 * hh + jj) * 2 + so], rstd = stat[(16 * k + 8 * hh + jj) * 2 + 1 + so]; v[jj] = (v[jj] - mean) * rstd * gg + bb; }
;             u32x4 af; af.x = pk2(v[0], v[1]); af.y = pk2(v[2], v[3]); af.z = pk2(v[4], v[5]); af.w = pk2(v[6], v[7]);
;             accB = MFMA32(__builtin_bit_cast(bf16x8, af), wB[k], accB);
;             if (k < NSA) accA = MFMA32(__builtin_bit_cast(bf16x8, af), wA[k < NSA ? k : 0], accA);
;         }
	v_mov_b32_e32 v116, v114
	v_mov_b32_e32 v117, v82
	v_mfma_f32_32x32x16_bf16 v[0:15], v[16:19], v[4:7], 0
	v_add_f32_e64 v80, v80, -v116
	v_add_f32_e64 v81, v81, -v117
	v_mov_b32_e32 v82, v115
	v_mul_f32_e64 v80, v80, v82
	v_mul_f32_e64 v81, v81, v83
	v_pk_fma_f32 v[108:109], v[74:75], v[108:109], v[76:77] op_sel_hi:[0,1,0]
	v_pk_fma_f32 v[114:115], v[74:75], v[80:81], v[76:77] op_sel_hi:[0,1,0]
	v_cvt_pk_bf16_f32 v80, v108, v109
	v_cvt_pk_bf16_f32 v81, v110, v111
	v_cvt_pk_bf16_f32 v82, v112, v113
	v_cvt_pk_bf16_f32 v83, v114, v115
	s_waitcnt vmcnt(0)
	v_mfma_f32_32x32x16_bf16 v[16:31], v[16:19], v[20:23], 0
	v_mfma_f32_32x32x16_bf16 v[0:15], v[80:83], v[84:87], v[0:15]
	v_add_u32_e32 v84, 0x2100, v79
	v_mfma_f32_32x32x16_bf16 v[16:31], v[80:83], v[104:107], v[16:31]
	v_add_u32_e32 v82, 0x2108, v79
	ds_read2_b32 v[82:83], v82 offset1:1
	ds_read2_b32 v[84:85], v84 offset1:1
	v_lshlrev_b32_e32 v80, 16, v88
	v_and_b32_e32 v81, 0xffff0000, v88
	s_waitcnt lgkmcnt(1)
	v_mov_b32_e32 v87, v82
	s_waitcnt lgkmcnt(0)
	v_mov_b32_e32 v86, v84
	v_pk_add_f32 v[80:81], v[80:81], v[86:87] neg_lo:[0,1] neg_hi:[0,1]
	v_add_u32_e32 v86, 0x2110, v79
	v_add_u32_e32 v84, 0x2118, v79
	v_mov_b32_e32 v82, v85
	ds_read2_b32 v[84:85], v84 offset1:1
	ds_read2_b32 v[86:87], v86 offset1:1
	v_pk_mul_f32 v[80:81], v[80:81], v[82:83]
	v_lshlrev_b32_e32 v82, 16, v89
	v_and_b32_e32 v83, 0xffff0000, v89
	s_waitcnt lgkmcnt(1)
	v_mov_b32_e32 v89, v84
	s_waitcnt lgkmcnt(0)
	v_mov_b32_e32 v88, v86
	v_pk_add_f32 v[82:83], v[82:83], v[88:89] neg_lo:[0,1] neg_hi:[0,1]
	v_add_u32_e32 v88, 0x2120, v79
	v_add_u32_e32 v86, 0x2128, v79
	v_mov_b32_e32 v84, v87
	ds_read2_b32 v[86:87], v86 offset1:1
	ds_read2_b32 v[88:89], v88 offset1:1
	v_pk_mul_f32 v[82:83], v[82:83], v[84:85]
	v_lshlrev_b32_e32 v84, 16, v90
	v_and_b32_e32 v85, 0xffff0000, v90
	s_waitcnt lgkmcnt(1)
	v_mov_b32_e32 v105, v86
	s_waitcnt lgkmcnt(0)
	v_mov_b32_e32 v104, v88
	v_pk_add_f32 v[84:85], v[84:85], v[104:105] neg_lo:[0,1] neg_hi:[0,1]
	v_mov_b32_e32 v86, v89
	v_add_u32_e32 v90, 0x2130, v79
	v_add_u32_e32 v88, 0x2138, v79
	v_pk_mul_f32 v[84:85], v[84:85], v[86:87]
	v_lshlrev_b32_e32 v86, 16, v91
	v_and_b32_e32 v87, 0xffff0000, v91
	ds_read2_b32 v[88:89], v88 offset1:1
	ds_read2_b32 v[90:91], v90 offset1:1
	v_pk_fma_f32 v[80:81], v[74:75], v[80:81], v[76:77] op_sel_hi:[0,1,0]
	v_pk_fma_f32 v[82:83], v[74:75], v[82:83], v[76:77] op_sel_hi:[0,1,0]
	v_pk_fma_f32 v[84:85], v[74:75], v[84:85], v[76:77] op_sel_hi:[0,1,0]
	s_waitcnt lgkmcnt(1)
	v_mov_b32_e32 v105, v88
	s_waitcnt lgkmcnt(0)
	v_mov_b32_e32 v104, v90
	v_pk_add_f32 v[86:87], v[86:87], v[104:105] neg_lo:[0,1] neg_hi:[0,1]
	v_mov_b32_e32 v88, v91
	v_pk_mul_f32 v[86:87], v[86:87], v[88:89]
	v_cvt_pk_bf16_f32 v80, v80, v81
	v_pk_fma_f32 v[86:87], v[74:75], v[86:87], v[76:77] op_sel_hi:[0,1,0]
	v_cvt_pk_bf16_f32 v81, v82, v83
	v_cvt_pk_bf16_f32 v82, v84, v85
	v_cvt_pk_bf16_f32 v83, v86, v87
	v_add_u32_e32 v84, 0x2180, v79
	s_nop 0
	v_mfma_f32_32x32x16_bf16 v[0:15], v[80:83], v[92:95], v[0:15]
	v_add_u32_e32 v82, 0x2188, v79
	ds_read2_b32 v[82:83], v82 offset1:1
	ds_read2_b32 v[84:85], v84 offset1:1
	v_lshlrev_b32_e32 v80, 16, v96
	v_and_b32_e32 v81, 0xffff0000, v96
	s_waitcnt lgkmcnt(1)
	v_mov_b32_e32 v87, v82
	s_waitcnt lgkmcnt(0)
	v_mov_b32_e32 v86, v84
	v_pk_add_f32 v[80:81], v[80:81], v[86:87] neg_lo:[0,1] neg_hi:[0,1]
	v_add_u32_e32 v86, 0x2190, v79
	v_add_u32_e32 v84, 0x2198, v79
	v_mov_b32_e32 v82, v85
	ds_read2_b32 v[84:85], v84 offset1:1
	ds_read2_b32 v[86:87], v86 offset1:1
	v_pk_mul_f32 v[80:81], v[80:81], v[82:83]
	v_lshlrev_b32_e32 v82, 16, v97
	v_and_b32_e32 v83, 0xffff0000, v97
	s_waitcnt lgkmcnt(1)
	v_mov_b32_e32 v89, v84
	s_waitcnt lgkmcnt(0)
	v_mov_b32_e32 v88, v86
	v_pk_add_f32 v[82:83], v[82:83], v[88:89] neg_lo:[0,1] neg_hi:[0,1]
	v_add_u32_e32 v88, 0x21a0, v79
	v_add_u32_e32 v86, 0x21a8, v79
	v_mov_b32_e32 v84, v87
	ds_read2_b32 v[86:87], v86 offset1:1
	ds_read2_b32 v[88:89], v88 offset1:1
	v_pk_mul_f32 v[82:83], v[82:83], v[84:85]
	v_lshlrev_b32_e32 v84, 16, v98
	v_and_b32_e32 v85, 0xffff0000, v98
	s_waitcnt lgkmcnt(1)
	v_mov_b32_e32 v91, v86
	s_waitcnt lgkmcnt(0)
	v_mov_b32_e32 v90, v88
	v_pk_add_f32 v[84:85], v[84:85], v[90:91] neg_lo:[0,1] neg_hi:[0,1]
	v_add_u32_e32 v90, 0x21b0, v79
	v_add_u32_e32 v88, 0x21b8, v79
	v_mov_b32_e32 v86, v89
	ds_read2_b32 v[88:89], v88 offset1:1
	ds_read2_b32 v[90:91], v90 offset1:1
	v_pk_mul_f32 v[84:85], v[84:85], v[86:87]
	v_lshlrev_b32_e32 v86, 16, v99
	v_and_b32_e32 v87, 0xffff0000, v99
	s_waitcnt lgkmcnt(1)
	v_mov_b32_e32 v93, v88
	s_waitcnt lgkmcnt(0)
	v_mov_b32_e32 v92, v90
	v_pk_add_f32 v[86:87], v[86:87], v[92:93] neg_lo:[0,1] neg_hi:[0,1]
	v_mov_b32_e32 v88, v91
	v_pk_mul_f32 v[86:87], v[86:87], v[88:89]
	v_pk_fma_f32 v[80:81], v[74:75], v[80:81], v[76:77] op_sel_hi:[0,1,0]
	v_pk_fma_f32 v[82:83], v[74:75], v[82:83], v[76:77] op_sel_hi:[0,1,0]
	v_pk_fma_f32 v[84:85], v[74:75], v[84:85], v[76:77] op_sel_hi:[0,1,0]
	v_pk_fma_f32 v[86:87], v[74:75], v[86:87], v[76:77] op_sel_hi:[0,1,0]
	v_cvt_pk_bf16_f32 v80, v80, v81
	v_cvt_pk_bf16_f32 v81, v82, v83
	v_cvt_pk_bf16_f32 v82, v84, v85
	v_cvt_pk_bf16_f32 v83, v86, v87
	v_add_u32_e32 v84, 0x2200, v79
	s_nop 0
	v_mfma_f32_32x32x16_bf16 v[0:15], v[80:83], v[100:103], v[0:15]
	v_lshlrev_b32_e32 v80, 16, v60
	v_and_b32_e32 v81, 0xffff0000, v60
	v_add_u32_e32 v60, 0x2208, v79
	ds_read2_b32 v[82:83], v60 offset1:1
	ds_read2_b32 v[84:85], v84 offset1:1
	v_lshlrev_b32_e32 v60, 16, v61
	v_and_b32_e32 v61, 0xffff0000, v61
	s_waitcnt lgkmcnt(1)
	v_mov_b32_e32 v87, v82
	s_waitcnt lgkmcnt(0)
; __device__ __forceinline__ unsigned pk2(float lo, float hi) { f32x2 v = {lo, hi}; bf16x2_t b = __builtin_convertvector(v, bf16x2_t); return __builtin_bit_cast(unsigned, b); }
; #define MFMA32(a, b, c) __builtin_amdgcn_mfma_f32_32x32x16_bf16((a), (b), (c), 0, 0, 0)
; __device__ __forceinline__ void unpack8(const u32x4 w, float* v) { v[0] = bflo(w.x); v[1] = bfhi(w.x); v[2] = bflo(w.y); v[3] = bfhi(w.y); v[4] = bflo(w.z); v[5] = bfhi(w.z); v[6] = bflo(w.w); v[7] = bfhi(w.w); }
; template <int tbA, int tbB> ...
;     ...
; #pragma unroll
;         for (int k = 0; k < NSB; ++k) {
;             float v[8]; unpack8(raw[k], v);
; #pragma unroll
;             for (int jj = 0; jj < 8; ++jj) { const float mean = stat[(16 * k + 8 * hh + jj) * 2 + so], rstd = stat[(16 * k + 8 * hh + jj) * 2 + 1 + so]; v[jj] = (v[jj] - mean) * rstd * gg + bb; }
;             u32x4 af; af.x = pk2(v[0], v[1]); af.y = pk2(v[2], v[3]); af.z = pk2(v[4], v[5]); af.w = pk2(v[6], v[7]);
;             accB = MFMA32(__builtin_bit_cast(bf16x8, af), wB[k], accB);
;             if (k < NSA) accA = MFMA32(__builtin_bit_cast(bf16x8, af), wA[k < NSA ? k : 0], accA);
;         }
	v_mov_b32_e32 v86, v84
	v_pk_add_f32 v[80:81], v[80:81], v[86:87] neg_lo:[0,1] neg_hi:[0,1]
	v_mov_b32_e32 v82, v85
	v_pk_mul_f32 v[80:81], v[80:81], v[82:83]
	v_add_u32_e32 v84, 0x2210, v79
	v_add_u32_e32 v82, 0x2218, v79
	ds_read2_b32 v[82:83], v82 offset1:1
	ds_read2_b32 v[84:85], v84 offset1:1
	v_pk_fma_f32 v[80:81], v[74:75], v[80:81], v[76:77] op_sel_hi:[0,1,0]
	s_waitcnt lgkmcnt(1)
	v_mov_b32_e32 v87, v82
	s_waitcnt lgkmcnt(0)
	v_mov_b32_e32 v86, v84
	v_pk_add_f32 v[60:61], v[60:61], v[86:87] neg_lo:[0,1] neg_hi:[0,1]
	v_mov_b32_e32 v82, v85
	v_pk_mul_f32 v[60:61], v[60:61], v[82:83]
	v_add_u32_e32 v86, 0x2220, v79
	v_pk_fma_f32 v[82:83], v[74:75], v[60:61], v[76:77] op_sel_hi:[0,1,0]
	v_lshlrev_b32_e32 v60, 16, v62
	v_and_b32_e32 v61, 0xffff0000, v62
	v_add_u32_e32 v62, 0x2228, v79
	ds_read2_b32 v[84:85], v62 offset1:1
	ds_read2_b32 v[86:87], v86 offset1:1
	v_add_u32_e32 v62, 0x2238, v79
	s_waitcnt lgkmcnt(1)
	v_mov_b32_e32 v89, v84
	s_waitcnt lgkmcnt(0)
	v_mov_b32_e32 v88, v86
	v_pk_add_f32 v[60:61], v[60:61], v[88:89] neg_lo:[0,1] neg_hi:[0,1]
	v_mov_b32_e32 v84, v87
	v_pk_mul_f32 v[60:61], v[60:61], v[84:85]
	v_add_u32_e32 v86, 0x2230, v79
	v_pk_fma_f32 v[84:85], v[74:75], v[60:61], v[76:77] op_sel_hi:[0,1,0]
	v_lshlrev_b32_e32 v60, 16, v63
	v_and_b32_e32 v61, 0xffff0000, v63
	ds_read2_b32 v[62:63], v62 offset1:1
	ds_read2_b32 v[86:87], v86 offset1:1
	s_waitcnt lgkmcnt(1)
	v_mov_b32_e32 v89, v62
	s_waitcnt lgkmcnt(0)
	v_mov_b32_e32 v88, v86
	v_pk_add_f32 v[60:61], v[60:61], v[88:89] neg_lo:[0,1] neg_hi:[0,1]
	v_mov_b32_e32 v62, v87
	v_pk_mul_f32 v[60:61], v[60:61], v[62:63]
	v_cvt_pk_bf16_f32 v62, v84, v85
	v_pk_fma_f32 v[86:87], v[74:75], v[60:61], v[76:77] op_sel_hi:[0,1,0]
	v_cvt_pk_bf16_f32 v60, v80, v81
	v_cvt_pk_bf16_f32 v61, v82, v83
	v_cvt_pk_bf16_f32 v63, v86, v87
	s_nop 1
	v_mfma_f32_32x32x16_bf16 v[0:15], v[60:63], v[56:59], v[0:15]
	v_add_u32_e32 v60, 0x2280, v79
	v_lshlrev_b32_e32 v56, 16, v52
	v_and_b32_e32 v57, 0xffff0000, v52
	v_add_u32_e32 v52, 0x2288, v79
	ds_read2_b32 v[58:59], v52 offset1:1
	ds_read2_b32 v[60:61], v60 offset1:1
	v_lshlrev_b32_e32 v52, 16, v53
	v_and_b32_e32 v53, 0xffff0000, v53
	s_waitcnt lgkmcnt(1)
	v_mov_b32_e32 v63, v58
	s_waitcnt lgkmcnt(0)
	v_mov_b32_e32 v62, v60
	v_pk_add_f32 v[56:57], v[56:57], v[62:63] neg_lo:[0,1] neg_hi:[0,1]
	v_mov_b32_e32 v58, v61
	v_pk_mul_f32 v[56:57], v[56:57], v[58:59]
	v_add_u32_e32 v60, 0x2290, v79
	v_add_u32_e32 v58, 0x2298, v79
	ds_read2_b32 v[58:59], v58 offset1:1
	ds_read2_b32 v[60:61], v60 offset1:1
	v_pk_fma_f32 v[56:57], v[74:75], v[56:57], v[76:77] op_sel_hi:[0,1,0]
	s_waitcnt lgkmcnt(1)
	v_mov_b32_e32 v63, v58
	s_waitcnt lgkmcnt(0)
	v_mov_b32_e32 v62, v60
	v_pk_add_f32 v[52:53], v[52:53], v[62:63] neg_lo:[0,1] neg_hi:[0,1]
	v_mov_b32_e32 v58, v61
	v_pk_mul_f32 v[52:53], v[52:53], v[58:59]
	v_add_u32_e32 v62, 0x22a0, v79
	v_pk_fma_f32 v[58:59], v[74:75], v[52:53], v[76:77] op_sel_hi:[0,1,0]
	v_lshlrev_b32_e32 v52, 16, v54
	v_and_b32_e32 v53, 0xffff0000, v54
	v_add_u32_e32 v54, 0x22a8, v79
	ds_read2_b32 v[60:61], v54 offset1:1
	ds_read2_b32 v[62:63], v62 offset1:1
	v_add_u32_e32 v54, 0x22b8, v79
	s_waitcnt lgkmcnt(1)
	v_mov_b32_e32 v81, v60
	s_waitcnt lgkmcnt(0)
	v_mov_b32_e32 v80, v62
	v_pk_add_f32 v[52:53], v[52:53], v[80:81] neg_lo:[0,1] neg_hi:[0,1]
	v_mov_b32_e32 v60, v63
	v_pk_mul_f32 v[52:53], v[52:53], v[60:61]
	v_add_u32_e32 v62, 0x22b0, v79
	v_pk_fma_f32 v[60:61], v[74:75], v[52:53], v[76:77] op_sel_hi:[0,1,0]
	v_lshlrev_b32_e32 v52, 16, v55
	v_and_b32_e32 v53, 0xffff0000, v55
	ds_read2_b32 v[54:55], v54 offset1:1
	ds_read2_b32 v[62:63], v62 offset1:1
	s_waitcnt lgkmcnt(1)
	v_mov_b32_e32 v81, v54
	s_waitcnt lgkmcnt(0)
	v_mov_b32_e32 v80, v62
	v_pk_add_f32 v[52:53], v[52:53], v[80:81] neg_lo:[0,1] neg_hi:[0,1]
	v_mov_b32_e32 v54, v63
	v_pk_mul_f32 v[52:53], v[52:53], v[54:55]
	v_cvt_pk_bf16_f32 v54, v60, v61
	v_pk_fma_f32 v[62:63], v[74:75], v[52:53], v[76:77] op_sel_hi:[0,1,0]
	v_cvt_pk_bf16_f32 v52, v56, v57
	v_cvt_pk_bf16_f32 v53, v58, v59
	v_cvt_pk_bf16_f32 v55, v62, v63
	s_nop 1
	v_mfma_f32_32x32x16_bf16 v[0:15], v[52:55], v[48:51], v[0:15]
	v_add_u32_e32 v52, 0x2300, v79
	v_lshlrev_b32_e32 v48, 16, v44
	v_and_b32_e32 v49, 0xffff0000, v44
	v_add_u32_e32 v44, 0x2308, v79
	ds_read2_b32 v[50:51], v44 offset1:1
	ds_read2_b32 v[52:53], v52 offset1:1
	v_lshlrev_b32_e32 v44, 16, v45
	v_and_b32_e32 v45, 0xffff0000, v45
	s_waitcnt lgkmcnt(1)
	v_mov_b32_e32 v55, v50
	s_waitcnt lgkmcnt(0)
	v_mov_b32_e32 v54, v52
	v_pk_add_f32 v[48:49], v[48:49], v[54:55] neg_lo:[0,1] neg_hi:[0,1]
	v_mov_b32_e32 v50, v53
	v_pk_mul_f32 v[48:49], v[48:49], v[50:51]
	v_add_u32_e32 v52, 0x2310, v79
	v_add_u32_e32 v50, 0x2318, v79
	ds_read2_b32 v[50:51], v50 offset1:1
	ds_read2_b32 v[52:53], v52 offset1:1
	v_pk_fma_f32 v[48:49], v[74:75], v[48:49], v[76:77] op_sel_hi:[0,1,0]
	s_waitcnt lgkmcnt(1)
	v_mov_b32_e32 v55, v50
	s_waitcnt lgkmcnt(0)
	v_mov_b32_e32 v54, v52
	v_pk_add_f32 v[44:45], v[44:45], v[54:55] neg_lo:[0,1] neg_hi:[0,1]
	v_mov_b32_e32 v50, v53
	v_pk_mul_f32 v[44:45], v[44:45], v[50:51]
	v_add_u32_e32 v54, 0x2320, v79
	v_pk_fma_f32 v[50:51], v[74:75], v[44:45], v[76:77] op_sel_hi:[0,1,0]
	v_lshlrev_b32_e32 v44, 16, v46
	v_and_b32_e32 v45, 0xffff0000, v46
	v_add_u32_e32 v46, 0x2328, v79
	ds_read2_b32 v[52:53], v46 offset1:1
	ds_read2_b32 v[54:55], v54 offset1:1
	v_add_u32_e32 v46, 0x2338, v79
	s_waitcnt lgkmcnt(1)
	v_mov_b32_e32 v57, v52
	s_waitcnt lgkmcnt(0)
; #define LAS __attribute__((address_space(3)))
; __device__ __forceinline__ unsigned pk2(float lo, float hi) { f32x2 v = {lo, hi}; bf16x2_t b = __builtin_convertvector(v, bf16x2_t); return __builtin_bit_cast(unsigned, b); }
; #define MFMA32(a, b, c) __builtin_amdgcn_mfma_f32_32x32x16_bf16((a), (b), (c), 0, 0, 0)
; __device__ __forceinline__ void unpack8(const u32x4 w, float* v) { v[0] = bflo(w.x); v[1] = bfhi(w.x); v[2] = bflo(w.y); v[3] = bfhi(w.y); v[4] = bflo(w.z); v[5] = bfhi(w.z); v[6] = bflo(w.w); v[7] = bfhi(w.w); }
; template <int tbA, int tbB> ...
;     ...
; #pragma unroll
;         for (int k = 0; k < NSB; ++k) {
;             float v[8]; unpack8(raw[k], v);
; #pragma unroll
;             for (int jj = 0; jj < 8; ++jj) { const float mean = stat[(16 * k + 8 * hh + jj) * 2 + so], rstd = stat[(16 * k + 8 * hh + jj) * 2 + 1 + so]; v[jj] = (v[jj] - mean) * rstd * gg + bb; }
;             u32x4 af; af.x = pk2(v[0], v[1]); af.y = pk2(v[2], v[3]); af.z = pk2(v[4], v[5]); af.w = pk2(v[6], v[7]);
;             accB = MFMA32(__builtin_bit_cast(bf16x8, af), wB[k], accB);
;             if (k < NSA) accA = MFMA32(__builtin_bit_cast(bf16x8, af), wA[k < NSA ? k : 0], accA);
;         }
; #pragma unroll
;         for (int which = 0; which < 2; ++which) {
;             const int tb = which ? tbB : tbA; const f32x16& acc = which ? accB : accA;
;             const float sbv = spb[g * 128 + tb * 32 + r];
; #pragma unroll
;             for (int q = 0; q < 4; ++q) {
;                 u32x2 w; w.x = pk2(acc[4 * q + 0] + sbv, acc[4 * q + 1] + sbv); w.y = pk2(acc[4 * q + 2] + sbv, acc[4 * q + 3] + sbv);
;                 *(LAS u32x2*)(stg + which * 2560 + r * 80 + (8 * q + 4 * hh) * 2) = w;
;             }
;         }
; #pragma unroll
;         for (int which = 0; which < 2; ++which) {
;             const int tb = which ? tbB : tbA;
; #pragma unroll
;             for (int i = 0; i < 2; ++i) {
;                 const int t = (lane >> 2) + 16 * i, ck = lane & 3;
;                 const size_t a = (size_t)(tok0 + tb * 32 + t) * DH + g * 128 + cb * 32 + ck * 8;
;                 const u32x4 uu = *(const u32x4*)(U + a), gc = *(const u32x4*)(GC + a);
	v_mov_b32_e32 v56, v54
	v_pk_add_f32 v[44:45], v[44:45], v[56:57] neg_lo:[0,1] neg_hi:[0,1]
	v_mov_b32_e32 v52, v55
	v_pk_mul_f32 v[44:45], v[44:45], v[52:53]
	v_add_u32_e32 v54, 0x2330, v79
	v_pk_fma_f32 v[52:53], v[74:75], v[44:45], v[76:77] op_sel_hi:[0,1,0]
	v_lshlrev_b32_e32 v44, 16, v47
	v_and_b32_e32 v45, 0xffff0000, v47
	ds_read2_b32 v[46:47], v46 offset1:1
	ds_read2_b32 v[54:55], v54 offset1:1
	s_waitcnt lgkmcnt(1)
	v_mov_b32_e32 v57, v46
	s_waitcnt lgkmcnt(0)
	v_mov_b32_e32 v56, v54
	v_pk_add_f32 v[44:45], v[44:45], v[56:57] neg_lo:[0,1] neg_hi:[0,1]
	v_mov_b32_e32 v46, v55
	v_pk_mul_f32 v[44:45], v[44:45], v[46:47]
	v_cvt_pk_bf16_f32 v46, v52, v53
	v_pk_fma_f32 v[54:55], v[74:75], v[44:45], v[76:77] op_sel_hi:[0,1,0]
	v_cvt_pk_bf16_f32 v44, v48, v49
	v_cvt_pk_bf16_f32 v45, v50, v51
	v_cvt_pk_bf16_f32 v47, v54, v55
	s_nop 1
	v_mfma_f32_32x32x16_bf16 v[0:15], v[44:47], v[40:43], v[0:15]
	v_add_u32_e32 v44, 0x2380, v79
	v_lshlrev_b32_e32 v40, 16, v36
	v_and_b32_e32 v41, 0xffff0000, v36
	v_add_u32_e32 v36, 0x2388, v79
	ds_read2_b32 v[42:43], v36 offset1:1
	ds_read2_b32 v[44:45], v44 offset1:1
	v_lshlrev_b32_e32 v36, 16, v37
	v_and_b32_e32 v37, 0xffff0000, v37
	s_waitcnt lgkmcnt(1)
	v_mov_b32_e32 v47, v42
	s_waitcnt lgkmcnt(0)
	v_mov_b32_e32 v46, v44
	v_pk_add_f32 v[40:41], v[40:41], v[46:47] neg_lo:[0,1] neg_hi:[0,1]
	v_mov_b32_e32 v42, v45
	v_pk_mul_f32 v[40:41], v[40:41], v[42:43]
	v_add_u32_e32 v44, 0x2390, v79
	v_add_u32_e32 v42, 0x2398, v79
	ds_read2_b32 v[42:43], v42 offset1:1
	ds_read2_b32 v[44:45], v44 offset1:1
	v_pk_fma_f32 v[40:41], v[74:75], v[40:41], v[76:77] op_sel_hi:[0,1,0]
	s_waitcnt lgkmcnt(1)
	v_mov_b32_e32 v47, v42
	s_waitcnt lgkmcnt(0)
	v_mov_b32_e32 v46, v44
	v_pk_add_f32 v[36:37], v[36:37], v[46:47] neg_lo:[0,1] neg_hi:[0,1]
	v_mov_b32_e32 v42, v45
	v_pk_mul_f32 v[36:37], v[36:37], v[42:43]
	v_add_u32_e32 v46, 0x23a0, v79
	v_pk_fma_f32 v[42:43], v[74:75], v[36:37], v[76:77] op_sel_hi:[0,1,0]
	v_lshlrev_b32_e32 v36, 16, v38
	v_and_b32_e32 v37, 0xffff0000, v38
	v_add_u32_e32 v38, 0x23a8, v79
	ds_read2_b32 v[44:45], v38 offset1:1
	ds_read2_b32 v[46:47], v46 offset1:1
	v_add_u32_e32 v38, 0x23b8, v79
	s_waitcnt lgkmcnt(1)
	v_mov_b32_e32 v49, v44
	s_waitcnt lgkmcnt(0)
	v_mov_b32_e32 v48, v46
	v_pk_add_f32 v[36:37], v[36:37], v[48:49] neg_lo:[0,1] neg_hi:[0,1]
	v_mov_b32_e32 v44, v47
	v_pk_mul_f32 v[36:37], v[36:37], v[44:45]
	v_add_u32_e32 v46, 0x23b0, v79
	v_pk_fma_f32 v[44:45], v[74:75], v[36:37], v[76:77] op_sel_hi:[0,1,0]
	v_lshlrev_b32_e32 v36, 16, v39
	v_and_b32_e32 v37, 0xffff0000, v39
	ds_read2_b32 v[38:39], v38 offset1:1
	ds_read2_b32 v[46:47], v46 offset1:1
	s_waitcnt lgkmcnt(1)
	v_mov_b32_e32 v49, v38
	s_waitcnt lgkmcnt(0)
	v_mov_b32_e32 v48, v46
	v_pk_add_f32 v[36:37], v[36:37], v[48:49] neg_lo:[0,1] neg_hi:[0,1]
	v_mov_b32_e32 v38, v47
	v_pk_mul_f32 v[36:37], v[36:37], v[38:39]
	v_cvt_pk_bf16_f32 v38, v44, v45
	v_pk_fma_f32 v[46:47], v[74:75], v[36:37], v[76:77] op_sel_hi:[0,1,0]
	v_cvt_pk_bf16_f32 v36, v40, v41
	v_cvt_pk_bf16_f32 v37, v42, v43
	v_cvt_pk_bf16_f32 v39, v46, v47
	s_nop 1
	v_mfma_f32_32x32x16_bf16 v[0:15], v[36:39], v[32:35], v[0:15]
	v_add_u32_e32 v120, s8, v77
	v_add_u32_e32 v122, 0xfa000000, v120
	v_mov_b32_e32 v123, 0
	v_lshlrev_b64 v[122:123], 1, v[122:123]
	v_lshl_add_u64 v[124:125], s[30:31], 0, v[122:123]
	global_load_dwordx4 v[80:83], v[124:125], off
	v_lshl_add_u64 v[124:125], s[34:35], 0, v[122:123]
	global_load_dwordx4 v[84:87], v[124:125], off
	v_add_u32_e32 v122, 0xfa004000, v120
	v_mov_b32_e32 v123, 0
	v_lshlrev_b64 v[122:123], 1, v[122:123]
	v_lshl_add_u64 v[124:125], s[30:31], 0, v[122:123]
	global_load_dwordx4 v[88:91], v[124:125], off
	v_lshl_add_u64 v[124:125], s[34:35], 0, v[122:123]
	global_load_dwordx4 v[92:95], v[124:125], off
	v_add_u32_e32 v122, 0xfa018000, v120
	v_mov_b32_e32 v123, 0
	v_lshlrev_b64 v[122:123], 1, v[122:123]
	v_lshl_add_u64 v[124:125], s[30:31], 0, v[122:123]
	global_load_dwordx4 v[96:99], v[124:125], off
	v_lshl_add_u64 v[124:125], s[34:35], 0, v[122:123]
	global_load_dwordx4 v[100:103], v[124:125], off
	v_add_u32_e32 v122, 0xfa01c000, v120
	v_mov_b32_e32 v123, 0
	v_lshlrev_b64 v[122:123], 1, v[122:123]
	v_lshl_add_u64 v[124:125], s[30:31], 0, v[122:123]
	global_load_dwordx4 v[104:107], v[124:125], off
	v_lshl_add_u64 v[124:125], s[34:35], 0, v[122:123]
	global_load_dwordx4 v[116:119], v[124:125], off
	global_load_dword v32, v[66:67], off offset:-384
	s_waitcnt vmcnt(0)
	v_add_f32_e64 v16, v16, v32
	v_add_f32_e64 v17, v17, v32
	v_add_f32_e64 v18, v18, v32
	v_add_f32_e64 v19, v19, v32
	v_cvt_pk_bf16_f32 v16, v16, v17
	v_cvt_pk_bf16_f32 v17, v18, v19
	v_pk_add_f32 v[18:19], v[20:21], v[32:33] op_sel_hi:[1,0]
	v_pk_add_f32 v[20:21], v[22:23], v[32:33] op_sel_hi:[1,0]
	v_cvt_pk_bf16_f32 v18, v18, v19
	v_cvt_pk_bf16_f32 v19, v20, v21
	v_add_u32_e32 v22, 0x4000, v78
	ds_write2_b64 v22, v[16:17], v[18:19] offset1:2
	v_pk_add_f32 v[16:17], v[24:25], v[32:33] op_sel_hi:[1,0]
	v_pk_add_f32 v[18:19], v[26:27], v[32:33] op_sel_hi:[1,0]
	v_cvt_pk_bf16_f32 v16, v16, v17
	v_cvt_pk_bf16_f32 v17, v18, v19
	v_pk_add_f32 v[18:19], v[28:29], v[32:33] op_sel_hi:[1,0]
	v_pk_add_f32 v[20:21], v[30:31], v[32:33] op_sel_hi:[1,0]
	v_cvt_pk_bf16_f32 v18, v18, v19
	v_cvt_pk_bf16_f32 v19, v20, v21
	ds_write2_b64 v22, v[16:17], v[18:19] offset0:4 offset1:6
	global_load_dword v16, v[66:67], off
	v_add_u32_e32 v18, s8, v77
	v_add_u32_e32 v132, 0xfa000000, v18
	s_addk_i32 s8, 0x80
	v_lshl_add_u64 v[66:67], v[66:67], 0, s[62:63]
	s_cmpk_eq_i32 s8, 0x200
	s_waitcnt vmcnt(0)
; #define LAS __attribute__((address_space(3)))
; __device__ __forceinline__ unsigned pk2(float lo, float hi) { f32x2 v = {lo, hi}; bf16x2_t b = __builtin_convertvector(v, bf16x2_t); return __builtin_bit_cast(unsigned, b); }
; __device__ __forceinline__ float bflo(unsigned u) { return __uint_as_float(u << 16); }
; __device__ __forceinline__ float bfhi(unsigned u) { return __uint_as_float(u & 0xffff0000u); }
; template <int tbA, int tbB> ...
;     ...
;         for (int which = 0; which < 2; ++which) {
;             const int tb = which ? tbB : tbA; const f32x16& acc = which ? accB : accA;
;             const float sbv = spb[g * 128 + tb * 32 + r];
; #pragma unroll
;             for (int q = 0; q < 4; ++q) {
;                 u32x2 w; w.x = pk2(acc[4 * q + 0] + sbv, acc[4 * q + 1] + sbv); w.y = pk2(acc[4 * q + 2] + sbv, acc[4 * q + 3] + sbv);
;                 *(LAS u32x2*)(stg + which * 2560 + r * 80 + (8 * q + 4 * hh) * 2) = w;
;             }
;         }
; #pragma unroll
;         for (int which = 0; which < 2; ++which) {
;             const int tb = which ? tbB : tbA;
; #pragma unroll
;             for (int i = 0; i < 2; ++i) {
;                 const int t = (lane >> 2) + 16 * i, ck = lane & 3;
;                 const size_t a = (size_t)(tok0 + tb * 32 + t) * DH + g * 128 + cb * 32 + ck * 8;
;                 const u32x4 uu = *(const u32x4*)(U + a), gc = *(const u32x4*)(GC + a);
;                 const u32x4 mv = *(const LAS u32x4*)(stg + which * 2560 + t * 80 + ck * 16);
;                 u32x4 o; o.x = pk2(bflo(uu.x) * bflo(mv.x) * bflo(gc.x), bfhi(uu.x) * bfhi(mv.x) * bfhi(gc.x)); o.y = pk2(bflo(uu.y) * bflo(mv.y) * bflo(gc.y), bfhi(uu.y) * bfhi(mv.y) * bfhi(gc.y));
;                 o.z = pk2(bflo(uu.z) * bflo(mv.z) * bflo(gc.z), bfhi(uu.z) * bfhi(mv.z) * bfhi(gc.z)); o.w = pk2(bflo(uu.w) * bflo(mv.w) * bflo(gc.w), bfhi(uu.w) * bfhi(mv.w) * bfhi(gc.w));
;                 *(u32x4*)(OC + a) = o;
;             }
	v_pk_add_f32 v[0:1], v[0:1], v[16:17] op_sel_hi:[1,0]
	v_pk_add_f32 v[2:3], v[2:3], v[16:17] op_sel_hi:[1,0]
	v_cvt_pk_bf16_f32 v0, v0, v1
	v_cvt_pk_bf16_f32 v1, v2, v3
	v_pk_add_f32 v[2:3], v[4:5], v[16:17] op_sel_hi:[1,0]
	v_pk_add_f32 v[4:5], v[6:7], v[16:17] op_sel_hi:[1,0]
	v_cvt_pk_bf16_f32 v2, v2, v3
	v_cvt_pk_bf16_f32 v3, v4, v5
	v_add_u32_e32 v6, 0x4800, v78
	ds_write2_b64 v6, v[0:1], v[2:3] offset0:64 offset1:66
	v_pk_add_f32 v[0:1], v[8:9], v[16:17] op_sel_hi:[1,0]
	v_pk_add_f32 v[2:3], v[10:11], v[16:17] op_sel_hi:[1,0]
	v_cvt_pk_bf16_f32 v0, v0, v1
	v_cvt_pk_bf16_f32 v1, v2, v3
	v_pk_add_f32 v[2:3], v[12:13], v[16:17] op_sel_hi:[1,0]
	v_pk_add_f32 v[4:5], v[14:15], v[16:17] op_sel_hi:[1,0]
	v_cvt_pk_bf16_f32 v2, v2, v3
	v_cvt_pk_bf16_f32 v3, v4, v5
	v_lshlrev_b64 v[12:13], 1, v[132:133]
	ds_write2_b64 v6, v[0:1], v[2:3] offset0:68 offset1:70
	v_mov_b32_e32 v0, v80
	v_mov_b32_e32 v1, v81
	v_mov_b32_e32 v2, v82
	v_mov_b32_e32 v3, v83
	v_mov_b32_e32 v4, v84
	v_mov_b32_e32 v5, v85
	v_mov_b32_e32 v6, v86
	v_mov_b32_e32 v7, v87
	ds_read_b128 v[8:11], v75 offset:16384
	v_add_u32_e32 v132, 0xfa004000, v18
	s_waitcnt lgkmcnt(0)
	v_lshlrev_b32_e32 v16, 16, v8
	v_and_b32_e32 v17, 0xffff0000, v8
	v_lshlrev_b32_e32 v8, 16, v9
	v_and_b32_e32 v9, 0xffff0000, v9
	v_lshlrev_b32_e32 v14, 16, v0
	v_and_b32_e32 v15, 0xffff0000, v0
	v_pk_mul_f32 v[14:15], v[14:15], v[16:17]
	v_lshlrev_b32_e32 v16, 16, v4
	v_and_b32_e32 v17, 0xffff0000, v4
	v_pk_mul_f32 v[14:15], v[14:15], v[16:17]
	v_lshlrev_b32_e32 v4, 16, v5
	v_cvt_pk_bf16_f32 v0, v14, v15
	v_lshlrev_b32_e32 v14, 16, v1
	v_and_b32_e32 v15, 0xffff0000, v1
	v_pk_mul_f32 v[8:9], v[14:15], v[8:9]
	v_and_b32_e32 v5, 0xffff0000, v5
	v_pk_mul_f32 v[4:5], v[8:9], v[4:5]
	v_lshlrev_b32_e32 v8, 16, v10
	v_cvt_pk_bf16_f32 v1, v4, v5
	v_lshlrev_b32_e32 v4, 16, v2
	v_and_b32_e32 v5, 0xffff0000, v2
	v_and_b32_e32 v9, 0xffff0000, v10
	v_pk_mul_f32 v[4:5], v[4:5], v[8:9]
	v_lshlrev_b32_e32 v8, 16, v6
	v_and_b32_e32 v9, 0xffff0000, v6
	v_pk_mul_f32 v[4:5], v[4:5], v[8:9]
	v_lshlrev_b32_e32 v8, 16, v11
	v_cvt_pk_bf16_f32 v2, v4, v5
	v_lshlrev_b32_e32 v4, 16, v3
	v_and_b32_e32 v5, 0xffff0000, v3
	v_and_b32_e32 v9, 0xffff0000, v11
	v_pk_mul_f32 v[4:5], v[4:5], v[8:9]
	v_lshlrev_b32_e32 v6, 16, v7
	v_and_b32_e32 v7, 0xffff0000, v7
	v_pk_mul_f32 v[4:5], v[4:5], v[6:7]
	ds_read_b128 v[8:11], v75 offset:17664
	v_cvt_pk_bf16_f32 v3, v4, v5
	v_lshl_add_u64 v[4:5], s[36:37], 0, v[12:13]
	v_lshlrev_b64 v[12:13], 1, v[132:133]
	global_store_dwordx4 v[4:5], v[0:3], off
	v_mov_b32_e32 v4, v92
	v_mov_b32_e32 v5, v93
	v_mov_b32_e32 v6, v94
	v_mov_b32_e32 v7, v95
	v_mov_b32_e32 v0, v88
	v_mov_b32_e32 v1, v89
	v_mov_b32_e32 v2, v90
	v_mov_b32_e32 v3, v91
	s_waitcnt lgkmcnt(0)
	v_lshlrev_b32_e32 v16, 16, v8
	v_and_b32_e32 v17, 0xffff0000, v8
	v_lshlrev_b32_e32 v8, 16, v9
	v_and_b32_e32 v9, 0xffff0000, v9
	v_add_u32_e32 v132, 0xfa018000, v18
	v_lshlrev_b32_e32 v14, 16, v0
	v_and_b32_e32 v15, 0xffff0000, v0
	v_pk_mul_f32 v[14:15], v[14:15], v[16:17]
	v_lshlrev_b32_e32 v16, 16, v4
	v_and_b32_e32 v17, 0xffff0000, v4
	v_pk_mul_f32 v[14:15], v[14:15], v[16:17]
	v_lshlrev_b32_e32 v4, 16, v5
	v_cvt_pk_bf16_f32 v0, v14, v15
	v_lshlrev_b32_e32 v14, 16, v1
	v_and_b32_e32 v15, 0xffff0000, v1
	v_pk_mul_f32 v[8:9], v[14:15], v[8:9]
	v_and_b32_e32 v5, 0xffff0000, v5
	v_pk_mul_f32 v[4:5], v[8:9], v[4:5]
	v_lshlrev_b32_e32 v8, 16, v10
	v_cvt_pk_bf16_f32 v1, v4, v5
	v_lshlrev_b32_e32 v4, 16, v2
	v_and_b32_e32 v5, 0xffff0000, v2
	v_and_b32_e32 v9, 0xffff0000, v10
	v_pk_mul_f32 v[4:5], v[4:5], v[8:9]
	v_lshlrev_b32_e32 v8, 16, v6
	v_and_b32_e32 v9, 0xffff0000, v6
	v_pk_mul_f32 v[4:5], v[4:5], v[8:9]
	v_lshlrev_b32_e32 v8, 16, v11
	v_cvt_pk_bf16_f32 v2, v4, v5
	v_lshlrev_b32_e32 v4, 16, v3
	v_and_b32_e32 v5, 0xffff0000, v3
	v_and_b32_e32 v9, 0xffff0000, v11
	v_pk_mul_f32 v[4:5], v[4:5], v[8:9]
	v_lshlrev_b32_e32 v6, 16, v7
	v_and_b32_e32 v7, 0xffff0000, v7
	v_pk_mul_f32 v[4:5], v[4:5], v[6:7]
	ds_read_b128 v[8:11], v75 offset:18944
	v_cvt_pk_bf16_f32 v3, v4, v5
	v_lshl_add_u64 v[4:5], s[36:37], 0, v[12:13]
	v_lshlrev_b64 v[12:13], 1, v[132:133]
	global_store_dwordx4 v[4:5], v[0:3], off
	v_mov_b32_e32 v4, v100
	v_mov_b32_e32 v5, v101
	v_mov_b32_e32 v6, v102
	v_mov_b32_e32 v7, v103
	v_mov_b32_e32 v0, v96
	v_mov_b32_e32 v1, v97
	v_mov_b32_e32 v2, v98
	v_mov_b32_e32 v3, v99
	s_waitcnt lgkmcnt(0)
; #define LAS __attribute__((address_space(3)))
; __device__ __forceinline__ unsigned pk2(float lo, float hi) { f32x2 v = {lo, hi}; bf16x2_t b = __builtin_convertvector(v, bf16x2_t); return __builtin_bit_cast(unsigned, b); }
; __device__ __forceinline__ float bflo(unsigned u) { return __uint_as_float(u << 16); }
; __device__ __forceinline__ float bfhi(unsigned u) { return __uint_as_float(u & 0xffff0000u); }
; template <int tbA, int tbB> ...
;     ...
; #pragma unroll
;         for (int which = 0; which < 2; ++which) {
;             const int tb = which ? tbB : tbA;
; #pragma unroll
;             for (int i = 0; i < 2; ++i) {
;                 const int t = (lane >> 2) + 16 * i, ck = lane & 3;
;                 const size_t a = (size_t)(tok0 + tb * 32 + t) * DH + g * 128 + cb * 32 + ck * 8;
;                 const u32x4 uu = *(const u32x4*)(U + a), gc = *(const u32x4*)(GC + a);
;                 const u32x4 mv = *(const LAS u32x4*)(stg + which * 2560 + t * 80 + ck * 16);
;                 u32x4 o; o.x = pk2(bflo(uu.x) * bflo(mv.x) * bflo(gc.x), bfhi(uu.x) * bfhi(mv.x) * bfhi(gc.x)); o.y = pk2(bflo(uu.y) * bflo(mv.y) * bflo(gc.y), bfhi(uu.y) * bfhi(mv.y) * bfhi(gc.y));
;                 o.z = pk2(bflo(uu.z) * bflo(mv.z) * bflo(gc.z), bfhi(uu.z) * bfhi(mv.z) * bfhi(gc.z)); o.w = pk2(bflo(uu.w) * bflo(mv.w) * bflo(gc.w), bfhi(uu.w) * bfhi(mv.w) * bfhi(gc.w));
;                 *(u32x4*)(OC + a) = o;
;             }
	v_lshlrev_b32_e32 v16, 16, v8
	v_and_b32_e32 v17, 0xffff0000, v8
	v_lshlrev_b32_e32 v8, 16, v9
	v_and_b32_e32 v9, 0xffff0000, v9
	v_add_u32_e32 v132, 0xfa01c000, v18
	v_lshlrev_b32_e32 v14, 16, v0
	v_and_b32_e32 v15, 0xffff0000, v0
	v_pk_mul_f32 v[14:15], v[14:15], v[16:17]
	v_lshlrev_b32_e32 v16, 16, v4
	v_and_b32_e32 v17, 0xffff0000, v4
	v_pk_mul_f32 v[14:15], v[14:15], v[16:17]
	v_lshlrev_b32_e32 v4, 16, v5
	v_cvt_pk_bf16_f32 v0, v14, v15
	v_lshlrev_b32_e32 v14, 16, v1
	v_and_b32_e32 v15, 0xffff0000, v1
	v_pk_mul_f32 v[8:9], v[14:15], v[8:9]
	v_and_b32_e32 v5, 0xffff0000, v5
	v_pk_mul_f32 v[4:5], v[8:9], v[4:5]
	v_lshlrev_b32_e32 v8, 16, v10
	v_cvt_pk_bf16_f32 v1, v4, v5
	v_lshlrev_b32_e32 v4, 16, v2
	v_and_b32_e32 v5, 0xffff0000, v2
	v_and_b32_e32 v9, 0xffff0000, v10
	v_pk_mul_f32 v[4:5], v[4:5], v[8:9]
	v_lshlrev_b32_e32 v8, 16, v6
	v_and_b32_e32 v9, 0xffff0000, v6
	v_pk_mul_f32 v[4:5], v[4:5], v[8:9]
	v_lshlrev_b32_e32 v8, 16, v11
	v_cvt_pk_bf16_f32 v2, v4, v5
	v_lshlrev_b32_e32 v4, 16, v3
	v_and_b32_e32 v5, 0xffff0000, v3
	v_and_b32_e32 v9, 0xffff0000, v11
	v_pk_mul_f32 v[4:5], v[4:5], v[8:9]
	v_lshlrev_b32_e32 v6, 16, v7
	v_and_b32_e32 v7, 0xffff0000, v7
	v_pk_mul_f32 v[4:5], v[4:5], v[6:7]
	ds_read_b128 v[8:11], v75 offset:20224
	v_cvt_pk_bf16_f32 v3, v4, v5
	v_lshl_add_u64 v[4:5], s[36:37], 0, v[12:13]
	v_lshlrev_b64 v[12:13], 1, v[132:133]
	global_store_dwordx4 v[4:5], v[0:3], off
	v_mov_b32_e32 v4, v116
	v_mov_b32_e32 v5, v117
	v_mov_b32_e32 v6, v118
	v_mov_b32_e32 v7, v119
	v_mov_b32_e32 v0, v104
	v_mov_b32_e32 v1, v105
	v_mov_b32_e32 v2, v106
	v_mov_b32_e32 v3, v107
	s_waitcnt lgkmcnt(0)
	v_lshlrev_b32_e32 v16, 16, v8
	v_and_b32_e32 v17, 0xffff0000, v8
	v_lshlrev_b32_e32 v8, 16, v9
	v_and_b32_e32 v9, 0xffff0000, v9
	v_lshlrev_b32_e32 v14, 16, v0
	v_and_b32_e32 v15, 0xffff0000, v0
	v_pk_mul_f32 v[14:15], v[14:15], v[16:17]
	v_lshlrev_b32_e32 v16, 16, v4
	v_and_b32_e32 v17, 0xffff0000, v4
	v_pk_mul_f32 v[14:15], v[14:15], v[16:17]
	v_lshlrev_b32_e32 v4, 16, v5
	v_cvt_pk_bf16_f32 v0, v14, v15
	v_lshlrev_b32_e32 v14, 16, v1
	v_and_b32_e32 v15, 0xffff0000, v1
	v_pk_mul_f32 v[8:9], v[14:15], v[8:9]
	v_and_b32_e32 v5, 0xffff0000, v5
	v_pk_mul_f32 v[4:5], v[8:9], v[4:5]
	v_lshlrev_b32_e32 v8, 16, v10
	v_cvt_pk_bf16_f32 v1, v4, v5
	v_lshlrev_b32_e32 v4, 16, v2
	v_and_b32_e32 v5, 0xffff0000, v2
	v_and_b32_e32 v9, 0xffff0000, v10
	v_pk_mul_f32 v[4:5], v[4:5], v[8:9]
	v_lshlrev_b32_e32 v8, 16, v6
	v_and_b32_e32 v9, 0xffff0000, v6
	v_pk_mul_f32 v[4:5], v[4:5], v[8:9]
	v_lshlrev_b32_e32 v8, 16, v11
	v_cvt_pk_bf16_f32 v2, v4, v5
	v_lshlrev_b32_e32 v4, 16, v3
	v_and_b32_e32 v5, 0xffff0000, v3
	v_and_b32_e32 v9, 0xffff0000, v11
	v_pk_mul_f32 v[4:5], v[4:5], v[8:9]
	v_lshlrev_b32_e32 v6, 16, v7
	v_and_b32_e32 v7, 0xffff0000, v7
	v_pk_mul_f32 v[4:5], v[4:5], v[6:7]
	s_nop 0
	v_cvt_pk_bf16_f32 v3, v4, v5
	v_lshl_add_u64 v[4:5], s[36:37], 0, v[12:13]
	global_store_dwordx4 v[4:5], v[0:3], off
	s_cbranch_scc0 .LBB0_233

; __device__ __forceinline__ void unpack8(const u32x4 w, float* v) { v[0] = bflo(w.x); v[1] = bfhi(w.x); v[2] = bflo(w.y); v[3] = bfhi(w.y); v[4] = bflo(w.z); v[5] = bfhi(w.z); v[6] = bflo(w.w); v[7] = bfhi(w.w); }
; template <int tbA, int tbB> ...
;     for (int gi = 0; gi < 4; ++gi) {
;         const int g = gh * 4 + gi;
;         const int ch = g * 128 + cb * 32 + r;
;         const float gg = lng[ch], bb = lnb[ch];
;         const bf16_t* ap = VCT + (size_t)ch * PT + tok0 + 8 * hh;
;         const bf16_t* wp = Wbf + (size_t)g * 16384 + 8 * hh;
;         constexpr int NSB = (tbB + 1) * 2, NSA = (tbA + 1) * 2;
;         int so = 0; asm volatile("" : "+v"(so));
;         u32x4 raw[NSB]; bf16x8 wB[NSB], wA[NSA];
; #pragma unroll
;         for (int k = 0; k < NSB; ++k) { raw[k] = *(const u32x4*)(ap + 16 * k); wB[k] = *(const bf16x8*)(wp + (size_t)(tbB * 32 + r) * 128 + 16 * k); }
; #pragma unroll
;         for (int k = 0; k < NSA; ++k) wA[k] = *(const bf16x8*)(wp + (size_t)(tbA * 32 + r) * 128 + 16 * k);
;         f32x16 accA, accB;
; #pragma unroll
;         for (int i = 0; i < 16; ++i) { accA[i] = 0.f; accB[i] = 0.f; }
; #pragma unroll
;         for (int k = 0; k < NSB; ++k) {
;             float v[8]; unpack8(raw[k], v);
; #pragma unroll
;             for (int jj = 0; jj < 8; ++jj) { const float mean = stat[(16 * k + 8 * hh + jj) * 2 + so], rstd = stat[(16 * k + 8 * hh + jj) * 2 + 1 + so]; v[jj] = (v[jj] - mean) * rstd * gg + bb; }
.LBB0_653:
	v_lshl_add_u64 v[8:9], v[52:53], 0, v[148:149]
	v_mov_b32_e32 v14, v133
	global_load_dword v60, v[56:57], off
	global_load_dword v62, v[54:55], off
	global_load_dwordx4 v[0:3], v[8:9], off offset:-96
	v_lshl_add_u64 v[10:11], v[58:59], 0, v[148:149]
	v_add_co_u32_e32 v12, vcc, s96, v10
	v_lshl_add_u32 v74, v14, 2, v158
	s_nop 0
	v_addc_co_u32_e32 v13, vcc, 0, v11, vcc
	v_add_co_u32_e32 v20, vcc, s97, v10
	global_load_dwordx4 v[4:7], v[12:13], off
	global_load_dwordx4 v[68:71], v[8:9], off offset:-64
	global_load_dwordx4 v[76:79], v[12:13], off offset:32
	global_load_dwordx4 v[80:83], v[8:9], off offset:-32
	global_load_dwordx4 v[84:87], v[12:13], off offset:64
	global_load_dwordx4 v[88:91], v[8:9], off
	global_load_dwordx4 v[92:95], v[12:13], off offset:96
	global_load_dwordx4 v[44:47], v[8:9], off offset:32
	global_load_dwordx4 v[40:43], v[12:13], off offset:128
	global_load_dwordx4 v[36:39], v[8:9], off offset:64
	global_load_dwordx4 v[32:35], v[12:13], off offset:160
	v_addc_co_u32_e32 v21, vcc, 0, v11, vcc
	v_add_u32_e32 v12, 0x2000, v74
	global_load_dwordx4 v[96:99], v[20:21], off offset:32
	global_load_dwordx4 v[100:103], v[20:21], off offset:64
	global_load_dwordx4 v[104:107], v[20:21], off offset:96
	v_add_u32_e32 v110, 0x2080, v74
	v_lshl_add_u64 v[58:59], v[58:59], 0, s[58:59]
	v_lshl_add_u64 v[52:53], v[52:53], 0, s[60:61]
	v_lshl_add_u64 v[54:55], v[54:55], 0, s[62:63]
	v_lshl_add_u64 v[56:57], v[56:57], 0, s[62:63]
	s_waitcnt vmcnt(12)
	v_lshlrev_b32_e32 v72, 16, v68
	v_lshlrev_b32_e32 v8, 16, v0
	v_and_b32_e32 v9, 0xffff0000, v0
	v_add_u32_e32 v0, 0x2008, v74
	ds_read2_b32 v[10:11], v0 offset1:1
	ds_read2_b32 v[12:13], v12 offset1:1
	v_lshlrev_b32_e32 v0, 16, v1
	v_and_b32_e32 v1, 0xffff0000, v1
	v_and_b32_e32 v73, 0xffff0000, v68
	s_waitcnt lgkmcnt(1)
	v_mov_b32_e32 v15, v10
	s_waitcnt lgkmcnt(0)
	v_mov_b32_e32 v14, v12
	v_pk_add_f32 v[8:9], v[8:9], v[14:15] neg_lo:[0,1] neg_hi:[0,1]
	v_mov_b32_e32 v10, v13
	v_pk_mul_f32 v[8:9], v[8:9], v[10:11]
	v_add_u32_e32 v12, 0x2010, v74
	v_add_u32_e32 v10, 0x2018, v74
	ds_read2_b32 v[10:11], v10 offset1:1
	ds_read2_b32 v[12:13], v12 offset1:1
	v_add_u32_e32 v68, 0x2088, v74
	v_pk_fma_f32 v[8:9], v[60:61], v[8:9], v[62:63] op_sel_hi:[0,1,0]
	s_waitcnt lgkmcnt(1)
	v_mov_b32_e32 v15, v10
	s_waitcnt lgkmcnt(0)
	v_mov_b32_e32 v14, v12
	v_pk_add_f32 v[0:1], v[0:1], v[14:15] neg_lo:[0,1] neg_hi:[0,1]
	v_mov_b32_e32 v10, v13
	v_pk_mul_f32 v[0:1], v[0:1], v[10:11]
	v_add_u32_e32 v14, 0x2020, v74
	v_lshlrev_b32_e32 v10, 16, v2
	v_and_b32_e32 v11, 0xffff0000, v2
	v_add_u32_e32 v2, 0x2028, v74
	ds_read2_b32 v[12:13], v2 offset1:1
	ds_read2_b32 v[14:15], v14 offset1:1
	v_lshlrev_b32_e32 v2, 16, v3
	v_and_b32_e32 v3, 0xffff0000, v3
	v_pk_fma_f32 v[0:1], v[60:61], v[0:1], v[62:63] op_sel_hi:[0,1,0]
	s_waitcnt lgkmcnt(1)
	v_mov_b32_e32 v17, v12
	s_waitcnt lgkmcnt(0)
	v_mov_b32_e32 v16, v14
	v_pk_add_f32 v[10:11], v[10:11], v[16:17] neg_lo:[0,1] neg_hi:[0,1]
	v_mov_b32_e32 v12, v15
	v_pk_mul_f32 v[10:11], v[10:11], v[12:13]
	v_add_u32_e32 v14, 0x2030, v74
	v_add_u32_e32 v12, 0x2038, v74
	ds_read2_b32 v[12:13], v12 offset1:1
	ds_read2_b32 v[14:15], v14 offset1:1
	global_load_dwordx4 v[20:23], v[20:21], off
	ds_read2_b32 v[108:109], v68 offset1:1
	ds_read2_b32 v[110:111], v110 offset1:1
	v_lshlrev_b32_e32 v68, 16, v69
	v_and_b32_e32 v69, 0xffff0000, v69
	s_waitcnt lgkmcnt(2)
	v_mov_b32_e32 v16, v14
	s_waitcnt lgkmcnt(1)
	v_mov_b32_e32 v113, v108
	s_waitcnt lgkmcnt(0)
	v_mov_b32_e32 v112, v110
	v_pk_add_f32 v[72:73], v[72:73], v[112:113] neg_lo:[0,1] neg_hi:[0,1]
	v_mov_b32_e32 v108, v111
	v_pk_mul_f32 v[72:73], v[72:73], v[108:109]
	v_add_u32_e32 v110, 0x2090, v74
	v_add_u32_e32 v108, 0x2098, v74
	ds_read2_b32 v[108:109], v108 offset1:1
	ds_read2_b32 v[110:111], v110 offset1:1
	v_mov_b32_e32 v17, v12
	v_pk_add_f32 v[2:3], v[2:3], v[16:17] neg_lo:[0,1] neg_hi:[0,1]
	v_mov_b32_e32 v12, v15
	s_waitcnt lgkmcnt(1)
	v_mov_b32_e32 v113, v108
	s_waitcnt lgkmcnt(0)
	v_mov_b32_e32 v112, v110
	v_pk_add_f32 v[68:69], v[68:69], v[112:113] neg_lo:[0,1] neg_hi:[0,1]
	v_mov_b32_e32 v108, v111
	v_pk_mul_f32 v[68:69], v[68:69], v[108:109]
	v_add_u32_e32 v112, 0x20a0, v74
	v_pk_fma_f32 v[108:109], v[60:61], v[68:69], v[62:63] op_sel_hi:[0,1,0]
	v_lshlrev_b32_e32 v68, 16, v70
	v_and_b32_e32 v69, 0xffff0000, v70
	v_add_u32_e32 v70, 0x20a8, v74
	ds_read2_b32 v[110:111], v70 offset1:1
	ds_read2_b32 v[112:113], v112 offset1:1
	v_pk_mul_f32 v[2:3], v[2:3], v[12:13]
	v_add_u32_e32 v70, 0x20b8, v74
	v_pk_fma_f32 v[10:11], v[60:61], v[10:11], v[62:63] op_sel_hi:[0,1,0]
	s_waitcnt lgkmcnt(1)
	v_mov_b32_e32 v115, v110
	s_waitcnt lgkmcnt(0)
	v_mov_b32_e32 v114, v112
	v_pk_add_f32 v[68:69], v[68:69], v[114:115] neg_lo:[0,1] neg_hi:[0,1]
	v_mov_b32_e32 v110, v113
	v_pk_mul_f32 v[68:69], v[68:69], v[110:111]
	v_add_u32_e32 v112, 0x20b0, v74
	v_pk_fma_f32 v[2:3], v[60:61], v[2:3], v[62:63] op_sel_hi:[0,1,0]
	v_pk_fma_f32 v[110:111], v[60:61], v[68:69], v[62:63] op_sel_hi:[0,1,0]
	v_lshlrev_b32_e32 v68, 16, v71
	v_and_b32_e32 v69, 0xffff0000, v71
	ds_read2_b32 v[70:71], v70 offset1:1
	ds_read2_b32 v[112:113], v112 offset1:1
	v_cvt_pk_bf16_f32 v16, v8, v9
	v_cvt_pk_bf16_f32 v17, v0, v1
	v_cvt_pk_bf16_f32 v18, v10, v11
	v_cvt_pk_bf16_f32 v19, v2, v3
	s_waitcnt lgkmcnt(0)
	v_mov_b32_e32 v114, v112
	v_mov_b32_e32 v115, v70
	v_mfma_f32_32x32x16_bf16 v[0:15], v[16:19], v[4:7], 0
	v_add_f32_e64 v68, v68, -v114
	v_add_f32_e64 v69, v69, -v115
	v_mov_b32_e32 v70, v113
	v_mul_f32_e64 v68, v68, v70
	v_mul_f32_e64 v69, v69, v71
	v_pk_fma_f32 v[72:73], v[60:61], v[72:73], v[62:63] op_sel_hi:[0,1,0]
	v_pk_fma_f32 v[112:113], v[60:61], v[68:69], v[62:63] op_sel_hi:[0,1,0]
	v_cvt_pk_bf16_f32 v68, v72, v73
	v_cvt_pk_bf16_f32 v69, v108, v109
	v_cvt_pk_bf16_f32 v70, v110, v111
	v_cvt_pk_bf16_f32 v71, v112, v113
	v_add_u32_e32 v72, 0x2100, v74
	s_waitcnt vmcnt(0)
; __device__ __forceinline__ unsigned pk2(float lo, float hi) { f32x2 v = {lo, hi}; bf16x2_t b = __builtin_convertvector(v, bf16x2_t); return __builtin_bit_cast(unsigned, b); }
; #define MFMA32(a, b, c) __builtin_amdgcn_mfma_f32_32x32x16_bf16((a), (b), (c), 0, 0, 0)
; __device__ __forceinline__ void unpack8(const u32x4 w, float* v) { v[0] = bflo(w.x); v[1] = bfhi(w.x); v[2] = bflo(w.y); v[3] = bfhi(w.y); v[4] = bflo(w.z); v[5] = bfhi(w.z); v[6] = bflo(w.w); v[7] = bfhi(w.w); }
; template <int tbA, int tbB> ...
;     ...
; #pragma unroll
;         for (int k = 0; k < NSB; ++k) {
;             float v[8]; unpack8(raw[k], v);
; #pragma unroll
;             for (int jj = 0; jj < 8; ++jj) { const float mean = stat[(16 * k + 8 * hh + jj) * 2 + so], rstd = stat[(16 * k + 8 * hh + jj) * 2 + 1 + so]; v[jj] = (v[jj] - mean) * rstd * gg + bb; }
;             u32x4 af; af.x = pk2(v[0], v[1]); af.y = pk2(v[2], v[3]); af.z = pk2(v[4], v[5]); af.w = pk2(v[6], v[7]);
;             accB = MFMA32(__builtin_bit_cast(bf16x8, af), wB[k], accB);
;             if (k < NSA) accA = MFMA32(__builtin_bit_cast(bf16x8, af), wA[k < NSA ? k : 0], accA);
;         }
	v_mfma_f32_32x32x16_bf16 v[16:31], v[16:19], v[20:23], 0
	v_mfma_f32_32x32x16_bf16 v[0:15], v[68:71], v[76:79], v[0:15]
	v_mfma_f32_32x32x16_bf16 v[16:31], v[68:71], v[96:99], v[16:31]
	v_add_u32_e32 v70, 0x2108, v74
	ds_read2_b32 v[70:71], v70 offset1:1
	ds_read2_b32 v[72:73], v72 offset1:1
	v_lshlrev_b32_e32 v68, 16, v80
	v_and_b32_e32 v69, 0xffff0000, v80
	s_waitcnt lgkmcnt(1)
	v_mov_b32_e32 v77, v70
	s_waitcnt lgkmcnt(0)
	v_mov_b32_e32 v76, v72
	v_pk_add_f32 v[68:69], v[68:69], v[76:77] neg_lo:[0,1] neg_hi:[0,1]
	v_add_u32_e32 v76, 0x2110, v74
	v_add_u32_e32 v72, 0x2118, v74
	v_mov_b32_e32 v70, v73
	ds_read2_b32 v[72:73], v72 offset1:1
	ds_read2_b32 v[76:77], v76 offset1:1
	v_pk_mul_f32 v[68:69], v[68:69], v[70:71]
	v_lshlrev_b32_e32 v70, 16, v81
	v_and_b32_e32 v71, 0xffff0000, v81
	s_waitcnt lgkmcnt(1)
	v_mov_b32_e32 v79, v72
	s_waitcnt lgkmcnt(0)
	v_mov_b32_e32 v78, v76
	v_pk_add_f32 v[70:71], v[70:71], v[78:79] neg_lo:[0,1] neg_hi:[0,1]
	v_add_u32_e32 v78, 0x2120, v74
	v_add_u32_e32 v76, 0x2128, v74
	v_mov_b32_e32 v72, v77
	ds_read2_b32 v[76:77], v76 offset1:1
	ds_read2_b32 v[78:79], v78 offset1:1
	v_pk_mul_f32 v[70:71], v[70:71], v[72:73]
	v_lshlrev_b32_e32 v72, 16, v82
	v_and_b32_e32 v73, 0xffff0000, v82
	s_waitcnt lgkmcnt(1)
	v_mov_b32_e32 v81, v76
	s_waitcnt lgkmcnt(0)
	v_mov_b32_e32 v80, v78
	v_pk_add_f32 v[72:73], v[72:73], v[80:81] neg_lo:[0,1] neg_hi:[0,1]
	v_add_u32_e32 v80, 0x2130, v74
	v_add_u32_e32 v78, 0x2138, v74
	v_mov_b32_e32 v76, v79
	ds_read2_b32 v[78:79], v78 offset1:1
	ds_read2_b32 v[80:81], v80 offset1:1
	v_pk_mul_f32 v[72:73], v[72:73], v[76:77]
	v_lshlrev_b32_e32 v76, 16, v83
	v_and_b32_e32 v77, 0xffff0000, v83
	s_waitcnt lgkmcnt(1)
	v_mov_b32_e32 v83, v78
	s_waitcnt lgkmcnt(0)
	v_mov_b32_e32 v82, v80
	v_pk_add_f32 v[76:77], v[76:77], v[82:83] neg_lo:[0,1] neg_hi:[0,1]
	v_mov_b32_e32 v78, v81
	v_pk_mul_f32 v[76:77], v[76:77], v[78:79]
	v_pk_fma_f32 v[68:69], v[60:61], v[68:69], v[62:63] op_sel_hi:[0,1,0]
	v_pk_fma_f32 v[70:71], v[60:61], v[70:71], v[62:63] op_sel_hi:[0,1,0]
	v_pk_fma_f32 v[72:73], v[60:61], v[72:73], v[62:63] op_sel_hi:[0,1,0]
	v_pk_fma_f32 v[76:77], v[60:61], v[76:77], v[62:63] op_sel_hi:[0,1,0]
	v_cvt_pk_bf16_f32 v68, v68, v69
	v_cvt_pk_bf16_f32 v69, v70, v71
	v_cvt_pk_bf16_f32 v70, v72, v73
	v_cvt_pk_bf16_f32 v71, v76, v77
	v_add_u32_e32 v72, 0x2180, v74
	s_nop 0
	v_mfma_f32_32x32x16_bf16 v[0:15], v[68:71], v[84:87], v[0:15]
	v_mfma_f32_32x32x16_bf16 v[16:31], v[68:71], v[100:103], v[16:31]
	v_add_u32_e32 v70, 0x2188, v74
	ds_read2_b32 v[70:71], v70 offset1:1
	ds_read2_b32 v[72:73], v72 offset1:1
	v_lshlrev_b32_e32 v68, 16, v88
	v_and_b32_e32 v69, 0xffff0000, v88
	s_waitcnt lgkmcnt(1)
	v_mov_b32_e32 v77, v70
	s_waitcnt lgkmcnt(0)
	v_mov_b32_e32 v76, v72
	v_pk_add_f32 v[68:69], v[68:69], v[76:77] neg_lo:[0,1] neg_hi:[0,1]
	v_add_u32_e32 v76, 0x2190, v74
	v_add_u32_e32 v72, 0x2198, v74
	v_mov_b32_e32 v70, v73
	ds_read2_b32 v[72:73], v72 offset1:1
	ds_read2_b32 v[76:77], v76 offset1:1
	v_pk_mul_f32 v[68:69], v[68:69], v[70:71]
	v_lshlrev_b32_e32 v70, 16, v89
	v_and_b32_e32 v71, 0xffff0000, v89
	s_waitcnt lgkmcnt(1)
	v_mov_b32_e32 v79, v72
	s_waitcnt lgkmcnt(0)
	v_mov_b32_e32 v78, v76
	v_pk_add_f32 v[70:71], v[70:71], v[78:79] neg_lo:[0,1] neg_hi:[0,1]
	v_add_u32_e32 v78, 0x21a0, v74
	v_add_u32_e32 v76, 0x21a8, v74
	v_mov_b32_e32 v72, v77
	ds_read2_b32 v[76:77], v76 offset1:1
	ds_read2_b32 v[78:79], v78 offset1:1
	v_pk_mul_f32 v[70:71], v[70:71], v[72:73]
	v_lshlrev_b32_e32 v72, 16, v90
	v_and_b32_e32 v73, 0xffff0000, v90
	s_waitcnt lgkmcnt(1)
	v_mov_b32_e32 v81, v76
	s_waitcnt lgkmcnt(0)
	v_mov_b32_e32 v80, v78
	v_pk_add_f32 v[72:73], v[72:73], v[80:81] neg_lo:[0,1] neg_hi:[0,1]
	v_add_u32_e32 v80, 0x21b0, v74
	v_add_u32_e32 v78, 0x21b8, v74
	v_mov_b32_e32 v76, v79
	ds_read2_b32 v[78:79], v78 offset1:1
	ds_read2_b32 v[80:81], v80 offset1:1
	v_pk_mul_f32 v[72:73], v[72:73], v[76:77]
	v_lshlrev_b32_e32 v76, 16, v91
	v_and_b32_e32 v77, 0xffff0000, v91
	s_waitcnt lgkmcnt(1)
	v_mov_b32_e32 v83, v78
	s_waitcnt lgkmcnt(0)
	v_mov_b32_e32 v82, v80
	v_pk_add_f32 v[76:77], v[76:77], v[82:83] neg_lo:[0,1] neg_hi:[0,1]
	v_mov_b32_e32 v78, v81
	v_pk_mul_f32 v[76:77], v[76:77], v[78:79]
	v_pk_fma_f32 v[68:69], v[60:61], v[68:69], v[62:63] op_sel_hi:[0,1,0]
	v_pk_fma_f32 v[70:71], v[60:61], v[70:71], v[62:63] op_sel_hi:[0,1,0]
	v_pk_fma_f32 v[72:73], v[60:61], v[72:73], v[62:63] op_sel_hi:[0,1,0]
	v_pk_fma_f32 v[76:77], v[60:61], v[76:77], v[62:63] op_sel_hi:[0,1,0]
	v_cvt_pk_bf16_f32 v68, v68, v69
	v_cvt_pk_bf16_f32 v69, v70, v71
	v_cvt_pk_bf16_f32 v70, v72, v73
	v_cvt_pk_bf16_f32 v71, v76, v77
	v_add_u32_e32 v72, 0x2200, v74
	s_nop 0
	v_mfma_f32_32x32x16_bf16 v[0:15], v[68:71], v[92:95], v[0:15]
	v_mfma_f32_32x32x16_bf16 v[16:31], v[68:71], v[104:107], v[16:31]
	v_lshlrev_b32_e32 v68, 16, v44
	v_and_b32_e32 v69, 0xffff0000, v44
	v_add_u32_e32 v44, 0x2208, v74
	ds_read2_b32 v[70:71], v44 offset1:1
	ds_read2_b32 v[72:73], v72 offset1:1
	v_lshlrev_b32_e32 v44, 16, v45
	v_and_b32_e32 v45, 0xffff0000, v45
	s_waitcnt lgkmcnt(1)
	v_mov_b32_e32 v77, v70
	s_waitcnt lgkmcnt(0)
	v_mov_b32_e32 v76, v72
	v_pk_add_f32 v[68:69], v[68:69], v[76:77] neg_lo:[0,1] neg_hi:[0,1]
	v_mov_b32_e32 v70, v73
	v_pk_mul_f32 v[68:69], v[68:69], v[70:71]
	v_add_u32_e32 v72, 0x2210, v74
	v_add_u32_e32 v70, 0x2218, v74
	ds_read2_b32 v[70:71], v70 offset1:1
	ds_read2_b32 v[72:73], v72 offset1:1
	v_pk_fma_f32 v[68:69], v[60:61], v[68:69], v[62:63] op_sel_hi:[0,1,0]
	s_waitcnt lgkmcnt(1)
	v_mov_b32_e32 v77, v70
	s_waitcnt lgkmcnt(0)
; #define LAS __attribute__((address_space(3)))
; __device__ __forceinline__ unsigned pk2(float lo, float hi) { f32x2 v = {lo, hi}; bf16x2_t b = __builtin_convertvector(v, bf16x2_t); return __builtin_bit_cast(unsigned, b); }
; #define MFMA32(a, b, c) __builtin_amdgcn_mfma_f32_32x32x16_bf16((a), (b), (c), 0, 0, 0)
; __device__ __forceinline__ void unpack8(const u32x4 w, float* v) { v[0] = bflo(w.x); v[1] = bfhi(w.x); v[2] = bflo(w.y); v[3] = bfhi(w.y); v[4] = bflo(w.z); v[5] = bfhi(w.z); v[6] = bflo(w.w); v[7] = bfhi(w.w); }
; template <int tbA, int tbB> ...
;     ...
; #pragma unroll
;         for (int k = 0; k < NSB; ++k) {
;             float v[8]; unpack8(raw[k], v);
; #pragma unroll
;             for (int jj = 0; jj < 8; ++jj) { const float mean = stat[(16 * k + 8 * hh + jj) * 2 + so], rstd = stat[(16 * k + 8 * hh + jj) * 2 + 1 + so]; v[jj] = (v[jj] - mean) * rstd * gg + bb; }
;             u32x4 af; af.x = pk2(v[0], v[1]); af.y = pk2(v[2], v[3]); af.z = pk2(v[4], v[5]); af.w = pk2(v[6], v[7]);
;             accB = MFMA32(__builtin_bit_cast(bf16x8, af), wB[k], accB);
;             if (k < NSA) accA = MFMA32(__builtin_bit_cast(bf16x8, af), wA[k < NSA ? k : 0], accA);
;         }
; #pragma unroll
;         for (int which = 0; which < 2; ++which) {
;             const int tb = which ? tbB : tbA; const f32x16& acc = which ? accB : accA;
;             const float sbv = spb[g * 128 + tb * 32 + r];
; #pragma unroll
;             for (int q = 0; q < 4; ++q) {
;                 u32x2 w; w.x = pk2(acc[4 * q + 0] + sbv, acc[4 * q + 1] + sbv); w.y = pk2(acc[4 * q + 2] + sbv, acc[4 * q + 3] + sbv);
;                 *(LAS u32x2*)(stg + which * 2560 + r * 80 + (8 * q + 4 * hh) * 2) = w;
;             }
;         }
; #pragma unroll
;         for (int which = 0; which < 2; ++which) {
;             const int tb = which ? tbB : tbA;
; #pragma unroll
;             for (int i = 0; i < 2; ++i) {
;                 const int t = (lane >> 2) + 16 * i, ck = lane & 3;
;                 const size_t a = (size_t)(tok0 + tb * 32 + t) * DH + g * 128 + cb * 32 + ck * 8;
;                 const u32x4 uu = *(const u32x4*)(U + a), gc = *(const u32x4*)(GC + a);
	v_mov_b32_e32 v76, v72
	v_pk_add_f32 v[44:45], v[44:45], v[76:77] neg_lo:[0,1] neg_hi:[0,1]
	v_mov_b32_e32 v70, v73
	v_pk_mul_f32 v[44:45], v[44:45], v[70:71]
	v_add_u32_e32 v76, 0x2220, v74
	v_pk_fma_f32 v[70:71], v[60:61], v[44:45], v[62:63] op_sel_hi:[0,1,0]
	v_lshlrev_b32_e32 v44, 16, v46
	v_and_b32_e32 v45, 0xffff0000, v46
	v_add_u32_e32 v46, 0x2228, v74
	ds_read2_b32 v[72:73], v46 offset1:1
	ds_read2_b32 v[76:77], v76 offset1:1
	v_add_u32_e32 v46, 0x2238, v74
	s_waitcnt lgkmcnt(1)
	v_mov_b32_e32 v79, v72
	s_waitcnt lgkmcnt(0)
	v_mov_b32_e32 v78, v76
	v_pk_add_f32 v[44:45], v[44:45], v[78:79] neg_lo:[0,1] neg_hi:[0,1]
	v_mov_b32_e32 v72, v77
	v_pk_mul_f32 v[44:45], v[44:45], v[72:73]
	v_add_u32_e32 v76, 0x2230, v74
	v_pk_fma_f32 v[72:73], v[60:61], v[44:45], v[62:63] op_sel_hi:[0,1,0]
	v_lshlrev_b32_e32 v44, 16, v47
	v_and_b32_e32 v45, 0xffff0000, v47
	ds_read2_b32 v[46:47], v46 offset1:1
	ds_read2_b32 v[76:77], v76 offset1:1
	s_waitcnt lgkmcnt(1)
	v_mov_b32_e32 v79, v46
	s_waitcnt lgkmcnt(0)
	v_mov_b32_e32 v78, v76
	v_pk_add_f32 v[44:45], v[44:45], v[78:79] neg_lo:[0,1] neg_hi:[0,1]
	v_mov_b32_e32 v46, v77
	v_pk_mul_f32 v[44:45], v[44:45], v[46:47]
	v_cvt_pk_bf16_f32 v46, v72, v73
	v_pk_fma_f32 v[76:77], v[60:61], v[44:45], v[62:63] op_sel_hi:[0,1,0]
	v_cvt_pk_bf16_f32 v44, v68, v69
	v_cvt_pk_bf16_f32 v45, v70, v71
	v_cvt_pk_bf16_f32 v47, v76, v77
	s_nop 1
	v_mfma_f32_32x32x16_bf16 v[0:15], v[44:47], v[40:43], v[0:15]
	v_add_u32_e32 v44, 0x2280, v74
	v_lshlrev_b32_e32 v40, 16, v36
	v_and_b32_e32 v41, 0xffff0000, v36
	v_add_u32_e32 v36, 0x2288, v74
	ds_read2_b32 v[42:43], v36 offset1:1
	ds_read2_b32 v[44:45], v44 offset1:1
	v_lshlrev_b32_e32 v36, 16, v37
	v_and_b32_e32 v37, 0xffff0000, v37
	s_waitcnt lgkmcnt(1)
	v_mov_b32_e32 v47, v42
	s_waitcnt lgkmcnt(0)
	v_mov_b32_e32 v46, v44
	v_pk_add_f32 v[40:41], v[40:41], v[46:47] neg_lo:[0,1] neg_hi:[0,1]
	v_mov_b32_e32 v42, v45
	v_pk_mul_f32 v[40:41], v[40:41], v[42:43]
	v_add_u32_e32 v44, 0x2290, v74
	v_add_u32_e32 v42, 0x2298, v74
	ds_read2_b32 v[42:43], v42 offset1:1
	ds_read2_b32 v[44:45], v44 offset1:1
	v_pk_fma_f32 v[40:41], v[60:61], v[40:41], v[62:63] op_sel_hi:[0,1,0]
	s_waitcnt lgkmcnt(1)
	v_mov_b32_e32 v47, v42
	s_waitcnt lgkmcnt(0)
	v_mov_b32_e32 v46, v44
	v_pk_add_f32 v[36:37], v[36:37], v[46:47] neg_lo:[0,1] neg_hi:[0,1]
	v_mov_b32_e32 v42, v45
	v_pk_mul_f32 v[36:37], v[36:37], v[42:43]
	v_add_u32_e32 v46, 0x22a0, v74
	v_pk_fma_f32 v[42:43], v[60:61], v[36:37], v[62:63] op_sel_hi:[0,1,0]
	v_lshlrev_b32_e32 v36, 16, v38
	v_and_b32_e32 v37, 0xffff0000, v38
	v_add_u32_e32 v38, 0x22a8, v74
	ds_read2_b32 v[44:45], v38 offset1:1
	ds_read2_b32 v[46:47], v46 offset1:1
	v_add_u32_e32 v38, 0x22b8, v74
	s_waitcnt lgkmcnt(1)
	v_mov_b32_e32 v69, v44
	s_waitcnt lgkmcnt(0)
	v_mov_b32_e32 v68, v46
	v_pk_add_f32 v[36:37], v[36:37], v[68:69] neg_lo:[0,1] neg_hi:[0,1]
	v_mov_b32_e32 v44, v47
	v_pk_mul_f32 v[36:37], v[36:37], v[44:45]
	v_add_u32_e32 v46, 0x22b0, v74
	v_pk_fma_f32 v[44:45], v[60:61], v[36:37], v[62:63] op_sel_hi:[0,1,0]
	v_lshlrev_b32_e32 v36, 16, v39
	v_and_b32_e32 v37, 0xffff0000, v39
	ds_read2_b32 v[38:39], v38 offset1:1
	ds_read2_b32 v[46:47], v46 offset1:1
	s_waitcnt lgkmcnt(1)
	v_mov_b32_e32 v69, v38
	s_waitcnt lgkmcnt(0)
	v_mov_b32_e32 v68, v46
	v_pk_add_f32 v[36:37], v[36:37], v[68:69] neg_lo:[0,1] neg_hi:[0,1]
	v_mov_b32_e32 v38, v47
	v_pk_mul_f32 v[36:37], v[36:37], v[38:39]
	v_cvt_pk_bf16_f32 v38, v44, v45
	v_pk_fma_f32 v[46:47], v[60:61], v[36:37], v[62:63] op_sel_hi:[0,1,0]
	v_cvt_pk_bf16_f32 v36, v40, v41
	v_cvt_pk_bf16_f32 v37, v42, v43
	v_cvt_pk_bf16_f32 v39, v46, v47
	s_nop 1
	v_mfma_f32_32x32x16_bf16 v[0:15], v[36:39], v[32:35], v[0:15]
	v_add_u32_e32 v120, s8, v66
	v_add_u32_e32 v122, 0xfa008000, v120
	v_mov_b32_e32 v123, 0
	v_lshlrev_b64 v[122:123], 1, v[122:123]
	v_lshl_add_u64 v[124:125], s[30:31], 0, v[122:123]
	global_load_dwordx4 v[80:83], v[124:125], off
	v_lshl_add_u64 v[124:125], s[34:35], 0, v[122:123]
	global_load_dwordx4 v[84:87], v[124:125], off
	v_add_u32_e32 v122, 0xfa00c000, v120
	v_mov_b32_e32 v123, 0
	v_lshlrev_b64 v[122:123], 1, v[122:123]
	v_lshl_add_u64 v[124:125], s[30:31], 0, v[122:123]
	global_load_dwordx4 v[88:91], v[124:125], off
	v_lshl_add_u64 v[124:125], s[34:35], 0, v[122:123]
	global_load_dwordx4 v[92:95], v[124:125], off
	v_add_u32_e32 v122, 0xfa010000, v120
	v_mov_b32_e32 v123, 0
	v_lshlrev_b64 v[122:123], 1, v[122:123]
	v_lshl_add_u64 v[124:125], s[30:31], 0, v[122:123]
	global_load_dwordx4 v[96:99], v[124:125], off
	v_lshl_add_u64 v[124:125], s[34:35], 0, v[122:123]
	global_load_dwordx4 v[100:103], v[124:125], off
	v_add_u32_e32 v122, 0xfa014000, v120
	v_mov_b32_e32 v123, 0
	v_lshlrev_b64 v[122:123], 1, v[122:123]
	v_lshl_add_u64 v[124:125], s[30:31], 0, v[122:123]
	global_load_dwordx4 v[104:107], v[124:125], off
	v_lshl_add_u64 v[124:125], s[34:35], 0, v[122:123]
	global_load_dwordx4 v[116:119], v[124:125], off
	global_load_dword v32, v[50:51], off offset:-128
	s_waitcnt vmcnt(0)
	v_add_f32_e64 v16, v16, v32
	v_add_f32_e64 v17, v17, v32
	v_add_f32_e64 v18, v18, v32
	v_add_f32_e64 v19, v19, v32
	v_cvt_pk_bf16_f32 v16, v16, v17
	v_cvt_pk_bf16_f32 v17, v18, v19
	v_pk_add_f32 v[18:19], v[20:21], v[32:33] op_sel_hi:[1,0]
	v_pk_add_f32 v[20:21], v[22:23], v[32:33] op_sel_hi:[1,0]
	v_cvt_pk_bf16_f32 v18, v18, v19
	v_cvt_pk_bf16_f32 v19, v20, v21
	v_add_u32_e32 v22, 0x4000, v67
	ds_write2_b64 v22, v[16:17], v[18:19] offset1:2
	v_pk_add_f32 v[16:17], v[24:25], v[32:33] op_sel_hi:[1,0]
	v_pk_add_f32 v[18:19], v[26:27], v[32:33] op_sel_hi:[1,0]
	v_cvt_pk_bf16_f32 v16, v16, v17
	v_cvt_pk_bf16_f32 v17, v18, v19
	v_pk_add_f32 v[18:19], v[28:29], v[32:33] op_sel_hi:[1,0]
	v_pk_add_f32 v[20:21], v[30:31], v[32:33] op_sel_hi:[1,0]
	v_cvt_pk_bf16_f32 v18, v18, v19
	v_cvt_pk_bf16_f32 v19, v20, v21
	ds_write2_b64 v22, v[16:17], v[18:19] offset0:4 offset1:6
	global_load_dword v16, v[50:51], off
	v_add_u32_e32 v18, s8, v66
	v_add_u32_e32 v132, 0xfa008000, v18
	s_addk_i32 s8, 0x80
	v_lshl_add_u64 v[50:51], v[50:51], 0, s[62:63]
	s_cmpk_lg_i32 s8, 0x200
	s_waitcnt vmcnt(0)
; #define LAS __attribute__((address_space(3)))
; __device__ __forceinline__ unsigned pk2(float lo, float hi) { f32x2 v = {lo, hi}; bf16x2_t b = __builtin_convertvector(v, bf16x2_t); return __builtin_bit_cast(unsigned, b); }
; __device__ __forceinline__ float bflo(unsigned u) { return __uint_as_float(u << 16); }
; __device__ __forceinline__ float bfhi(unsigned u) { return __uint_as_float(u & 0xffff0000u); }
; template <int tbA, int tbB> ...
;     ...
;         for (int which = 0; which < 2; ++which) {
;             const int tb = which ? tbB : tbA; const f32x16& acc = which ? accB : accA;
;             const float sbv = spb[g * 128 + tb * 32 + r];
; #pragma unroll
;             for (int q = 0; q < 4; ++q) {
;                 u32x2 w; w.x = pk2(acc[4 * q + 0] + sbv, acc[4 * q + 1] + sbv); w.y = pk2(acc[4 * q + 2] + sbv, acc[4 * q + 3] + sbv);
;                 *(LAS u32x2*)(stg + which * 2560 + r * 80 + (8 * q + 4 * hh) * 2) = w;
;             }
;         }
; #pragma unroll
;         for (int which = 0; which < 2; ++which) {
;             const int tb = which ? tbB : tbA;
; #pragma unroll
;             for (int i = 0; i < 2; ++i) {
;                 const int t = (lane >> 2) + 16 * i, ck = lane & 3;
;                 const size_t a = (size_t)(tok0 + tb * 32 + t) * DH + g * 128 + cb * 32 + ck * 8;
;                 const u32x4 uu = *(const u32x4*)(U + a), gc = *(const u32x4*)(GC + a);
;                 const u32x4 mv = *(const LAS u32x4*)(stg + which * 2560 + t * 80 + ck * 16);
;                 u32x4 o; o.x = pk2(bflo(uu.x) * bflo(mv.x) * bflo(gc.x), bfhi(uu.x) * bfhi(mv.x) * bfhi(gc.x)); o.y = pk2(bflo(uu.y) * bflo(mv.y) * bflo(gc.y), bfhi(uu.y) * bfhi(mv.y) * bfhi(gc.y));
;                 o.z = pk2(bflo(uu.z) * bflo(mv.z) * bflo(gc.z), bfhi(uu.z) * bfhi(mv.z) * bfhi(gc.z)); o.w = pk2(bflo(uu.w) * bflo(mv.w) * bflo(gc.w), bfhi(uu.w) * bfhi(mv.w) * bfhi(gc.w));
;                 *(u32x4*)(OC + a) = o;
;             }
	v_pk_add_f32 v[0:1], v[0:1], v[16:17] op_sel_hi:[1,0]
	v_pk_add_f32 v[2:3], v[2:3], v[16:17] op_sel_hi:[1,0]
	v_cvt_pk_bf16_f32 v0, v0, v1
	v_cvt_pk_bf16_f32 v1, v2, v3
	v_pk_add_f32 v[2:3], v[4:5], v[16:17] op_sel_hi:[1,0]
	v_pk_add_f32 v[4:5], v[6:7], v[16:17] op_sel_hi:[1,0]
	v_cvt_pk_bf16_f32 v2, v2, v3
	v_cvt_pk_bf16_f32 v3, v4, v5
	v_add_u32_e32 v6, 0x4800, v67
	ds_write2_b64 v6, v[0:1], v[2:3] offset0:64 offset1:66
	v_pk_add_f32 v[0:1], v[8:9], v[16:17] op_sel_hi:[1,0]
	v_pk_add_f32 v[2:3], v[10:11], v[16:17] op_sel_hi:[1,0]
	v_cvt_pk_bf16_f32 v0, v0, v1
	v_cvt_pk_bf16_f32 v1, v2, v3
	v_pk_add_f32 v[2:3], v[12:13], v[16:17] op_sel_hi:[1,0]
	v_pk_add_f32 v[4:5], v[14:15], v[16:17] op_sel_hi:[1,0]
	v_cvt_pk_bf16_f32 v2, v2, v3
	v_cvt_pk_bf16_f32 v3, v4, v5
	v_lshlrev_b64 v[12:13], 1, v[132:133]
	ds_write2_b64 v6, v[0:1], v[2:3] offset0:68 offset1:70
	v_mov_b32_e32 v0, v80
	v_mov_b32_e32 v1, v81
	v_mov_b32_e32 v2, v82
	v_mov_b32_e32 v3, v83
	v_mov_b32_e32 v4, v84
	v_mov_b32_e32 v5, v85
	v_mov_b32_e32 v6, v86
	v_mov_b32_e32 v7, v87
	ds_read_b128 v[8:11], v75 offset:16384
	v_add_u32_e32 v132, 0xfa00c000, v18
	s_waitcnt lgkmcnt(0)
	v_lshlrev_b32_e32 v16, 16, v8
	v_and_b32_e32 v17, 0xffff0000, v8
	v_lshlrev_b32_e32 v8, 16, v9
	v_and_b32_e32 v9, 0xffff0000, v9
	v_lshlrev_b32_e32 v14, 16, v0
	v_and_b32_e32 v15, 0xffff0000, v0
	v_pk_mul_f32 v[14:15], v[14:15], v[16:17]
	v_lshlrev_b32_e32 v16, 16, v4
	v_and_b32_e32 v17, 0xffff0000, v4
	v_pk_mul_f32 v[14:15], v[14:15], v[16:17]
	v_lshlrev_b32_e32 v4, 16, v5
	v_cvt_pk_bf16_f32 v0, v14, v15
	v_lshlrev_b32_e32 v14, 16, v1
	v_and_b32_e32 v15, 0xffff0000, v1
	v_pk_mul_f32 v[8:9], v[14:15], v[8:9]
	v_and_b32_e32 v5, 0xffff0000, v5
	v_pk_mul_f32 v[4:5], v[8:9], v[4:5]
	v_lshlrev_b32_e32 v8, 16, v10
	v_cvt_pk_bf16_f32 v1, v4, v5
	v_lshlrev_b32_e32 v4, 16, v2
	v_and_b32_e32 v5, 0xffff0000, v2
	v_and_b32_e32 v9, 0xffff0000, v10
	v_pk_mul_f32 v[4:5], v[4:5], v[8:9]
	v_lshlrev_b32_e32 v8, 16, v6
	v_and_b32_e32 v9, 0xffff0000, v6
	v_pk_mul_f32 v[4:5], v[4:5], v[8:9]
	v_lshlrev_b32_e32 v8, 16, v11
	v_cvt_pk_bf16_f32 v2, v4, v5
	v_lshlrev_b32_e32 v4, 16, v3
	v_and_b32_e32 v5, 0xffff0000, v3
	v_and_b32_e32 v9, 0xffff0000, v11
	v_pk_mul_f32 v[4:5], v[4:5], v[8:9]
	v_lshlrev_b32_e32 v6, 16, v7
	v_and_b32_e32 v7, 0xffff0000, v7
	v_pk_mul_f32 v[4:5], v[4:5], v[6:7]
	ds_read_b128 v[8:11], v75 offset:17664
	v_cvt_pk_bf16_f32 v3, v4, v5
	v_lshl_add_u64 v[4:5], s[36:37], 0, v[12:13]
	v_lshlrev_b64 v[12:13], 1, v[132:133]
	global_store_dwordx4 v[4:5], v[0:3], off
	v_mov_b32_e32 v4, v92
	v_mov_b32_e32 v5, v93
	v_mov_b32_e32 v6, v94
	v_mov_b32_e32 v7, v95
	v_mov_b32_e32 v0, v88
	v_mov_b32_e32 v1, v89
	v_mov_b32_e32 v2, v90
	v_mov_b32_e32 v3, v91
	s_waitcnt lgkmcnt(0)
	v_lshlrev_b32_e32 v16, 16, v8
	v_and_b32_e32 v17, 0xffff0000, v8
	v_lshlrev_b32_e32 v8, 16, v9
	v_and_b32_e32 v9, 0xffff0000, v9
	v_add_u32_e32 v132, 0xfa010000, v18
	v_lshlrev_b32_e32 v14, 16, v0
	v_and_b32_e32 v15, 0xffff0000, v0
	v_pk_mul_f32 v[14:15], v[14:15], v[16:17]
	v_lshlrev_b32_e32 v16, 16, v4
	v_and_b32_e32 v17, 0xffff0000, v4
	v_pk_mul_f32 v[14:15], v[14:15], v[16:17]
	v_lshlrev_b32_e32 v4, 16, v5
	v_cvt_pk_bf16_f32 v0, v14, v15
	v_lshlrev_b32_e32 v14, 16, v1
	v_and_b32_e32 v15, 0xffff0000, v1
	v_pk_mul_f32 v[8:9], v[14:15], v[8:9]
	v_and_b32_e32 v5, 0xffff0000, v5
	v_pk_mul_f32 v[4:5], v[8:9], v[4:5]
	v_lshlrev_b32_e32 v8, 16, v10
	v_cvt_pk_bf16_f32 v1, v4, v5
	v_lshlrev_b32_e32 v4, 16, v2
	v_and_b32_e32 v5, 0xffff0000, v2
	v_and_b32_e32 v9, 0xffff0000, v10
	v_pk_mul_f32 v[4:5], v[4:5], v[8:9]
	v_lshlrev_b32_e32 v8, 16, v6
	v_and_b32_e32 v9, 0xffff0000, v6
	v_pk_mul_f32 v[4:5], v[4:5], v[8:9]
	v_lshlrev_b32_e32 v8, 16, v11
	v_cvt_pk_bf16_f32 v2, v4, v5
	v_lshlrev_b32_e32 v4, 16, v3
	v_and_b32_e32 v5, 0xffff0000, v3
	v_and_b32_e32 v9, 0xffff0000, v11
	v_pk_mul_f32 v[4:5], v[4:5], v[8:9]
	v_lshlrev_b32_e32 v6, 16, v7
	v_and_b32_e32 v7, 0xffff0000, v7
	v_pk_mul_f32 v[4:5], v[4:5], v[6:7]
	ds_read_b128 v[8:11], v75 offset:18944
	v_cvt_pk_bf16_f32 v3, v4, v5
	v_lshl_add_u64 v[4:5], s[36:37], 0, v[12:13]
	v_lshlrev_b64 v[12:13], 1, v[132:133]
	global_store_dwordx4 v[4:5], v[0:3], off
	v_mov_b32_e32 v4, v100
	v_mov_b32_e32 v5, v101
	v_mov_b32_e32 v6, v102
	v_mov_b32_e32 v7, v103
	v_mov_b32_e32 v0, v96
	v_mov_b32_e32 v1, v97
	v_mov_b32_e32 v2, v98
	v_mov_b32_e32 v3, v99
	s_waitcnt lgkmcnt(0)
; #define LAS __attribute__((address_space(3)))
; __device__ __forceinline__ unsigned pk2(float lo, float hi) { f32x2 v = {lo, hi}; bf16x2_t b = __builtin_convertvector(v, bf16x2_t); return __builtin_bit_cast(unsigned, b); }
; __device__ __forceinline__ float bflo(unsigned u) { return __uint_as_float(u << 16); }
; __device__ __forceinline__ float bfhi(unsigned u) { return __uint_as_float(u & 0xffff0000u); }
; template <int tbA, int tbB> ...
;     ...
; #pragma unroll
;         for (int which = 0; which < 2; ++which) {
;             const int tb = which ? tbB : tbA;
; #pragma unroll
;             for (int i = 0; i < 2; ++i) {
;                 const int t = (lane >> 2) + 16 * i, ck = lane & 3;
;                 const size_t a = (size_t)(tok0 + tb * 32 + t) * DH + g * 128 + cb * 32 + ck * 8;
;                 const u32x4 uu = *(const u32x4*)(U + a), gc = *(const u32x4*)(GC + a);
;                 const u32x4 mv = *(const LAS u32x4*)(stg + which * 2560 + t * 80 + ck * 16);
;                 u32x4 o; o.x = pk2(bflo(uu.x) * bflo(mv.x) * bflo(gc.x), bfhi(uu.x) * bfhi(mv.x) * bfhi(gc.x)); o.y = pk2(bflo(uu.y) * bflo(mv.y) * bflo(gc.y), bfhi(uu.y) * bfhi(mv.y) * bfhi(gc.y));
;                 o.z = pk2(bflo(uu.z) * bflo(mv.z) * bflo(gc.z), bfhi(uu.z) * bfhi(mv.z) * bfhi(gc.z)); o.w = pk2(bflo(uu.w) * bflo(mv.w) * bflo(gc.w), bfhi(uu.w) * bfhi(mv.w) * bfhi(gc.w));
;                 *(u32x4*)(OC + a) = o;
;             }
	v_lshlrev_b32_e32 v16, 16, v8
	v_and_b32_e32 v17, 0xffff0000, v8
	v_lshlrev_b32_e32 v8, 16, v9
	v_and_b32_e32 v9, 0xffff0000, v9
	v_add_u32_e32 v132, 0xfa014000, v18
	v_lshlrev_b32_e32 v14, 16, v0
	v_and_b32_e32 v15, 0xffff0000, v0
	v_pk_mul_f32 v[14:15], v[14:15], v[16:17]
	v_lshlrev_b32_e32 v16, 16, v4
	v_and_b32_e32 v17, 0xffff0000, v4
	v_pk_mul_f32 v[14:15], v[14:15], v[16:17]
	v_lshlrev_b32_e32 v4, 16, v5
	v_cvt_pk_bf16_f32 v0, v14, v15
	v_lshlrev_b32_e32 v14, 16, v1
	v_and_b32_e32 v15, 0xffff0000, v1
	v_pk_mul_f32 v[8:9], v[14:15], v[8:9]
	v_and_b32_e32 v5, 0xffff0000, v5
	v_pk_mul_f32 v[4:5], v[8:9], v[4:5]
	v_lshlrev_b32_e32 v8, 16, v10
	v_cvt_pk_bf16_f32 v1, v4, v5
	v_lshlrev_b32_e32 v4, 16, v2
	v_and_b32_e32 v5, 0xffff0000, v2
	v_and_b32_e32 v9, 0xffff0000, v10
	v_pk_mul_f32 v[4:5], v[4:5], v[8:9]
	v_lshlrev_b32_e32 v8, 16, v6
	v_and_b32_e32 v9, 0xffff0000, v6
	v_pk_mul_f32 v[4:5], v[4:5], v[8:9]
	v_lshlrev_b32_e32 v8, 16, v11
	v_cvt_pk_bf16_f32 v2, v4, v5
	v_lshlrev_b32_e32 v4, 16, v3
	v_and_b32_e32 v5, 0xffff0000, v3
	v_and_b32_e32 v9, 0xffff0000, v11
	v_pk_mul_f32 v[4:5], v[4:5], v[8:9]
	v_lshlrev_b32_e32 v6, 16, v7
	v_and_b32_e32 v7, 0xffff0000, v7
	v_pk_mul_f32 v[4:5], v[4:5], v[6:7]
	ds_read_b128 v[8:11], v75 offset:20224
	v_cvt_pk_bf16_f32 v3, v4, v5
	v_lshl_add_u64 v[4:5], s[36:37], 0, v[12:13]
	v_lshlrev_b64 v[12:13], 1, v[132:133]
	global_store_dwordx4 v[4:5], v[0:3], off
	v_mov_b32_e32 v4, v116
	v_mov_b32_e32 v5, v117
	v_mov_b32_e32 v6, v118
	v_mov_b32_e32 v7, v119
	v_mov_b32_e32 v0, v104
	v_mov_b32_e32 v1, v105
	v_mov_b32_e32 v2, v106
	v_mov_b32_e32 v3, v107
	s_waitcnt lgkmcnt(0)
	v_lshlrev_b32_e32 v16, 16, v8
	v_and_b32_e32 v17, 0xffff0000, v8
	v_lshlrev_b32_e32 v8, 16, v9
	v_and_b32_e32 v9, 0xffff0000, v9
	v_lshlrev_b32_e32 v14, 16, v0
	v_and_b32_e32 v15, 0xffff0000, v0
	v_pk_mul_f32 v[14:15], v[14:15], v[16:17]
	v_lshlrev_b32_e32 v16, 16, v4
	v_and_b32_e32 v17, 0xffff0000, v4
	v_pk_mul_f32 v[14:15], v[14:15], v[16:17]
	v_lshlrev_b32_e32 v4, 16, v5
	v_cvt_pk_bf16_f32 v0, v14, v15
	v_lshlrev_b32_e32 v14, 16, v1
	v_and_b32_e32 v15, 0xffff0000, v1
	v_pk_mul_f32 v[8:9], v[14:15], v[8:9]
	v_and_b32_e32 v5, 0xffff0000, v5
	v_pk_mul_f32 v[4:5], v[8:9], v[4:5]
	v_lshlrev_b32_e32 v8, 16, v10
	v_cvt_pk_bf16_f32 v1, v4, v5
	v_lshlrev_b32_e32 v4, 16, v2
	v_and_b32_e32 v5, 0xffff0000, v2
	v_and_b32_e32 v9, 0xffff0000, v10
	v_pk_mul_f32 v[4:5], v[4:5], v[8:9]
	v_lshlrev_b32_e32 v8, 16, v6
	v_and_b32_e32 v9, 0xffff0000, v6
	v_pk_mul_f32 v[4:5], v[4:5], v[8:9]
	v_lshlrev_b32_e32 v8, 16, v11
	v_cvt_pk_bf16_f32 v2, v4, v5
	v_lshlrev_b32_e32 v4, 16, v3
	v_and_b32_e32 v5, 0xffff0000, v3
	v_and_b32_e32 v9, 0xffff0000, v11
	v_pk_mul_f32 v[4:5], v[4:5], v[8:9]
	v_lshlrev_b32_e32 v6, 16, v7
	v_and_b32_e32 v7, 0xffff0000, v7
	v_pk_mul_f32 v[4:5], v[4:5], v[6:7]
	s_nop 0
	v_cvt_pk_bf16_f32 v3, v4, v5
	v_lshl_add_u64 v[4:5], s[36:37], 0, v[12:13]
	global_store_dwordx4 v[4:5], v[0:3], off
	s_cbranch_scc1 .LBB0_653
	s_mov_b64 s[8:9], 0

; __device__ __forceinline__ void unpack8(const u32x4 w, float* v) { v[0] = bflo(w.x); v[1] = bfhi(w.x); v[2] = bflo(w.y); v[3] = bfhi(w.y); v[4] = bflo(w.z); v[5] = bfhi(w.z); v[6] = bflo(w.w); v[7] = bfhi(w.w); }
; template <int tbA, int tbB> ...
;     for (int gi = 0; gi < 4; ++gi) {
;         const int g = gh * 4 + gi;
;         const int ch = g * 128 + cb * 32 + r;
;         const float gg = lng[ch], bb = lnb[ch];
;         const bf16_t* ap = VCT + (size_t)ch * PT + tok0 + 8 * hh;
;         const bf16_t* wp = Wbf + (size_t)g * 16384 + 8 * hh;
;         constexpr int NSB = (tbB + 1) * 2, NSA = (tbA + 1) * 2;
;         int so = 0; asm volatile("" : "+v"(so));
;         u32x4 raw[NSB]; bf16x8 wB[NSB], wA[NSA];
; #pragma unroll
;         for (int k = 0; k < NSB; ++k) { raw[k] = *(const u32x4*)(ap + 16 * k); wB[k] = *(const bf16x8*)(wp + (size_t)(tbB * 32 + r) * 128 + 16 * k); }
; #pragma unroll
;         for (int k = 0; k < NSA; ++k) wA[k] = *(const bf16x8*)(wp + (size_t)(tbA * 32 + r) * 128 + 16 * k);
;         f32x16 accA, accB;
; #pragma unroll
;         for (int i = 0; i < 16; ++i) { accA[i] = 0.f; accB[i] = 0.f; }
; #pragma unroll
;         for (int k = 0; k < NSB; ++k) {
;             float v[8]; unpack8(raw[k], v);
; #pragma unroll
;             for (int jj = 0; jj < 8; ++jj) { const float mean = stat[(16 * k + 8 * hh + jj) * 2 + so], rstd = stat[(16 * k + 8 * hh + jj) * 2 + 1 + so]; v[jj] = (v[jj] - mean) * rstd * gg + bb; }
.LBB0_657:
	v_lshl_add_u64 v[8:9], v[68:69], 0, v[148:149]
	v_mov_b32_e32 v14, 0
	global_load_dword v74, v[72:73], off
	global_load_dword v76, v[70:71], off
	global_load_dwordx4 v[0:3], v[8:9], off offset:-128
	v_lshl_add_u64 v[10:11], v[64:65], 0, v[148:149]
	v_add_co_u32_e32 v12, vcc, s94, v10
	v_lshl_add_u32 v79, v14, 2, v158
	s_nop 0
	v_addc_co_u32_e32 v13, vcc, 0, v11, vcc
	v_add_co_u32_e32 v20, vcc, s95, v10
	global_load_dwordx4 v[4:7], v[12:13], off
	global_load_dwordx4 v[80:83], v[8:9], off offset:-96
	global_load_dwordx4 v[84:87], v[12:13], off offset:32
	global_load_dwordx4 v[88:91], v[8:9], off offset:-64
	global_load_dwordx4 v[92:95], v[12:13], off offset:64
	global_load_dwordx4 v[96:99], v[8:9], off offset:-32
	global_load_dwordx4 v[100:103], v[12:13], off offset:96
	global_load_dwordx4 v[60:63], v[8:9], off
	global_load_dwordx4 v[56:59], v[12:13], off offset:128
	global_load_dwordx4 v[52:55], v[8:9], off offset:32
	global_load_dwordx4 v[48:51], v[12:13], off offset:160
	global_load_dwordx4 v[44:47], v[8:9], off offset:64
	global_load_dwordx4 v[40:43], v[12:13], off offset:192
	global_load_dwordx4 v[36:39], v[8:9], off offset:96
	global_load_dwordx4 v[32:35], v[12:13], off offset:224
	v_addc_co_u32_e32 v21, vcc, 0, v11, vcc
	v_add_u32_e32 v12, 0x2000, v79
	global_load_dwordx4 v[104:107], v[20:21], off offset:32
	v_add_u32_e32 v112, 0x2080, v79
	v_lshl_add_u64 v[64:65], v[64:65], 0, s[58:59]
	v_lshl_add_u64 v[68:69], v[68:69], 0, s[60:61]
	v_lshl_add_u64 v[70:71], v[70:71], 0, s[62:63]
	v_lshl_add_u64 v[72:73], v[72:73], 0, s[62:63]
	s_waitcnt vmcnt(14)
	v_lshlrev_b32_e32 v108, 16, v80
	v_and_b32_e32 v109, 0xffff0000, v80
	v_add_u32_e32 v80, 0x2088, v79
	v_lshlrev_b32_e32 v8, 16, v0
	v_and_b32_e32 v9, 0xffff0000, v0
	v_add_u32_e32 v0, 0x2008, v79
	ds_read2_b32 v[10:11], v0 offset1:1
	ds_read2_b32 v[12:13], v12 offset1:1
	v_lshlrev_b32_e32 v0, 16, v1
	v_and_b32_e32 v1, 0xffff0000, v1
	s_waitcnt lgkmcnt(1)
	v_mov_b32_e32 v15, v10
	s_waitcnt lgkmcnt(0)
	v_mov_b32_e32 v14, v12
	v_pk_add_f32 v[8:9], v[8:9], v[14:15] neg_lo:[0,1] neg_hi:[0,1]
	v_mov_b32_e32 v10, v13
	v_pk_mul_f32 v[8:9], v[8:9], v[10:11]
	v_add_u32_e32 v12, 0x2010, v79
	v_add_u32_e32 v10, 0x2018, v79
	ds_read2_b32 v[10:11], v10 offset1:1
	ds_read2_b32 v[12:13], v12 offset1:1
	v_pk_fma_f32 v[8:9], v[74:75], v[8:9], v[76:77] op_sel_hi:[0,1,0]
	s_waitcnt lgkmcnt(1)
	v_mov_b32_e32 v15, v10
	s_waitcnt lgkmcnt(0)
	v_mov_b32_e32 v14, v12
	v_pk_add_f32 v[0:1], v[0:1], v[14:15] neg_lo:[0,1] neg_hi:[0,1]
	v_mov_b32_e32 v10, v13
	v_pk_mul_f32 v[0:1], v[0:1], v[10:11]
	v_add_u32_e32 v14, 0x2020, v79
	v_lshlrev_b32_e32 v10, 16, v2
	v_and_b32_e32 v11, 0xffff0000, v2
	v_add_u32_e32 v2, 0x2028, v79
	ds_read2_b32 v[12:13], v2 offset1:1
	ds_read2_b32 v[14:15], v14 offset1:1
	v_lshlrev_b32_e32 v2, 16, v3
	v_and_b32_e32 v3, 0xffff0000, v3
	v_pk_fma_f32 v[0:1], v[74:75], v[0:1], v[76:77] op_sel_hi:[0,1,0]
	s_waitcnt lgkmcnt(1)
	v_mov_b32_e32 v17, v12
	s_waitcnt lgkmcnt(0)
	v_mov_b32_e32 v16, v14
	v_pk_add_f32 v[10:11], v[10:11], v[16:17] neg_lo:[0,1] neg_hi:[0,1]
	v_mov_b32_e32 v12, v15
	v_pk_mul_f32 v[10:11], v[10:11], v[12:13]
	v_add_u32_e32 v14, 0x2030, v79
	v_add_u32_e32 v12, 0x2038, v79
	ds_read2_b32 v[12:13], v12 offset1:1
	ds_read2_b32 v[14:15], v14 offset1:1
	global_load_dwordx4 v[20:23], v[20:21], off
	ds_read2_b32 v[110:111], v80 offset1:1
	ds_read2_b32 v[112:113], v112 offset1:1
	v_lshlrev_b32_e32 v80, 16, v81
	v_and_b32_e32 v81, 0xffff0000, v81
	s_waitcnt lgkmcnt(2)
	v_mov_b32_e32 v16, v14
	s_waitcnt lgkmcnt(1)
	v_mov_b32_e32 v115, v110
	s_waitcnt lgkmcnt(0)
	v_mov_b32_e32 v114, v112
	v_pk_add_f32 v[108:109], v[108:109], v[114:115] neg_lo:[0,1] neg_hi:[0,1]
	v_mov_b32_e32 v110, v113
	v_pk_mul_f32 v[108:109], v[108:109], v[110:111]
	v_add_u32_e32 v112, 0x2090, v79
	v_add_u32_e32 v110, 0x2098, v79
	ds_read2_b32 v[110:111], v110 offset1:1
	ds_read2_b32 v[112:113], v112 offset1:1
	v_mov_b32_e32 v17, v12
	v_pk_add_f32 v[2:3], v[2:3], v[16:17] neg_lo:[0,1] neg_hi:[0,1]
	v_mov_b32_e32 v12, v15
	s_waitcnt lgkmcnt(1)
	v_mov_b32_e32 v115, v110
	s_waitcnt lgkmcnt(0)
	v_mov_b32_e32 v114, v112
	v_pk_add_f32 v[80:81], v[80:81], v[114:115] neg_lo:[0,1] neg_hi:[0,1]
	v_mov_b32_e32 v110, v113
	v_pk_mul_f32 v[80:81], v[80:81], v[110:111]
	v_add_u32_e32 v114, 0x20a0, v79
	v_pk_fma_f32 v[110:111], v[74:75], v[80:81], v[76:77] op_sel_hi:[0,1,0]
	v_lshlrev_b32_e32 v80, 16, v82
	v_and_b32_e32 v81, 0xffff0000, v82
	v_add_u32_e32 v82, 0x20a8, v79
	ds_read2_b32 v[112:113], v82 offset1:1
	ds_read2_b32 v[114:115], v114 offset1:1
	v_pk_mul_f32 v[2:3], v[2:3], v[12:13]
	v_add_u32_e32 v82, 0x20b8, v79
	v_pk_fma_f32 v[10:11], v[74:75], v[10:11], v[76:77] op_sel_hi:[0,1,0]
	s_waitcnt lgkmcnt(1)
	v_mov_b32_e32 v117, v112
	s_waitcnt lgkmcnt(0)
	v_mov_b32_e32 v116, v114
	v_pk_add_f32 v[80:81], v[80:81], v[116:117] neg_lo:[0,1] neg_hi:[0,1]
	v_mov_b32_e32 v112, v115
	v_pk_mul_f32 v[80:81], v[80:81], v[112:113]
	v_add_u32_e32 v114, 0x20b0, v79
	v_pk_fma_f32 v[2:3], v[74:75], v[2:3], v[76:77] op_sel_hi:[0,1,0]
	v_pk_fma_f32 v[112:113], v[74:75], v[80:81], v[76:77] op_sel_hi:[0,1,0]
	v_lshlrev_b32_e32 v80, 16, v83
	v_and_b32_e32 v81, 0xffff0000, v83
	ds_read2_b32 v[82:83], v82 offset1:1
	ds_read2_b32 v[114:115], v114 offset1:1
	v_cvt_pk_bf16_f32 v16, v8, v9
	v_cvt_pk_bf16_f32 v17, v0, v1
	v_cvt_pk_bf16_f32 v18, v10, v11
	v_cvt_pk_bf16_f32 v19, v2, v3
	s_waitcnt lgkmcnt(0)
; __device__ __forceinline__ unsigned pk2(float lo, float hi) { f32x2 v = {lo, hi}; bf16x2_t b = __builtin_convertvector(v, bf16x2_t); return __builtin_bit_cast(unsigned, b); }
; #define MFMA32(a, b, c) __builtin_amdgcn_mfma_f32_32x32x16_bf16((a), (b), (c), 0, 0, 0)
; __device__ __forceinline__ void unpack8(const u32x4 w, float* v) { v[0] = bflo(w.x); v[1] = bfhi(w.x); v[2] = bflo(w.y); v[3] = bfhi(w.y); v[4] = bflo(w.z); v[5] = bfhi(w.z); v[6] = bflo(w.w); v[7] = bfhi(w.w); }
; template <int tbA, int tbB> ...
;     ...
; #pragma unroll
;         for (int k = 0; k < NSB; ++k) {
;             float v[8]; unpack8(raw[k], v);
; #pragma unroll
;             for (int jj = 0; jj < 8; ++jj) { const float mean = stat[(16 * k + 8 * hh + jj) * 2 + so], rstd = stat[(16 * k + 8 * hh + jj) * 2 + 1 + so]; v[jj] = (v[jj] - mean) * rstd * gg + bb; }
;             u32x4 af; af.x = pk2(v[0], v[1]); af.y = pk2(v[2], v[3]); af.z = pk2(v[4], v[5]); af.w = pk2(v[6], v[7]);
;             accB = MFMA32(__builtin_bit_cast(bf16x8, af), wB[k], accB);
;             if (k < NSA) accA = MFMA32(__builtin_bit_cast(bf16x8, af), wA[k < NSA ? k : 0], accA);
;         }
	v_mov_b32_e32 v116, v114
	v_mov_b32_e32 v117, v82
	v_mfma_f32_32x32x16_bf16 v[0:15], v[16:19], v[4:7], 0
	v_add_f32_e64 v80, v80, -v116
	v_add_f32_e64 v81, v81, -v117
	v_mov_b32_e32 v82, v115
	v_mul_f32_e64 v80, v80, v82
	v_mul_f32_e64 v81, v81, v83
	v_pk_fma_f32 v[108:109], v[74:75], v[108:109], v[76:77] op_sel_hi:[0,1,0]
	v_pk_fma_f32 v[114:115], v[74:75], v[80:81], v[76:77] op_sel_hi:[0,1,0]
	v_cvt_pk_bf16_f32 v80, v108, v109
	v_cvt_pk_bf16_f32 v81, v110, v111
	v_cvt_pk_bf16_f32 v82, v112, v113
	v_cvt_pk_bf16_f32 v83, v114, v115
	s_waitcnt vmcnt(0)
	v_mfma_f32_32x32x16_bf16 v[16:31], v[16:19], v[20:23], 0
	v_mfma_f32_32x32x16_bf16 v[0:15], v[80:83], v[84:87], v[0:15]
	v_add_u32_e32 v84, 0x2100, v79
	v_mfma_f32_32x32x16_bf16 v[16:31], v[80:83], v[104:107], v[16:31]
	v_add_u32_e32 v82, 0x2108, v79
	ds_read2_b32 v[82:83], v82 offset1:1
	ds_read2_b32 v[84:85], v84 offset1:1
	v_lshlrev_b32_e32 v80, 16, v88
	v_and_b32_e32 v81, 0xffff0000, v88
	s_waitcnt lgkmcnt(1)
	v_mov_b32_e32 v87, v82
	s_waitcnt lgkmcnt(0)
	v_mov_b32_e32 v86, v84
	v_pk_add_f32 v[80:81], v[80:81], v[86:87] neg_lo:[0,1] neg_hi:[0,1]
	v_add_u32_e32 v86, 0x2110, v79
	v_add_u32_e32 v84, 0x2118, v79
	v_mov_b32_e32 v82, v85
	ds_read2_b32 v[84:85], v84 offset1:1
	ds_read2_b32 v[86:87], v86 offset1:1
	v_pk_mul_f32 v[80:81], v[80:81], v[82:83]
	v_lshlrev_b32_e32 v82, 16, v89
	v_and_b32_e32 v83, 0xffff0000, v89
	s_waitcnt lgkmcnt(1)
	v_mov_b32_e32 v89, v84
	s_waitcnt lgkmcnt(0)
	v_mov_b32_e32 v88, v86
	v_pk_add_f32 v[82:83], v[82:83], v[88:89] neg_lo:[0,1] neg_hi:[0,1]
	v_add_u32_e32 v88, 0x2120, v79
	v_add_u32_e32 v86, 0x2128, v79
	v_mov_b32_e32 v84, v87
	ds_read2_b32 v[86:87], v86 offset1:1
	ds_read2_b32 v[88:89], v88 offset1:1
	v_pk_mul_f32 v[82:83], v[82:83], v[84:85]
	v_lshlrev_b32_e32 v84, 16, v90
	v_and_b32_e32 v85, 0xffff0000, v90
	s_waitcnt lgkmcnt(1)
	v_mov_b32_e32 v105, v86
	s_waitcnt lgkmcnt(0)
	v_mov_b32_e32 v104, v88
	v_pk_add_f32 v[84:85], v[84:85], v[104:105] neg_lo:[0,1] neg_hi:[0,1]
	v_mov_b32_e32 v86, v89
	v_add_u32_e32 v90, 0x2130, v79
	v_add_u32_e32 v88, 0x2138, v79
	v_pk_mul_f32 v[84:85], v[84:85], v[86:87]
	v_lshlrev_b32_e32 v86, 16, v91
	v_and_b32_e32 v87, 0xffff0000, v91
	ds_read2_b32 v[88:89], v88 offset1:1
	ds_read2_b32 v[90:91], v90 offset1:1
	v_pk_fma_f32 v[80:81], v[74:75], v[80:81], v[76:77] op_sel_hi:[0,1,0]
	v_pk_fma_f32 v[82:83], v[74:75], v[82:83], v[76:77] op_sel_hi:[0,1,0]
	v_pk_fma_f32 v[84:85], v[74:75], v[84:85], v[76:77] op_sel_hi:[0,1,0]
	s_waitcnt lgkmcnt(1)
	v_mov_b32_e32 v105, v88
	s_waitcnt lgkmcnt(0)
	v_mov_b32_e32 v104, v90
	v_pk_add_f32 v[86:87], v[86:87], v[104:105] neg_lo:[0,1] neg_hi:[0,1]
	v_mov_b32_e32 v88, v91
	v_pk_mul_f32 v[86:87], v[86:87], v[88:89]
	v_cvt_pk_bf16_f32 v80, v80, v81
	v_pk_fma_f32 v[86:87], v[74:75], v[86:87], v[76:77] op_sel_hi:[0,1,0]
	v_cvt_pk_bf16_f32 v81, v82, v83
	v_cvt_pk_bf16_f32 v82, v84, v85
	v_cvt_pk_bf16_f32 v83, v86, v87
	v_add_u32_e32 v84, 0x2180, v79
	s_nop 0
	v_mfma_f32_32x32x16_bf16 v[0:15], v[80:83], v[92:95], v[0:15]
	v_add_u32_e32 v82, 0x2188, v79
	ds_read2_b32 v[82:83], v82 offset1:1
	ds_read2_b32 v[84:85], v84 offset1:1
	v_lshlrev_b32_e32 v80, 16, v96
	v_and_b32_e32 v81, 0xffff0000, v96
	s_waitcnt lgkmcnt(1)
	v_mov_b32_e32 v87, v82
	s_waitcnt lgkmcnt(0)
	v_mov_b32_e32 v86, v84
	v_pk_add_f32 v[80:81], v[80:81], v[86:87] neg_lo:[0,1] neg_hi:[0,1]
	v_add_u32_e32 v86, 0x2190, v79
	v_add_u32_e32 v84, 0x2198, v79
	v_mov_b32_e32 v82, v85
	ds_read2_b32 v[84:85], v84 offset1:1
	ds_read2_b32 v[86:87], v86 offset1:1
	v_pk_mul_f32 v[80:81], v[80:81], v[82:83]
	v_lshlrev_b32_e32 v82, 16, v97
	v_and_b32_e32 v83, 0xffff0000, v97
	s_waitcnt lgkmcnt(1)
	v_mov_b32_e32 v89, v84
	s_waitcnt lgkmcnt(0)
	v_mov_b32_e32 v88, v86
	v_pk_add_f32 v[82:83], v[82:83], v[88:89] neg_lo:[0,1] neg_hi:[0,1]
	v_add_u32_e32 v88, 0x21a0, v79
	v_add_u32_e32 v86, 0x21a8, v79
	v_mov_b32_e32 v84, v87
	ds_read2_b32 v[86:87], v86 offset1:1
	ds_read2_b32 v[88:89], v88 offset1:1
	v_pk_mul_f32 v[82:83], v[82:83], v[84:85]
	v_lshlrev_b32_e32 v84, 16, v98
	v_and_b32_e32 v85, 0xffff0000, v98
	s_waitcnt lgkmcnt(1)
	v_mov_b32_e32 v91, v86
	s_waitcnt lgkmcnt(0)
	v_mov_b32_e32 v90, v88
	v_pk_add_f32 v[84:85], v[84:85], v[90:91] neg_lo:[0,1] neg_hi:[0,1]
	v_add_u32_e32 v90, 0x21b0, v79
	v_add_u32_e32 v88, 0x21b8, v79
	v_mov_b32_e32 v86, v89
	ds_read2_b32 v[88:89], v88 offset1:1
	ds_read2_b32 v[90:91], v90 offset1:1
	v_pk_mul_f32 v[84:85], v[84:85], v[86:87]
	v_lshlrev_b32_e32 v86, 16, v99
	v_and_b32_e32 v87, 0xffff0000, v99
	s_waitcnt lgkmcnt(1)
	v_mov_b32_e32 v93, v88
	s_waitcnt lgkmcnt(0)
	v_mov_b32_e32 v92, v90
	v_pk_add_f32 v[86:87], v[86:87], v[92:93] neg_lo:[0,1] neg_hi:[0,1]
	v_mov_b32_e32 v88, v91
	v_pk_mul_f32 v[86:87], v[86:87], v[88:89]
	v_pk_fma_f32 v[80:81], v[74:75], v[80:81], v[76:77] op_sel_hi:[0,1,0]
	v_pk_fma_f32 v[82:83], v[74:75], v[82:83], v[76:77] op_sel_hi:[0,1,0]
	v_pk_fma_f32 v[84:85], v[74:75], v[84:85], v[76:77] op_sel_hi:[0,1,0]
	v_pk_fma_f32 v[86:87], v[74:75], v[86:87], v[76:77] op_sel_hi:[0,1,0]
	v_cvt_pk_bf16_f32 v80, v80, v81
	v_cvt_pk_bf16_f32 v81, v82, v83
	v_cvt_pk_bf16_f32 v82, v84, v85
	v_cvt_pk_bf16_f32 v83, v86, v87
	v_add_u32_e32 v84, 0x2200, v79
	s_nop 0
	v_mfma_f32_32x32x16_bf16 v[0:15], v[80:83], v[100:103], v[0:15]
	v_lshlrev_b32_e32 v80, 16, v60
	v_and_b32_e32 v81, 0xffff0000, v60
	v_add_u32_e32 v60, 0x2208, v79
	ds_read2_b32 v[82:83], v60 offset1:1
	ds_read2_b32 v[84:85], v84 offset1:1
	v_lshlrev_b32_e32 v60, 16, v61
	v_and_b32_e32 v61, 0xffff0000, v61
	s_waitcnt lgkmcnt(1)
	v_mov_b32_e32 v87, v82
	s_waitcnt lgkmcnt(0)
; __device__ __forceinline__ unsigned pk2(float lo, float hi) { f32x2 v = {lo, hi}; bf16x2_t b = __builtin_convertvector(v, bf16x2_t); return __builtin_bit_cast(unsigned, b); }
; #define MFMA32(a, b, c) __builtin_amdgcn_mfma_f32_32x32x16_bf16((a), (b), (c), 0, 0, 0)
; __device__ __forceinline__ void unpack8(const u32x4 w, float* v) { v[0] = bflo(w.x); v[1] = bfhi(w.x); v[2] = bflo(w.y); v[3] = bfhi(w.y); v[4] = bflo(w.z); v[5] = bfhi(w.z); v[6] = bflo(w.w); v[7] = bfhi(w.w); }
; template <int tbA, int tbB> ...
;     ...
; #pragma unroll
;         for (int k = 0; k < NSB; ++k) {
;             float v[8]; unpack8(raw[k], v);
; #pragma unroll
;             for (int jj = 0; jj < 8; ++jj) { const float mean = stat[(16 * k + 8 * hh + jj) * 2 + so], rstd = stat[(16 * k + 8 * hh + jj) * 2 + 1 + so]; v[jj] = (v[jj] - mean) * rstd * gg + bb; }
;             u32x4 af; af.x = pk2(v[0], v[1]); af.y = pk2(v[2], v[3]); af.z = pk2(v[4], v[5]); af.w = pk2(v[6], v[7]);
;             accB = MFMA32(__builtin_bit_cast(bf16x8, af), wB[k], accB);
;             if (k < NSA) accA = MFMA32(__builtin_bit_cast(bf16x8, af), wA[k < NSA ? k : 0], accA);
;         }
	v_mov_b32_e32 v86, v84
	v_pk_add_f32 v[80:81], v[80:81], v[86:87] neg_lo:[0,1] neg_hi:[0,1]
	v_mov_b32_e32 v82, v85
	v_pk_mul_f32 v[80:81], v[80:81], v[82:83]
	v_add_u32_e32 v84, 0x2210, v79
	v_add_u32_e32 v82, 0x2218, v79
	ds_read2_b32 v[82:83], v82 offset1:1
	ds_read2_b32 v[84:85], v84 offset1:1
	v_pk_fma_f32 v[80:81], v[74:75], v[80:81], v[76:77] op_sel_hi:[0,1,0]
	s_waitcnt lgkmcnt(1)
	v_mov_b32_e32 v87, v82
	s_waitcnt lgkmcnt(0)
	v_mov_b32_e32 v86, v84
	v_pk_add_f32 v[60:61], v[60:61], v[86:87] neg_lo:[0,1] neg_hi:[0,1]
	v_mov_b32_e32 v82, v85
	v_pk_mul_f32 v[60:61], v[60:61], v[82:83]
	v_add_u32_e32 v86, 0x2220, v79
	v_pk_fma_f32 v[82:83], v[74:75], v[60:61], v[76:77] op_sel_hi:[0,1,0]
	v_lshlrev_b32_e32 v60, 16, v62
	v_and_b32_e32 v61, 0xffff0000, v62
	v_add_u32_e32 v62, 0x2228, v79
	ds_read2_b32 v[84:85], v62 offset1:1
	ds_read2_b32 v[86:87], v86 offset1:1
	v_add_u32_e32 v62, 0x2238, v79
	s_waitcnt lgkmcnt(1)
	v_mov_b32_e32 v89, v84
	s_waitcnt lgkmcnt(0)
	v_mov_b32_e32 v88, v86
	v_pk_add_f32 v[60:61], v[60:61], v[88:89] neg_lo:[0,1] neg_hi:[0,1]
	v_mov_b32_e32 v84, v87
	v_pk_mul_f32 v[60:61], v[60:61], v[84:85]
	v_add_u32_e32 v86, 0x2230, v79
	v_pk_fma_f32 v[84:85], v[74:75], v[60:61], v[76:77] op_sel_hi:[0,1,0]
	v_lshlrev_b32_e32 v60, 16, v63
	v_and_b32_e32 v61, 0xffff0000, v63
	ds_read2_b32 v[62:63], v62 offset1:1
	ds_read2_b32 v[86:87], v86 offset1:1
	s_waitcnt lgkmcnt(1)
	v_mov_b32_e32 v89, v62
	s_waitcnt lgkmcnt(0)
	v_mov_b32_e32 v88, v86
	v_pk_add_f32 v[60:61], v[60:61], v[88:89] neg_lo:[0,1] neg_hi:[0,1]
	v_mov_b32_e32 v62, v87
	v_pk_mul_f32 v[60:61], v[60:61], v[62:63]
	v_cvt_pk_bf16_f32 v62, v84, v85
	v_pk_fma_f32 v[86:87], v[74:75], v[60:61], v[76:77] op_sel_hi:[0,1,0]
	v_cvt_pk_bf16_f32 v60, v80, v81
	v_cvt_pk_bf16_f32 v61, v82, v83
	v_cvt_pk_bf16_f32 v63, v86, v87
	s_nop 1
	v_mfma_f32_32x32x16_bf16 v[0:15], v[60:63], v[56:59], v[0:15]
	v_add_u32_e32 v60, 0x2280, v79
	v_lshlrev_b32_e32 v56, 16, v52
	v_and_b32_e32 v57, 0xffff0000, v52
	v_add_u32_e32 v52, 0x2288, v79
	ds_read2_b32 v[58:59], v52 offset1:1
	ds_read2_b32 v[60:61], v60 offset1:1
	v_lshlrev_b32_e32 v52, 16, v53
	v_and_b32_e32 v53, 0xffff0000, v53
	s_waitcnt lgkmcnt(1)
	v_mov_b32_e32 v63, v58
	s_waitcnt lgkmcnt(0)
	v_mov_b32_e32 v62, v60
	v_pk_add_f32 v[56:57], v[56:57], v[62:63] neg_lo:[0,1] neg_hi:[0,1]
	v_mov_b32_e32 v58, v61
	v_pk_mul_f32 v[56:57], v[56:57], v[58:59]
	v_add_u32_e32 v60, 0x2290, v79
	v_add_u32_e32 v58, 0x2298, v79
	ds_read2_b32 v[58:59], v58 offset1:1
	ds_read2_b32 v[60:61], v60 offset1:1
	v_pk_fma_f32 v[56:57], v[74:75], v[56:57], v[76:77] op_sel_hi:[0,1,0]
	s_waitcnt lgkmcnt(1)
	v_mov_b32_e32 v63, v58
	s_waitcnt lgkmcnt(0)
	v_mov_b32_e32 v62, v60
	v_pk_add_f32 v[52:53], v[52:53], v[62:63] neg_lo:[0,1] neg_hi:[0,1]
	v_mov_b32_e32 v58, v61
	v_pk_mul_f32 v[52:53], v[52:53], v[58:59]
	v_add_u32_e32 v62, 0x22a0, v79
	v_pk_fma_f32 v[58:59], v[74:75], v[52:53], v[76:77] op_sel_hi:[0,1,0]
	v_lshlrev_b32_e32 v52, 16, v54
	v_and_b32_e32 v53, 0xffff0000, v54
	v_add_u32_e32 v54, 0x22a8, v79
	ds_read2_b32 v[60:61], v54 offset1:1
	ds_read2_b32 v[62:63], v62 offset1:1
	v_add_u32_e32 v54, 0x22b8, v79
	s_waitcnt lgkmcnt(1)
	v_mov_b32_e32 v81, v60
	s_waitcnt lgkmcnt(0)
	v_mov_b32_e32 v80, v62
	v_pk_add_f32 v[52:53], v[52:53], v[80:81] neg_lo:[0,1] neg_hi:[0,1]
	v_mov_b32_e32 v60, v63
	v_pk_mul_f32 v[52:53], v[52:53], v[60:61]
	v_add_u32_e32 v62, 0x22b0, v79
	v_pk_fma_f32 v[60:61], v[74:75], v[52:53], v[76:77] op_sel_hi:[0,1,0]
	v_lshlrev_b32_e32 v52, 16, v55
	v_and_b32_e32 v53, 0xffff0000, v55
	ds_read2_b32 v[54:55], v54 offset1:1
	ds_read2_b32 v[62:63], v62 offset1:1
	s_waitcnt lgkmcnt(1)
	v_mov_b32_e32 v81, v54
	s_waitcnt lgkmcnt(0)
	v_mov_b32_e32 v80, v62
	v_pk_add_f32 v[52:53], v[52:53], v[80:81] neg_lo:[0,1] neg_hi:[0,1]
	v_mov_b32_e32 v54, v63
	v_pk_mul_f32 v[52:53], v[52:53], v[54:55]
	v_cvt_pk_bf16_f32 v54, v60, v61
	v_pk_fma_f32 v[62:63], v[74:75], v[52:53], v[76:77] op_sel_hi:[0,1,0]
	v_cvt_pk_bf16_f32 v52, v56, v57
	v_cvt_pk_bf16_f32 v53, v58, v59
	v_cvt_pk_bf16_f32 v55, v62, v63
	s_nop 1
	v_mfma_f32_32x32x16_bf16 v[0:15], v[52:55], v[48:51], v[0:15]
	v_add_u32_e32 v52, 0x2300, v79
	v_lshlrev_b32_e32 v48, 16, v44
	v_and_b32_e32 v49, 0xffff0000, v44
	v_add_u32_e32 v44, 0x2308, v79
	ds_read2_b32 v[50:51], v44 offset1:1
	ds_read2_b32 v[52:53], v52 offset1:1
	v_lshlrev_b32_e32 v44, 16, v45
	v_and_b32_e32 v45, 0xffff0000, v45
	s_waitcnt lgkmcnt(1)
	v_mov_b32_e32 v55, v50
	s_waitcnt lgkmcnt(0)
	v_mov_b32_e32 v54, v52
	v_pk_add_f32 v[48:49], v[48:49], v[54:55] neg_lo:[0,1] neg_hi:[0,1]
	v_mov_b32_e32 v50, v53
	v_pk_mul_f32 v[48:49], v[48:49], v[50:51]
	v_add_u32_e32 v52, 0x2310, v79
	v_add_u32_e32 v50, 0x2318, v79
	ds_read2_b32 v[50:51], v50 offset1:1
	ds_read2_b32 v[52:53], v52 offset1:1
	v_pk_fma_f32 v[48:49], v[74:75], v[48:49], v[76:77] op_sel_hi:[0,1,0]
	s_waitcnt lgkmcnt(1)
	v_mov_b32_e32 v55, v50
	s_waitcnt lgkmcnt(0)
	v_mov_b32_e32 v54, v52
	v_pk_add_f32 v[44:45], v[44:45], v[54:55] neg_lo:[0,1] neg_hi:[0,1]
	v_mov_b32_e32 v50, v53
	v_pk_mul_f32 v[44:45], v[44:45], v[50:51]
	v_add_u32_e32 v54, 0x2320, v79
	v_pk_fma_f32 v[50:51], v[74:75], v[44:45], v[76:77] op_sel_hi:[0,1,0]
	v_lshlrev_b32_e32 v44, 16, v46
	v_and_b32_e32 v45, 0xffff0000, v46
	v_add_u32_e32 v46, 0x2328, v79
	ds_read2_b32 v[52:53], v46 offset1:1
	ds_read2_b32 v[54:55], v54 offset1:1
	v_add_u32_e32 v46, 0x2338, v79
	s_waitcnt lgkmcnt(1)
	v_mov_b32_e32 v57, v52
	s_waitcnt lgkmcnt(0)
; #define LAS __attribute__((address_space(3)))
; __device__ __forceinline__ unsigned pk2(float lo, float hi) { f32x2 v = {lo, hi}; bf16x2_t b = __builtin_convertvector(v, bf16x2_t); return __builtin_bit_cast(unsigned, b); }
; #define MFMA32(a, b, c) __builtin_amdgcn_mfma_f32_32x32x16_bf16((a), (b), (c), 0, 0, 0)
; __device__ __forceinline__ void unpack8(const u32x4 w, float* v) { v[0] = bflo(w.x); v[1] = bfhi(w.x); v[2] = bflo(w.y); v[3] = bfhi(w.y); v[4] = bflo(w.z); v[5] = bfhi(w.z); v[6] = bflo(w.w); v[7] = bfhi(w.w); }
; template <int tbA, int tbB> ...
;     ...
; #pragma unroll
;         for (int k = 0; k < NSB; ++k) {
;             float v[8]; unpack8(raw[k], v);
; #pragma unroll
;             for (int jj = 0; jj < 8; ++jj) { const float mean = stat[(16 * k + 8 * hh + jj) * 2 + so], rstd = stat[(16 * k + 8 * hh + jj) * 2 + 1 + so]; v[jj] = (v[jj] - mean) * rstd * gg + bb; }
;             u32x4 af; af.x = pk2(v[0], v[1]); af.y = pk2(v[2], v[3]); af.z = pk2(v[4], v[5]); af.w = pk2(v[6], v[7]);
;             accB = MFMA32(__builtin_bit_cast(bf16x8, af), wB[k], accB);
;             if (k < NSA) accA = MFMA32(__builtin_bit_cast(bf16x8, af), wA[k < NSA ? k : 0], accA);
;         }
; #pragma unroll
;         for (int which = 0; which < 2; ++which) {
;             const int tb = which ? tbB : tbA; const f32x16& acc = which ? accB : accA;
;             const float sbv = spb[g * 128 + tb * 32 + r];
; #pragma unroll
;             for (int q = 0; q < 4; ++q) {
;                 u32x2 w; w.x = pk2(acc[4 * q + 0] + sbv, acc[4 * q + 1] + sbv); w.y = pk2(acc[4 * q + 2] + sbv, acc[4 * q + 3] + sbv);
;                 *(LAS u32x2*)(stg + which * 2560 + r * 80 + (8 * q + 4 * hh) * 2) = w;
;             }
;         }
; #pragma unroll
;         for (int which = 0; which < 2; ++which) {
;             const int tb = which ? tbB : tbA;
; #pragma unroll
;             for (int i = 0; i < 2; ++i) {
;                 const int t = (lane >> 2) + 16 * i, ck = lane & 3;
;                 const size_t a = (size_t)(tok0 + tb * 32 + t) * DH + g * 128 + cb * 32 + ck * 8;
;                 const u32x4 uu = *(const u32x4*)(U + a), gc = *(const u32x4*)(GC + a);
	v_mov_b32_e32 v56, v54
	v_pk_add_f32 v[44:45], v[44:45], v[56:57] neg_lo:[0,1] neg_hi:[0,1]
	v_mov_b32_e32 v52, v55
	v_pk_mul_f32 v[44:45], v[44:45], v[52:53]
	v_add_u32_e32 v54, 0x2330, v79
	v_pk_fma_f32 v[52:53], v[74:75], v[44:45], v[76:77] op_sel_hi:[0,1,0]
	v_lshlrev_b32_e32 v44, 16, v47
	v_and_b32_e32 v45, 0xffff0000, v47
	ds_read2_b32 v[46:47], v46 offset1:1
	ds_read2_b32 v[54:55], v54 offset1:1
	s_waitcnt lgkmcnt(1)
	v_mov_b32_e32 v57, v46
	s_waitcnt lgkmcnt(0)
	v_mov_b32_e32 v56, v54
	v_pk_add_f32 v[44:45], v[44:45], v[56:57] neg_lo:[0,1] neg_hi:[0,1]
	v_mov_b32_e32 v46, v55
	v_pk_mul_f32 v[44:45], v[44:45], v[46:47]
	v_cvt_pk_bf16_f32 v46, v52, v53
	v_pk_fma_f32 v[54:55], v[74:75], v[44:45], v[76:77] op_sel_hi:[0,1,0]
	v_cvt_pk_bf16_f32 v44, v48, v49
	v_cvt_pk_bf16_f32 v45, v50, v51
	v_cvt_pk_bf16_f32 v47, v54, v55
	s_nop 1
	v_mfma_f32_32x32x16_bf16 v[0:15], v[44:47], v[40:43], v[0:15]
	v_add_u32_e32 v44, 0x2380, v79
	v_lshlrev_b32_e32 v40, 16, v36
	v_and_b32_e32 v41, 0xffff0000, v36
	v_add_u32_e32 v36, 0x2388, v79
	ds_read2_b32 v[42:43], v36 offset1:1
	ds_read2_b32 v[44:45], v44 offset1:1
	v_lshlrev_b32_e32 v36, 16, v37
	v_and_b32_e32 v37, 0xffff0000, v37
	s_waitcnt lgkmcnt(1)
	v_mov_b32_e32 v47, v42
	s_waitcnt lgkmcnt(0)
	v_mov_b32_e32 v46, v44
	v_pk_add_f32 v[40:41], v[40:41], v[46:47] neg_lo:[0,1] neg_hi:[0,1]
	v_mov_b32_e32 v42, v45
	v_pk_mul_f32 v[40:41], v[40:41], v[42:43]
	v_add_u32_e32 v44, 0x2390, v79
	v_add_u32_e32 v42, 0x2398, v79
	ds_read2_b32 v[42:43], v42 offset1:1
	ds_read2_b32 v[44:45], v44 offset1:1
	v_pk_fma_f32 v[40:41], v[74:75], v[40:41], v[76:77] op_sel_hi:[0,1,0]
	s_waitcnt lgkmcnt(1)
	v_mov_b32_e32 v47, v42
	s_waitcnt lgkmcnt(0)
	v_mov_b32_e32 v46, v44
	v_pk_add_f32 v[36:37], v[36:37], v[46:47] neg_lo:[0,1] neg_hi:[0,1]
	v_mov_b32_e32 v42, v45
	v_pk_mul_f32 v[36:37], v[36:37], v[42:43]
	v_add_u32_e32 v46, 0x23a0, v79
	v_pk_fma_f32 v[42:43], v[74:75], v[36:37], v[76:77] op_sel_hi:[0,1,0]
	v_lshlrev_b32_e32 v36, 16, v38
	v_and_b32_e32 v37, 0xffff0000, v38
	v_add_u32_e32 v38, 0x23a8, v79
	ds_read2_b32 v[44:45], v38 offset1:1
	ds_read2_b32 v[46:47], v46 offset1:1
	v_add_u32_e32 v38, 0x23b8, v79
	s_waitcnt lgkmcnt(1)
	v_mov_b32_e32 v49, v44
	s_waitcnt lgkmcnt(0)
	v_mov_b32_e32 v48, v46
	v_pk_add_f32 v[36:37], v[36:37], v[48:49] neg_lo:[0,1] neg_hi:[0,1]
	v_mov_b32_e32 v44, v47
	v_pk_mul_f32 v[36:37], v[36:37], v[44:45]
	v_add_u32_e32 v46, 0x23b0, v79
	v_pk_fma_f32 v[44:45], v[74:75], v[36:37], v[76:77] op_sel_hi:[0,1,0]
	v_lshlrev_b32_e32 v36, 16, v39
	v_and_b32_e32 v37, 0xffff0000, v39
	ds_read2_b32 v[38:39], v38 offset1:1
	ds_read2_b32 v[46:47], v46 offset1:1
	s_waitcnt lgkmcnt(1)
	v_mov_b32_e32 v49, v38
	s_waitcnt lgkmcnt(0)
	v_mov_b32_e32 v48, v46
	v_pk_add_f32 v[36:37], v[36:37], v[48:49] neg_lo:[0,1] neg_hi:[0,1]
	v_mov_b32_e32 v38, v47
	v_pk_mul_f32 v[36:37], v[36:37], v[38:39]
	v_cvt_pk_bf16_f32 v38, v44, v45
	v_pk_fma_f32 v[46:47], v[74:75], v[36:37], v[76:77] op_sel_hi:[0,1,0]
	v_cvt_pk_bf16_f32 v36, v40, v41
	v_cvt_pk_bf16_f32 v37, v42, v43
	v_cvt_pk_bf16_f32 v39, v46, v47
	s_nop 1
	v_mfma_f32_32x32x16_bf16 v[0:15], v[36:39], v[32:35], v[0:15]
	v_add_u32_e32 v120, s8, v77
	v_add_u32_e32 v122, 0xfa000000, v120
	v_mov_b32_e32 v123, 0
	v_lshlrev_b64 v[122:123], 1, v[122:123]
	v_lshl_add_u64 v[124:125], s[30:31], 0, v[122:123]
	global_load_dwordx4 v[80:83], v[124:125], off
	v_lshl_add_u64 v[124:125], s[34:35], 0, v[122:123]
	global_load_dwordx4 v[84:87], v[124:125], off
	v_add_u32_e32 v122, 0xfa004000, v120
	v_mov_b32_e32 v123, 0
	v_lshlrev_b64 v[122:123], 1, v[122:123]
	v_lshl_add_u64 v[124:125], s[30:31], 0, v[122:123]
	global_load_dwordx4 v[88:91], v[124:125], off
	v_lshl_add_u64 v[124:125], s[34:35], 0, v[122:123]
	global_load_dwordx4 v[92:95], v[124:125], off
	v_add_u32_e32 v122, 0xfa018000, v120
	v_mov_b32_e32 v123, 0
	v_lshlrev_b64 v[122:123], 1, v[122:123]
	v_lshl_add_u64 v[124:125], s[30:31], 0, v[122:123]
	global_load_dwordx4 v[96:99], v[124:125], off
	v_lshl_add_u64 v[124:125], s[34:35], 0, v[122:123]
	global_load_dwordx4 v[100:103], v[124:125], off
	v_add_u32_e32 v122, 0xfa01c000, v120
	v_mov_b32_e32 v123, 0
	v_lshlrev_b64 v[122:123], 1, v[122:123]
	v_lshl_add_u64 v[124:125], s[30:31], 0, v[122:123]
	global_load_dwordx4 v[104:107], v[124:125], off
	v_lshl_add_u64 v[124:125], s[34:35], 0, v[122:123]
	global_load_dwordx4 v[116:119], v[124:125], off
	global_load_dword v32, v[66:67], off offset:-384
	s_waitcnt vmcnt(0)
	v_add_f32_e64 v16, v16, v32
	v_add_f32_e64 v17, v17, v32
	v_add_f32_e64 v18, v18, v32
	v_add_f32_e64 v19, v19, v32
	v_cvt_pk_bf16_f32 v16, v16, v17
	v_cvt_pk_bf16_f32 v17, v18, v19
	v_pk_add_f32 v[18:19], v[20:21], v[32:33] op_sel_hi:[1,0]
	v_pk_add_f32 v[20:21], v[22:23], v[32:33] op_sel_hi:[1,0]
	v_cvt_pk_bf16_f32 v18, v18, v19
	v_cvt_pk_bf16_f32 v19, v20, v21
	v_add_u32_e32 v22, 0x4000, v78
	ds_write2_b64 v22, v[16:17], v[18:19] offset1:2
	v_pk_add_f32 v[16:17], v[24:25], v[32:33] op_sel_hi:[1,0]
	v_pk_add_f32 v[18:19], v[26:27], v[32:33] op_sel_hi:[1,0]
	v_cvt_pk_bf16_f32 v16, v16, v17
	v_cvt_pk_bf16_f32 v17, v18, v19
	v_pk_add_f32 v[18:19], v[28:29], v[32:33] op_sel_hi:[1,0]
	v_pk_add_f32 v[20:21], v[30:31], v[32:33] op_sel_hi:[1,0]
	v_cvt_pk_bf16_f32 v18, v18, v19
	v_cvt_pk_bf16_f32 v19, v20, v21
	ds_write2_b64 v22, v[16:17], v[18:19] offset0:4 offset1:6
	global_load_dword v16, v[66:67], off
	v_add_u32_e32 v18, s8, v77
	v_add_u32_e32 v132, 0xfa000000, v18
	s_addk_i32 s8, 0x80
	v_lshl_add_u64 v[66:67], v[66:67], 0, s[62:63]
	s_cmpk_eq_i32 s8, 0x200
	s_waitcnt vmcnt(0)
; #define LAS __attribute__((address_space(3)))
; __device__ __forceinline__ unsigned pk2(float lo, float hi) { f32x2 v = {lo, hi}; bf16x2_t b = __builtin_convertvector(v, bf16x2_t); return __builtin_bit_cast(unsigned, b); }
; __device__ __forceinline__ float bflo(unsigned u) { return __uint_as_float(u << 16); }
; __device__ __forceinline__ float bfhi(unsigned u) { return __uint_as_float(u & 0xffff0000u); }
; template <int tbA, int tbB> ...
;     ...
;         for (int which = 0; which < 2; ++which) {
;             const int tb = which ? tbB : tbA; const f32x16& acc = which ? accB : accA;
;             const float sbv = spb[g * 128 + tb * 32 + r];
; #pragma unroll
;             for (int q = 0; q < 4; ++q) {
;                 u32x2 w; w.x = pk2(acc[4 * q + 0] + sbv, acc[4 * q + 1] + sbv); w.y = pk2(acc[4 * q + 2] + sbv, acc[4 * q + 3] + sbv);
;                 *(LAS u32x2*)(stg + which * 2560 + r * 80 + (8 * q + 4 * hh) * 2) = w;
;             }
;         }
; #pragma unroll
;         for (int which = 0; which < 2; ++which) {
;             const int tb = which ? tbB : tbA;
; #pragma unroll
;             for (int i = 0; i < 2; ++i) {
;                 const int t = (lane >> 2) + 16 * i, ck = lane & 3;
;                 const size_t a = (size_t)(tok0 + tb * 32 + t) * DH + g * 128 + cb * 32 + ck * 8;
;                 const u32x4 uu = *(const u32x4*)(U + a), gc = *(const u32x4*)(GC + a);
;                 const u32x4 mv = *(const LAS u32x4*)(stg + which * 2560 + t * 80 + ck * 16);
;                 u32x4 o; o.x = pk2(bflo(uu.x) * bflo(mv.x) * bflo(gc.x), bfhi(uu.x) * bfhi(mv.x) * bfhi(gc.x)); o.y = pk2(bflo(uu.y) * bflo(mv.y) * bflo(gc.y), bfhi(uu.y) * bfhi(mv.y) * bfhi(gc.y));
;                 o.z = pk2(bflo(uu.z) * bflo(mv.z) * bflo(gc.z), bfhi(uu.z) * bfhi(mv.z) * bfhi(gc.z)); o.w = pk2(bflo(uu.w) * bflo(mv.w) * bflo(gc.w), bfhi(uu.w) * bfhi(mv.w) * bfhi(gc.w));
;                 *(u32x4*)(OC + a) = o;
;             }
	v_pk_add_f32 v[0:1], v[0:1], v[16:17] op_sel_hi:[1,0]
	v_pk_add_f32 v[2:3], v[2:3], v[16:17] op_sel_hi:[1,0]
	v_cvt_pk_bf16_f32 v0, v0, v1
	v_cvt_pk_bf16_f32 v1, v2, v3
	v_pk_add_f32 v[2:3], v[4:5], v[16:17] op_sel_hi:[1,0]
	v_pk_add_f32 v[4:5], v[6:7], v[16:17] op_sel_hi:[1,0]
	v_cvt_pk_bf16_f32 v2, v2, v3
	v_cvt_pk_bf16_f32 v3, v4, v5
	v_add_u32_e32 v6, 0x4800, v78
	ds_write2_b64 v6, v[0:1], v[2:3] offset0:64 offset1:66
	v_pk_add_f32 v[0:1], v[8:9], v[16:17] op_sel_hi:[1,0]
	v_pk_add_f32 v[2:3], v[10:11], v[16:17] op_sel_hi:[1,0]
	v_cvt_pk_bf16_f32 v0, v0, v1
	v_cvt_pk_bf16_f32 v1, v2, v3
	v_pk_add_f32 v[2:3], v[12:13], v[16:17] op_sel_hi:[1,0]
	v_pk_add_f32 v[4:5], v[14:15], v[16:17] op_sel_hi:[1,0]
	v_cvt_pk_bf16_f32 v2, v2, v3
	v_cvt_pk_bf16_f32 v3, v4, v5
	v_lshlrev_b64 v[12:13], 1, v[132:133]
	ds_write2_b64 v6, v[0:1], v[2:3] offset0:68 offset1:70
	v_mov_b32_e32 v0, v80
	v_mov_b32_e32 v1, v81
	v_mov_b32_e32 v2, v82
	v_mov_b32_e32 v3, v83
	v_mov_b32_e32 v4, v84
	v_mov_b32_e32 v5, v85
	v_mov_b32_e32 v6, v86
	v_mov_b32_e32 v7, v87
	ds_read_b128 v[8:11], v75 offset:16384
	v_add_u32_e32 v132, 0xfa004000, v18
	s_waitcnt lgkmcnt(0)
	v_lshlrev_b32_e32 v16, 16, v8
	v_and_b32_e32 v17, 0xffff0000, v8
	v_lshlrev_b32_e32 v8, 16, v9
	v_and_b32_e32 v9, 0xffff0000, v9
	v_lshlrev_b32_e32 v14, 16, v0
	v_and_b32_e32 v15, 0xffff0000, v0
	v_pk_mul_f32 v[14:15], v[14:15], v[16:17]
	v_lshlrev_b32_e32 v16, 16, v4
	v_and_b32_e32 v17, 0xffff0000, v4
	v_pk_mul_f32 v[14:15], v[14:15], v[16:17]
	v_lshlrev_b32_e32 v4, 16, v5
	v_cvt_pk_bf16_f32 v0, v14, v15
	v_lshlrev_b32_e32 v14, 16, v1
	v_and_b32_e32 v15, 0xffff0000, v1
	v_pk_mul_f32 v[8:9], v[14:15], v[8:9]
	v_and_b32_e32 v5, 0xffff0000, v5
	v_pk_mul_f32 v[4:5], v[8:9], v[4:5]
	v_lshlrev_b32_e32 v8, 16, v10
	v_cvt_pk_bf16_f32 v1, v4, v5
	v_lshlrev_b32_e32 v4, 16, v2
	v_and_b32_e32 v5, 0xffff0000, v2
	v_and_b32_e32 v9, 0xffff0000, v10
	v_pk_mul_f32 v[4:5], v[4:5], v[8:9]
	v_lshlrev_b32_e32 v8, 16, v6
	v_and_b32_e32 v9, 0xffff0000, v6
	v_pk_mul_f32 v[4:5], v[4:5], v[8:9]
	v_lshlrev_b32_e32 v8, 16, v11
	v_cvt_pk_bf16_f32 v2, v4, v5
	v_lshlrev_b32_e32 v4, 16, v3
	v_and_b32_e32 v5, 0xffff0000, v3
	v_and_b32_e32 v9, 0xffff0000, v11
	v_pk_mul_f32 v[4:5], v[4:5], v[8:9]
	v_lshlrev_b32_e32 v6, 16, v7
	v_and_b32_e32 v7, 0xffff0000, v7
	v_pk_mul_f32 v[4:5], v[4:5], v[6:7]
	ds_read_b128 v[8:11], v75 offset:17664
	v_cvt_pk_bf16_f32 v3, v4, v5
	v_lshl_add_u64 v[4:5], s[36:37], 0, v[12:13]
	v_lshlrev_b64 v[12:13], 1, v[132:133]
	global_store_dwordx4 v[4:5], v[0:3], off
	v_mov_b32_e32 v4, v92
	v_mov_b32_e32 v5, v93
	v_mov_b32_e32 v6, v94
	v_mov_b32_e32 v7, v95
	v_mov_b32_e32 v0, v88
	v_mov_b32_e32 v1, v89
	v_mov_b32_e32 v2, v90
	v_mov_b32_e32 v3, v91
	s_waitcnt lgkmcnt(0)
	v_lshlrev_b32_e32 v16, 16, v8
	v_and_b32_e32 v17, 0xffff0000, v8
	v_lshlrev_b32_e32 v8, 16, v9
	v_and_b32_e32 v9, 0xffff0000, v9
	v_add_u32_e32 v132, 0xfa018000, v18
	v_lshlrev_b32_e32 v14, 16, v0
	v_and_b32_e32 v15, 0xffff0000, v0
	v_pk_mul_f32 v[14:15], v[14:15], v[16:17]
	v_lshlrev_b32_e32 v16, 16, v4
	v_and_b32_e32 v17, 0xffff0000, v4
	v_pk_mul_f32 v[14:15], v[14:15], v[16:17]
	v_lshlrev_b32_e32 v4, 16, v5
	v_cvt_pk_bf16_f32 v0, v14, v15
	v_lshlrev_b32_e32 v14, 16, v1
	v_and_b32_e32 v15, 0xffff0000, v1
	v_pk_mul_f32 v[8:9], v[14:15], v[8:9]
	v_and_b32_e32 v5, 0xffff0000, v5
	v_pk_mul_f32 v[4:5], v[8:9], v[4:5]
	v_lshlrev_b32_e32 v8, 16, v10
	v_cvt_pk_bf16_f32 v1, v4, v5
	v_lshlrev_b32_e32 v4, 16, v2
	v_and_b32_e32 v5, 0xffff0000, v2
	v_and_b32_e32 v9, 0xffff0000, v10
	v_pk_mul_f32 v[4:5], v[4:5], v[8:9]
	v_lshlrev_b32_e32 v8, 16, v6
	v_and_b32_e32 v9, 0xffff0000, v6
	v_pk_mul_f32 v[4:5], v[4:5], v[8:9]
	v_lshlrev_b32_e32 v8, 16, v11
	v_cvt_pk_bf16_f32 v2, v4, v5
	v_lshlrev_b32_e32 v4, 16, v3
	v_and_b32_e32 v5, 0xffff0000, v3
	v_and_b32_e32 v9, 0xffff0000, v11
	v_pk_mul_f32 v[4:5], v[4:5], v[8:9]
	v_lshlrev_b32_e32 v6, 16, v7
	v_and_b32_e32 v7, 0xffff0000, v7
	v_pk_mul_f32 v[4:5], v[4:5], v[6:7]
	ds_read_b128 v[8:11], v75 offset:18944
	v_cvt_pk_bf16_f32 v3, v4, v5
	v_lshl_add_u64 v[4:5], s[36:37], 0, v[12:13]
	v_lshlrev_b64 v[12:13], 1, v[132:133]
	global_store_dwordx4 v[4:5], v[0:3], off
	v_mov_b32_e32 v4, v100
	v_mov_b32_e32 v5, v101
	v_mov_b32_e32 v6, v102
	v_mov_b32_e32 v7, v103
	v_mov_b32_e32 v0, v96
	v_mov_b32_e32 v1, v97
	v_mov_b32_e32 v2, v98
	v_mov_b32_e32 v3, v99
	s_waitcnt lgkmcnt(0)
; #define LAS __attribute__((address_space(3)))
; __device__ __forceinline__ unsigned pk2(float lo, float hi) { f32x2 v = {lo, hi}; bf16x2_t b = __builtin_convertvector(v, bf16x2_t); return __builtin_bit_cast(unsigned, b); }
; __device__ __forceinline__ float bflo(unsigned u) { return __uint_as_float(u << 16); }
; __device__ __forceinline__ float bfhi(unsigned u) { return __uint_as_float(u & 0xffff0000u); }
; template <int tbA, int tbB> ...
;     ...
; #pragma unroll
;         for (int which = 0; which < 2; ++which) {
;             const int tb = which ? tbB : tbA;
; #pragma unroll
;             for (int i = 0; i < 2; ++i) {
;                 const int t = (lane >> 2) + 16 * i, ck = lane & 3;
;                 const size_t a = (size_t)(tok0 + tb * 32 + t) * DH + g * 128 + cb * 32 + ck * 8;
;                 const u32x4 uu = *(const u32x4*)(U + a), gc = *(const u32x4*)(GC + a);
;                 const u32x4 mv = *(const LAS u32x4*)(stg + which * 2560 + t * 80 + ck * 16);
;                 u32x4 o; o.x = pk2(bflo(uu.x) * bflo(mv.x) * bflo(gc.x), bfhi(uu.x) * bfhi(mv.x) * bfhi(gc.x)); o.y = pk2(bflo(uu.y) * bflo(mv.y) * bflo(gc.y), bfhi(uu.y) * bfhi(mv.y) * bfhi(gc.y));
;                 o.z = pk2(bflo(uu.z) * bflo(mv.z) * bflo(gc.z), bfhi(uu.z) * bfhi(mv.z) * bfhi(gc.z)); o.w = pk2(bflo(uu.w) * bflo(mv.w) * bflo(gc.w), bfhi(uu.w) * bfhi(mv.w) * bfhi(gc.w));
;                 *(u32x4*)(OC + a) = o;
;             }
	v_lshlrev_b32_e32 v16, 16, v8
	v_and_b32_e32 v17, 0xffff0000, v8
	v_lshlrev_b32_e32 v8, 16, v9
	v_and_b32_e32 v9, 0xffff0000, v9
	v_add_u32_e32 v132, 0xfa01c000, v18
	v_lshlrev_b32_e32 v14, 16, v0
	v_and_b32_e32 v15, 0xffff0000, v0
	v_pk_mul_f32 v[14:15], v[14:15], v[16:17]
	v_lshlrev_b32_e32 v16, 16, v4
	v_and_b32_e32 v17, 0xffff0000, v4
	v_pk_mul_f32 v[14:15], v[14:15], v[16:17]
	v_lshlrev_b32_e32 v4, 16, v5
	v_cvt_pk_bf16_f32 v0, v14, v15
	v_lshlrev_b32_e32 v14, 16, v1
	v_and_b32_e32 v15, 0xffff0000, v1
	v_pk_mul_f32 v[8:9], v[14:15], v[8:9]
	v_and_b32_e32 v5, 0xffff0000, v5
	v_pk_mul_f32 v[4:5], v[8:9], v[4:5]
	v_lshlrev_b32_e32 v8, 16, v10
	v_cvt_pk_bf16_f32 v1, v4, v5
	v_lshlrev_b32_e32 v4, 16, v2
	v_and_b32_e32 v5, 0xffff0000, v2
	v_and_b32_e32 v9, 0xffff0000, v10
	v_pk_mul_f32 v[4:5], v[4:5], v[8:9]
	v_lshlrev_b32_e32 v8, 16, v6
	v_and_b32_e32 v9, 0xffff0000, v6
	v_pk_mul_f32 v[4:5], v[4:5], v[8:9]
	v_lshlrev_b32_e32 v8, 16, v11
	v_cvt_pk_bf16_f32 v2, v4, v5
	v_lshlrev_b32_e32 v4, 16, v3
	v_and_b32_e32 v5, 0xffff0000, v3
	v_and_b32_e32 v9, 0xffff0000, v11
	v_pk_mul_f32 v[4:5], v[4:5], v[8:9]
	v_lshlrev_b32_e32 v6, 16, v7
	v_and_b32_e32 v7, 0xffff0000, v7
	v_pk_mul_f32 v[4:5], v[4:5], v[6:7]
	ds_read_b128 v[8:11], v75 offset:20224
	v_cvt_pk_bf16_f32 v3, v4, v5
	v_lshl_add_u64 v[4:5], s[36:37], 0, v[12:13]
	v_lshlrev_b64 v[12:13], 1, v[132:133]
	global_store_dwordx4 v[4:5], v[0:3], off
	v_mov_b32_e32 v4, v116
	v_mov_b32_e32 v5, v117
	v_mov_b32_e32 v6, v118
	v_mov_b32_e32 v7, v119
	v_mov_b32_e32 v0, v104
	v_mov_b32_e32 v1, v105
	v_mov_b32_e32 v2, v106
	v_mov_b32_e32 v3, v107
	s_waitcnt lgkmcnt(0)
	v_lshlrev_b32_e32 v16, 16, v8
	v_and_b32_e32 v17, 0xffff0000, v8
	v_lshlrev_b32_e32 v8, 16, v9
	v_and_b32_e32 v9, 0xffff0000, v9
	v_lshlrev_b32_e32 v14, 16, v0
	v_and_b32_e32 v15, 0xffff0000, v0
	v_pk_mul_f32 v[14:15], v[14:15], v[16:17]
	v_lshlrev_b32_e32 v16, 16, v4
	v_and_b32_e32 v17, 0xffff0000, v4
	v_pk_mul_f32 v[14:15], v[14:15], v[16:17]
	v_lshlrev_b32_e32 v4, 16, v5
	v_cvt_pk_bf16_f32 v0, v14, v15
	v_lshlrev_b32_e32 v14, 16, v1
	v_and_b32_e32 v15, 0xffff0000, v1
	v_pk_mul_f32 v[8:9], v[14:15], v[8:9]
	v_and_b32_e32 v5, 0xffff0000, v5
	v_pk_mul_f32 v[4:5], v[8:9], v[4:5]
	v_lshlrev_b32_e32 v8, 16, v10
	v_cvt_pk_bf16_f32 v1, v4, v5
	v_lshlrev_b32_e32 v4, 16, v2
	v_and_b32_e32 v5, 0xffff0000, v2
	v_and_b32_e32 v9, 0xffff0000, v10
	v_pk_mul_f32 v[4:5], v[4:5], v[8:9]
	v_lshlrev_b32_e32 v8, 16, v6
	v_and_b32_e32 v9, 0xffff0000, v6
	v_pk_mul_f32 v[4:5], v[4:5], v[8:9]
	v_lshlrev_b32_e32 v8, 16, v11
	v_cvt_pk_bf16_f32 v2, v4, v5
	v_lshlrev_b32_e32 v4, 16, v3
	v_and_b32_e32 v5, 0xffff0000, v3
	v_and_b32_e32 v9, 0xffff0000, v11
	v_pk_mul_f32 v[4:5], v[4:5], v[8:9]
	v_lshlrev_b32_e32 v6, 16, v7
	v_and_b32_e32 v7, 0xffff0000, v7
	v_pk_mul_f32 v[4:5], v[4:5], v[6:7]
	s_nop 0
	v_cvt_pk_bf16_f32 v3, v4, v5
	v_lshl_add_u64 v[4:5], s[36:37], 0, v[12:13]
	global_store_dwordx4 v[4:5], v[0:3], off
	s_cbranch_scc0 .LBB0_657
